# static s_setprio 1 for waves 4-7 also in the phase 9a, 9b and 11 MFMA loops; the two end-of-iteration waits of the DMA K-loops merged into one s_waitcnt
# speedup vs baseline: 1.0031x; 1.0031x over previous
.Lg2_p2_loop:
	ds_read_b128 v[208:211], v172 offset:8192
	ds_read_b128 v[212:215], v172 offset:10240
	ds_read_b128 v[218:221], v172 offset:12288
	ds_read_b128 v[224:227], v172 offset:14336
	s_waitcnt lgkmcnt(4)
	s_nop 0
	v_mfma_f32_16x16x32_bf16 v[126:129], v[228:231], v[192:195], v[126:129]
	v_mfma_f32_16x16x32_bf16 v[122:125], v[232:235], v[192:195], v[122:125]
	v_mfma_f32_16x16x32_bf16 v[118:121], v[236:239], v[192:195], v[118:121]
	v_mfma_f32_16x16x32_bf16 v[114:117], v[240:243], v[192:195], v[114:117]
	v_mfma_f32_16x16x32_bf16 v[110:113], v[228:231], v[196:199], v[110:113]
	v_mfma_f32_16x16x32_bf16 v[106:109], v[232:235], v[196:199], v[106:109]
	v_mfma_f32_16x16x32_bf16 v[102:105], v[236:239], v[196:199], v[102:105]
	v_mfma_f32_16x16x32_bf16 v[98:101], v[240:243], v[196:199], v[98:101]
	v_mfma_f32_16x16x32_bf16 v[94:97], v[228:231], v[200:203], v[94:97]
	v_mfma_f32_16x16x32_bf16 v[90:93], v[232:235], v[200:203], v[90:93]
	v_mfma_f32_16x16x32_bf16 v[86:89], v[236:239], v[200:203], v[86:89]
	v_mfma_f32_16x16x32_bf16 v[82:85], v[240:243], v[200:203], v[82:85]
	v_mfma_f32_16x16x32_bf16 v[78:81], v[228:231], v[204:207], v[78:81]
	v_mfma_f32_16x16x32_bf16 v[74:77], v[232:235], v[204:207], v[74:77]
	v_mfma_f32_16x16x32_bf16 v[70:73], v[236:239], v[204:207], v[70:73]
	v_mfma_f32_16x16x32_bf16 v[66:69], v[240:243], v[204:207], v[66:69]
	ds_read_b128 v[192:195], v216
	ds_read_b128 v[196:199], v216 offset:2048
	ds_read_b128 v[200:203], v216 offset:4096
	ds_read_b128 v[204:207], v216 offset:6144
	ds_read_b128 v[244:247], v217
	ds_read_b128 v[248:251], v217 offset:2048
	ds_read_b128 v[252:255], v217 offset:4096
	ds_read_b128 v[152:155], v217 offset:6144
	s_waitcnt lgkmcnt(8)
	s_nop 0
	v_mfma_f32_16x16x32_bf16 v[62:65], v[228:231], v[208:211], v[62:65]
	v_mfma_f32_16x16x32_bf16 v[58:61], v[232:235], v[208:211], v[58:61]
	v_mfma_f32_16x16x32_bf16 v[54:57], v[236:239], v[208:211], v[54:57]
	v_mfma_f32_16x16x32_bf16 v[50:53], v[240:243], v[208:211], v[50:53]
	v_mfma_f32_16x16x32_bf16 v[46:49], v[228:231], v[212:215], v[46:49]
	v_mfma_f32_16x16x32_bf16 v[42:45], v[232:235], v[212:215], v[42:45]
	v_mfma_f32_16x16x32_bf16 v[38:41], v[236:239], v[212:215], v[38:41]
	v_mfma_f32_16x16x32_bf16 v[34:37], v[240:243], v[212:215], v[34:37]
	v_mfma_f32_16x16x32_bf16 v[30:33], v[228:231], v[218:221], v[30:33]
	v_mfma_f32_16x16x32_bf16 v[26:29], v[232:235], v[218:221], v[26:29]
	v_mfma_f32_16x16x32_bf16 v[22:25], v[236:239], v[218:221], v[22:25]
	v_mfma_f32_16x16x32_bf16 v[18:21], v[240:243], v[218:221], v[18:21]
	v_mfma_f32_16x16x32_bf16 v[14:17], v[228:231], v[224:227], v[14:17]
	v_mfma_f32_16x16x32_bf16 v[10:13], v[232:235], v[224:227], v[10:13]
	v_mfma_f32_16x16x32_bf16 v[6:9], v[236:239], v[224:227], v[6:9]
	v_mfma_f32_16x16x32_bf16 v[2:5], v[240:243], v[224:227], v[2:5]
	ds_read_b128 v[208:211], v216 offset:8192
	ds_read_b128 v[212:215], v216 offset:10240
	ds_read_b128 v[218:221], v216 offset:12288
	ds_read_b128 v[224:227], v216 offset:14336
	s_waitcnt lgkmcnt(4)
	s_nop 0
	v_mfma_f32_16x16x32_bf16 v[126:129], v[244:247], v[192:195], v[126:129]
	v_mfma_f32_16x16x32_bf16 v[122:125], v[248:251], v[192:195], v[122:125]
	v_mfma_f32_16x16x32_bf16 v[118:121], v[252:255], v[192:195], v[118:121]
	v_mfma_f32_16x16x32_bf16 v[114:117], v[152:155], v[192:195], v[114:117]
	v_mfma_f32_16x16x32_bf16 v[110:113], v[244:247], v[196:199], v[110:113]
	v_mfma_f32_16x16x32_bf16 v[106:109], v[248:251], v[196:199], v[106:109]
	v_mfma_f32_16x16x32_bf16 v[102:105], v[252:255], v[196:199], v[102:105]
	v_mfma_f32_16x16x32_bf16 v[98:101], v[152:155], v[196:199], v[98:101]
	v_mfma_f32_16x16x32_bf16 v[94:97], v[244:247], v[200:203], v[94:97]
	v_mfma_f32_16x16x32_bf16 v[90:93], v[248:251], v[200:203], v[90:93]
	v_mfma_f32_16x16x32_bf16 v[86:89], v[252:255], v[200:203], v[86:89]
	v_mfma_f32_16x16x32_bf16 v[82:85], v[152:155], v[200:203], v[82:85]
	v_mfma_f32_16x16x32_bf16 v[78:81], v[244:247], v[204:207], v[78:81]
	v_mfma_f32_16x16x32_bf16 v[74:77], v[248:251], v[204:207], v[74:77]
	v_mfma_f32_16x16x32_bf16 v[70:73], v[252:255], v[204:207], v[70:73]
	v_mfma_f32_16x16x32_bf16 v[66:69], v[152:155], v[204:207], v[66:69]
	s_waitcnt vmcnt(0) lgkmcnt(0)
	s_nop 0
	s_barrier
	s_add_u32 s0, s0, 0x80
	s_addc_u32 s1, s1, 0
	s_add_u32 s98, s98, 0x80
	s_addc_u32 s99, s99, 0
	s_add_u32 s100, s100, 0x80
	s_addc_u32 s101, s101, 0
	s_cmpk_eq_i32 s0, 0x780
	s_cbranch_scc1 .Lg2_p2_tail
	ds_read_b128 v[192:195], v172 offset:32768
	ds_read_b128 v[196:199], v172 offset:34816
	ds_read_b128 v[200:203], v172 offset:36864
	ds_read_b128 v[204:207], v172 offset:38912
	ds_read_b128 v[228:231], v173 offset:32768
	ds_read_b128 v[232:235], v173 offset:34816
	ds_read_b128 v[236:239], v173 offset:36864
	ds_read_b128 v[240:243], v173 offset:38912
	v_mfma_f32_16x16x32_bf16 v[62:65], v[244:247], v[208:211], v[62:65]
	s_mov_b32 m0, s96
	s_nop 0
	v_mfma_f32_16x16x32_bf16 v[58:61], v[248:251], v[208:211], v[58:61]
	global_load_lds_dwordx4 v160, s[98:99]
	v_mfma_f32_16x16x32_bf16 v[54:57], v[252:255], v[208:211], v[54:57]
	s_add_u32 m0, m0, 0x2000
	v_mfma_f32_16x16x32_bf16 v[50:53], v[152:155], v[208:211], v[50:53]
	global_load_lds_dwordx4 v161, s[98:99]
	v_mfma_f32_16x16x32_bf16 v[46:49], v[244:247], v[212:215], v[46:49]
	s_add_u32 m0, m0, 0x2000
	v_mfma_f32_16x16x32_bf16 v[42:45], v[248:251], v[212:215], v[42:45]
	global_load_lds_dwordx4 v162, s[98:99]
	v_mfma_f32_16x16x32_bf16 v[38:41], v[252:255], v[212:215], v[38:41]
	s_add_u32 m0, m0, 0x2000
	v_mfma_f32_16x16x32_bf16 v[34:37], v[152:155], v[212:215], v[34:37]
	global_load_lds_dwordx4 v163, s[98:99]
	v_mfma_f32_16x16x32_bf16 v[30:33], v[244:247], v[218:221], v[30:33]
	s_add_u32 m0, m0, 0xa000
	v_mfma_f32_16x16x32_bf16 v[26:29], v[248:251], v[218:221], v[26:29]
	global_load_lds_dwordx4 v164, s[100:101]
	v_mfma_f32_16x16x32_bf16 v[22:25], v[252:255], v[218:221], v[22:25]
	s_add_u32 m0, m0, 0x2000
	v_mfma_f32_16x16x32_bf16 v[18:21], v[152:155], v[218:221], v[18:21]
	global_load_lds_dwordx4 v165, s[100:101]
	v_mfma_f32_16x16x32_bf16 v[14:17], v[244:247], v[224:227], v[14:17]
	s_add_u32 m0, m0, 0x2000
	v_mfma_f32_16x16x32_bf16 v[10:13], v[248:251], v[224:227], v[10:13]
	global_load_lds_dwordx4 v166, s[100:101]
	v_mfma_f32_16x16x32_bf16 v[6:9], v[252:255], v[224:227], v[6:9]
	s_add_u32 m0, m0, 0x2000
	v_mfma_f32_16x16x32_bf16 v[2:5], v[152:155], v[224:227], v[2:5]
	global_load_lds_dwordx4 v167, s[100:101]
	ds_read_b128 v[208:211], v172 offset:40960
	ds_read_b128 v[212:215], v172 offset:43008
	ds_read_b128 v[218:221], v172 offset:45056
	ds_read_b128 v[224:227], v172 offset:47104
	s_waitcnt lgkmcnt(4)
	s_nop 0
	v_mfma_f32_16x16x32_bf16 v[126:129], v[228:231], v[192:195], v[126:129]
	v_mfma_f32_16x16x32_bf16 v[122:125], v[232:235], v[192:195], v[122:125]
	v_mfma_f32_16x16x32_bf16 v[118:121], v[236:239], v[192:195], v[118:121]
	v_mfma_f32_16x16x32_bf16 v[114:117], v[240:243], v[192:195], v[114:117]
	v_mfma_f32_16x16x32_bf16 v[110:113], v[228:231], v[196:199], v[110:113]
	v_mfma_f32_16x16x32_bf16 v[106:109], v[232:235], v[196:199], v[106:109]
	v_mfma_f32_16x16x32_bf16 v[102:105], v[236:239], v[196:199], v[102:105]
	v_mfma_f32_16x16x32_bf16 v[98:101], v[240:243], v[196:199], v[98:101]
	v_mfma_f32_16x16x32_bf16 v[94:97], v[228:231], v[200:203], v[94:97]
	v_mfma_f32_16x16x32_bf16 v[90:93], v[232:235], v[200:203], v[90:93]
	v_mfma_f32_16x16x32_bf16 v[86:89], v[236:239], v[200:203], v[86:89]
	v_mfma_f32_16x16x32_bf16 v[82:85], v[240:243], v[200:203], v[82:85]
	v_mfma_f32_16x16x32_bf16 v[78:81], v[228:231], v[204:207], v[78:81]
	v_mfma_f32_16x16x32_bf16 v[74:77], v[232:235], v[204:207], v[74:77]
	v_mfma_f32_16x16x32_bf16 v[70:73], v[236:239], v[204:207], v[70:73]
	v_mfma_f32_16x16x32_bf16 v[66:69], v[240:243], v[204:207], v[66:69]
	ds_read_b128 v[192:195], v216 offset:32768
	ds_read_b128 v[196:199], v216 offset:34816
	ds_read_b128 v[200:203], v216 offset:36864
	ds_read_b128 v[204:207], v216 offset:38912
	ds_read_b128 v[244:247], v217 offset:32768
	ds_read_b128 v[248:251], v217 offset:34816
	ds_read_b128 v[252:255], v217 offset:36864
	ds_read_b128 v[152:155], v217 offset:38912
	s_waitcnt lgkmcnt(8)
	s_nop 0
	v_mfma_f32_16x16x32_bf16 v[62:65], v[228:231], v[208:211], v[62:65]
	v_mfma_f32_16x16x32_bf16 v[58:61], v[232:235], v[208:211], v[58:61]
	v_mfma_f32_16x16x32_bf16 v[54:57], v[236:239], v[208:211], v[54:57]
	v_mfma_f32_16x16x32_bf16 v[50:53], v[240:243], v[208:211], v[50:53]
	v_mfma_f32_16x16x32_bf16 v[46:49], v[228:231], v[212:215], v[46:49]
	v_mfma_f32_16x16x32_bf16 v[42:45], v[232:235], v[212:215], v[42:45]
	v_mfma_f32_16x16x32_bf16 v[38:41], v[236:239], v[212:215], v[38:41]
	v_mfma_f32_16x16x32_bf16 v[34:37], v[240:243], v[212:215], v[34:37]
	v_mfma_f32_16x16x32_bf16 v[30:33], v[228:231], v[218:221], v[30:33]
	v_mfma_f32_16x16x32_bf16 v[26:29], v[232:235], v[218:221], v[26:29]
	v_mfma_f32_16x16x32_bf16 v[22:25], v[236:239], v[218:221], v[22:25]
	v_mfma_f32_16x16x32_bf16 v[18:21], v[240:243], v[218:221], v[18:21]
	v_mfma_f32_16x16x32_bf16 v[14:17], v[228:231], v[224:227], v[14:17]
	v_mfma_f32_16x16x32_bf16 v[10:13], v[232:235], v[224:227], v[10:13]
	v_mfma_f32_16x16x32_bf16 v[6:9], v[236:239], v[224:227], v[6:9]
	v_mfma_f32_16x16x32_bf16 v[2:5], v[240:243], v[224:227], v[2:5]
	ds_read_b128 v[208:211], v216 offset:40960
	ds_read_b128 v[212:215], v216 offset:43008
	ds_read_b128 v[218:221], v216 offset:45056
	ds_read_b128 v[224:227], v216 offset:47104
	s_waitcnt lgkmcnt(4)
	s_nop 0
	v_mfma_f32_16x16x32_bf16 v[126:129], v[244:247], v[192:195], v[126:129]
	v_mfma_f32_16x16x32_bf16 v[122:125], v[248:251], v[192:195], v[122:125]
	v_mfma_f32_16x16x32_bf16 v[118:121], v[252:255], v[192:195], v[118:121]
	v_mfma_f32_16x16x32_bf16 v[114:117], v[152:155], v[192:195], v[114:117]
	v_mfma_f32_16x16x32_bf16 v[110:113], v[244:247], v[196:199], v[110:113]
	v_mfma_f32_16x16x32_bf16 v[106:109], v[248:251], v[196:199], v[106:109]
	v_mfma_f32_16x16x32_bf16 v[102:105], v[252:255], v[196:199], v[102:105]
	v_mfma_f32_16x16x32_bf16 v[98:101], v[152:155], v[196:199], v[98:101]
	v_mfma_f32_16x16x32_bf16 v[94:97], v[244:247], v[200:203], v[94:97]
	v_mfma_f32_16x16x32_bf16 v[90:93], v[248:251], v[200:203], v[90:93]
	v_mfma_f32_16x16x32_bf16 v[86:89], v[252:255], v[200:203], v[86:89]
	v_mfma_f32_16x16x32_bf16 v[82:85], v[152:155], v[200:203], v[82:85]
	v_mfma_f32_16x16x32_bf16 v[78:81], v[244:247], v[204:207], v[78:81]
	v_mfma_f32_16x16x32_bf16 v[74:77], v[248:251], v[204:207], v[74:77]
	v_mfma_f32_16x16x32_bf16 v[70:73], v[252:255], v[204:207], v[70:73]
	v_mfma_f32_16x16x32_bf16 v[66:69], v[152:155], v[204:207], v[66:69]
	s_waitcnt vmcnt(0) lgkmcnt(0)
	s_nop 0
	s_barrier
	s_add_u32 s0, s0, 0x80
	s_addc_u32 s1, s1, 0
	s_add_u32 s98, s98, 0x80
	s_addc_u32 s99, s99, 0
	s_add_u32 s100, s100, 0x80
	s_addc_u32 s101, s101, 0
	s_cmpk_eq_i32 s0, 0x780
	s_cbranch_scc1 .Lg2_p2_tail
	ds_read_b128 v[192:195], v172
	ds_read_b128 v[196:199], v172 offset:2048
	ds_read_b128 v[200:203], v172 offset:4096
	ds_read_b128 v[204:207], v172 offset:6144
	ds_read_b128 v[228:231], v173
	ds_read_b128 v[232:235], v173 offset:2048
	ds_read_b128 v[236:239], v173 offset:4096
	ds_read_b128 v[240:243], v173 offset:6144
	v_mfma_f32_16x16x32_bf16 v[62:65], v[244:247], v[208:211], v[62:65]
	s_add_u32 m0, s96, 0x8000
	v_mfma_f32_16x16x32_bf16 v[58:61], v[248:251], v[208:211], v[58:61]
	global_load_lds_dwordx4 v160, s[98:99]
	v_mfma_f32_16x16x32_bf16 v[54:57], v[252:255], v[208:211], v[54:57]
	s_add_u32 m0, m0, 0x2000
	v_mfma_f32_16x16x32_bf16 v[50:53], v[152:155], v[208:211], v[50:53]
	global_load_lds_dwordx4 v161, s[98:99]
	v_mfma_f32_16x16x32_bf16 v[46:49], v[244:247], v[212:215], v[46:49]
	s_add_u32 m0, m0, 0x2000
	v_mfma_f32_16x16x32_bf16 v[42:45], v[248:251], v[212:215], v[42:45]
	global_load_lds_dwordx4 v162, s[98:99]
	v_mfma_f32_16x16x32_bf16 v[38:41], v[252:255], v[212:215], v[38:41]
	s_add_u32 m0, m0, 0x2000
	v_mfma_f32_16x16x32_bf16 v[34:37], v[152:155], v[212:215], v[34:37]
	global_load_lds_dwordx4 v163, s[98:99]
	v_mfma_f32_16x16x32_bf16 v[30:33], v[244:247], v[218:221], v[30:33]
	s_add_u32 m0, m0, 0xa000
	v_mfma_f32_16x16x32_bf16 v[26:29], v[248:251], v[218:221], v[26:29]
	global_load_lds_dwordx4 v164, s[100:101]
	v_mfma_f32_16x16x32_bf16 v[22:25], v[252:255], v[218:221], v[22:25]
	s_add_u32 m0, m0, 0x2000
	v_mfma_f32_16x16x32_bf16 v[18:21], v[152:155], v[218:221], v[18:21]
	global_load_lds_dwordx4 v165, s[100:101]
	v_mfma_f32_16x16x32_bf16 v[14:17], v[244:247], v[224:227], v[14:17]
	s_add_u32 m0, m0, 0x2000
	v_mfma_f32_16x16x32_bf16 v[10:13], v[248:251], v[224:227], v[10:13]
	global_load_lds_dwordx4 v166, s[100:101]
	v_mfma_f32_16x16x32_bf16 v[6:9], v[252:255], v[224:227], v[6:9]
	s_add_u32 m0, m0, 0x2000
	v_mfma_f32_16x16x32_bf16 v[2:5], v[152:155], v[224:227], v[2:5]
	global_load_lds_dwordx4 v167, s[100:101]
	s_branch .Lg2_p2_loop

.Lg2_p4_loop:
	s_nop 0
	ds_read_b128 v[196:199], v148 offset:8192
	ds_read_b128 v[200:203], v148 offset:10240
	ds_read_b128 v[204:207], v148 offset:12288
	ds_read_b128 v[208:211], v148 offset:14336
	s_waitcnt lgkmcnt(4)
	s_nop 0
	v_mfma_f32_16x16x32_bf16 v[126:129], v[212:215], v[180:183], v[126:129]
	v_mfma_f32_16x16x32_bf16 v[122:125], v[218:221], v[180:183], v[122:125]
	v_mfma_f32_16x16x32_bf16 v[118:121], v[224:227], v[180:183], v[118:121]
	v_mfma_f32_16x16x32_bf16 v[114:117], v[228:231], v[180:183], v[114:117]
	v_mfma_f32_16x16x32_bf16 v[110:113], v[212:215], v[184:187], v[110:113]
	v_mfma_f32_16x16x32_bf16 v[106:109], v[218:221], v[184:187], v[106:109]
	v_mfma_f32_16x16x32_bf16 v[102:105], v[224:227], v[184:187], v[102:105]
	v_mfma_f32_16x16x32_bf16 v[98:101], v[228:231], v[184:187], v[98:101]
	v_mfma_f32_16x16x32_bf16 v[94:97], v[212:215], v[188:191], v[94:97]
	v_mfma_f32_16x16x32_bf16 v[90:93], v[218:221], v[188:191], v[90:93]
	v_mfma_f32_16x16x32_bf16 v[86:89], v[224:227], v[188:191], v[86:89]
	v_mfma_f32_16x16x32_bf16 v[82:85], v[228:231], v[188:191], v[82:85]
	v_mfma_f32_16x16x32_bf16 v[78:81], v[212:215], v[192:195], v[78:81]
	v_mfma_f32_16x16x32_bf16 v[74:77], v[218:221], v[192:195], v[74:77]
	v_mfma_f32_16x16x32_bf16 v[70:73], v[224:227], v[192:195], v[70:73]
	v_mfma_f32_16x16x32_bf16 v[66:69], v[228:231], v[192:195], v[66:69]
	ds_read_b128 v[180:183], v216
	ds_read_b128 v[184:187], v216 offset:2048
	ds_read_b128 v[188:191], v216 offset:4096
	ds_read_b128 v[192:195], v216 offset:6144
	ds_read_b128 v[232:235], v217
	ds_read_b128 v[236:239], v217 offset:2048
	ds_read_b128 v[240:243], v217 offset:4096
	ds_read_b128 v[244:247], v217 offset:6144
	s_waitcnt lgkmcnt(8)
	s_nop 0
	v_mfma_f32_16x16x32_bf16 v[62:65], v[212:215], v[196:199], v[62:65]
	v_mfma_f32_16x16x32_bf16 v[58:61], v[218:221], v[196:199], v[58:61]
	v_mfma_f32_16x16x32_bf16 v[54:57], v[224:227], v[196:199], v[54:57]
	v_mfma_f32_16x16x32_bf16 v[50:53], v[228:231], v[196:199], v[50:53]
	v_mfma_f32_16x16x32_bf16 v[46:49], v[212:215], v[200:203], v[46:49]
	v_mfma_f32_16x16x32_bf16 v[42:45], v[218:221], v[200:203], v[42:45]
	v_mfma_f32_16x16x32_bf16 v[38:41], v[224:227], v[200:203], v[38:41]
	v_mfma_f32_16x16x32_bf16 v[34:37], v[228:231], v[200:203], v[34:37]
	v_mfma_f32_16x16x32_bf16 v[30:33], v[212:215], v[204:207], v[30:33]
	v_mfma_f32_16x16x32_bf16 v[26:29], v[218:221], v[204:207], v[26:29]
	v_mfma_f32_16x16x32_bf16 v[22:25], v[224:227], v[204:207], v[22:25]
	v_mfma_f32_16x16x32_bf16 v[18:21], v[228:231], v[204:207], v[18:21]
	v_mfma_f32_16x16x32_bf16 v[14:17], v[212:215], v[208:211], v[14:17]
	v_mfma_f32_16x16x32_bf16 v[10:13], v[218:221], v[208:211], v[10:13]
	v_mfma_f32_16x16x32_bf16 v[6:9], v[224:227], v[208:211], v[6:9]
	v_mfma_f32_16x16x32_bf16 v[2:5], v[228:231], v[208:211], v[2:5]
	ds_read_b128 v[196:199], v216 offset:8192
	ds_read_b128 v[200:203], v216 offset:10240
	ds_read_b128 v[204:207], v216 offset:12288
	ds_read_b128 v[208:211], v216 offset:14336
	s_waitcnt lgkmcnt(4)
	s_nop 0
	v_mfma_f32_16x16x32_bf16 v[126:129], v[232:235], v[180:183], v[126:129]
	v_mfma_f32_16x16x32_bf16 v[122:125], v[236:239], v[180:183], v[122:125]
	v_mfma_f32_16x16x32_bf16 v[118:121], v[240:243], v[180:183], v[118:121]
	v_mfma_f32_16x16x32_bf16 v[114:117], v[244:247], v[180:183], v[114:117]
	v_mfma_f32_16x16x32_bf16 v[110:113], v[232:235], v[184:187], v[110:113]
	v_mfma_f32_16x16x32_bf16 v[106:109], v[236:239], v[184:187], v[106:109]
	v_mfma_f32_16x16x32_bf16 v[102:105], v[240:243], v[184:187], v[102:105]
	v_mfma_f32_16x16x32_bf16 v[98:101], v[244:247], v[184:187], v[98:101]
	v_mfma_f32_16x16x32_bf16 v[94:97], v[232:235], v[188:191], v[94:97]
	v_mfma_f32_16x16x32_bf16 v[90:93], v[236:239], v[188:191], v[90:93]
	v_mfma_f32_16x16x32_bf16 v[86:89], v[240:243], v[188:191], v[86:89]
	v_mfma_f32_16x16x32_bf16 v[82:85], v[244:247], v[188:191], v[82:85]
	v_mfma_f32_16x16x32_bf16 v[78:81], v[232:235], v[192:195], v[78:81]
	v_mfma_f32_16x16x32_bf16 v[74:77], v[236:239], v[192:195], v[74:77]
	v_mfma_f32_16x16x32_bf16 v[70:73], v[240:243], v[192:195], v[70:73]
	v_mfma_f32_16x16x32_bf16 v[66:69], v[244:247], v[192:195], v[66:69]
	s_waitcnt vmcnt(0) lgkmcnt(0)
	s_nop 0
	s_barrier
	s_add_u32 s8, s8, 0x80
	s_addc_u32 s9, s9, 0
	s_add_u32 s98, s98, 0x80
	s_addc_u32 s99, s99, 0
	s_add_u32 s100, s100, 0x80
	s_addc_u32 s101, s101, 0
	s_cmpk_eq_i32 s8, 0x780
	s_cbranch_scc1 .Lg2_p4_tail
	ds_read_b128 v[180:183], v148 offset:32768
	ds_read_b128 v[184:187], v148 offset:34816
	ds_read_b128 v[188:191], v148 offset:36864
	ds_read_b128 v[192:195], v148 offset:38912
	ds_read_b128 v[212:215], v149 offset:32768
	ds_read_b128 v[218:221], v149 offset:34816
	ds_read_b128 v[224:227], v149 offset:36864
	ds_read_b128 v[228:231], v149 offset:38912
	v_mfma_f32_16x16x32_bf16 v[62:65], v[232:235], v[196:199], v[62:65]
	s_mov_b32 m0, s96
	s_nop 0
	v_mfma_f32_16x16x32_bf16 v[58:61], v[236:239], v[196:199], v[58:61]
	global_load_lds_dwordx4 v140, s[98:99]
	v_mfma_f32_16x16x32_bf16 v[54:57], v[240:243], v[196:199], v[54:57]
	s_add_u32 m0, m0, 0x2000
	v_mfma_f32_16x16x32_bf16 v[50:53], v[244:247], v[196:199], v[50:53]
	global_load_lds_dwordx4 v152, s[98:99]
	v_mfma_f32_16x16x32_bf16 v[46:49], v[232:235], v[200:203], v[46:49]
	s_add_u32 m0, m0, 0x2000
	v_mfma_f32_16x16x32_bf16 v[42:45], v[236:239], v[200:203], v[42:45]
	global_load_lds_dwordx4 v156, s[98:99]
	v_mfma_f32_16x16x32_bf16 v[38:41], v[240:243], v[200:203], v[38:41]
	s_add_u32 m0, m0, 0x2000
	v_mfma_f32_16x16x32_bf16 v[34:37], v[244:247], v[200:203], v[34:37]
	global_load_lds_dwordx4 v160, s[98:99]
	v_mfma_f32_16x16x32_bf16 v[30:33], v[232:235], v[204:207], v[30:33]
	s_add_u32 m0, m0, 0xa000
	v_mfma_f32_16x16x32_bf16 v[26:29], v[236:239], v[204:207], v[26:29]
	global_load_lds_dwordx4 v164, s[100:101]
	v_mfma_f32_16x16x32_bf16 v[22:25], v[240:243], v[204:207], v[22:25]
	s_add_u32 m0, m0, 0x2000
	v_mfma_f32_16x16x32_bf16 v[18:21], v[244:247], v[204:207], v[18:21]
	global_load_lds_dwordx4 v168, s[100:101]
	v_mfma_f32_16x16x32_bf16 v[14:17], v[232:235], v[208:211], v[14:17]
	s_add_u32 m0, m0, 0x2000
	v_mfma_f32_16x16x32_bf16 v[10:13], v[236:239], v[208:211], v[10:13]
	global_load_lds_dwordx4 v172, s[100:101]
	v_mfma_f32_16x16x32_bf16 v[6:9], v[240:243], v[208:211], v[6:9]
	s_add_u32 m0, m0, 0x2000
	v_mfma_f32_16x16x32_bf16 v[2:5], v[244:247], v[208:211], v[2:5]
	global_load_lds_dwordx4 v176, s[100:101]
	ds_read_b128 v[196:199], v148 offset:40960
	ds_read_b128 v[200:203], v148 offset:43008
	ds_read_b128 v[204:207], v148 offset:45056
	ds_read_b128 v[208:211], v148 offset:47104
	s_waitcnt lgkmcnt(4)
	s_nop 0
	v_mfma_f32_16x16x32_bf16 v[126:129], v[212:215], v[180:183], v[126:129]
	v_mfma_f32_16x16x32_bf16 v[122:125], v[218:221], v[180:183], v[122:125]
	v_mfma_f32_16x16x32_bf16 v[118:121], v[224:227], v[180:183], v[118:121]
	v_mfma_f32_16x16x32_bf16 v[114:117], v[228:231], v[180:183], v[114:117]
	v_mfma_f32_16x16x32_bf16 v[110:113], v[212:215], v[184:187], v[110:113]
	v_mfma_f32_16x16x32_bf16 v[106:109], v[218:221], v[184:187], v[106:109]
	v_mfma_f32_16x16x32_bf16 v[102:105], v[224:227], v[184:187], v[102:105]
	v_mfma_f32_16x16x32_bf16 v[98:101], v[228:231], v[184:187], v[98:101]
	v_mfma_f32_16x16x32_bf16 v[94:97], v[212:215], v[188:191], v[94:97]
	v_mfma_f32_16x16x32_bf16 v[90:93], v[218:221], v[188:191], v[90:93]
	v_mfma_f32_16x16x32_bf16 v[86:89], v[224:227], v[188:191], v[86:89]
	v_mfma_f32_16x16x32_bf16 v[82:85], v[228:231], v[188:191], v[82:85]
	v_mfma_f32_16x16x32_bf16 v[78:81], v[212:215], v[192:195], v[78:81]
	v_mfma_f32_16x16x32_bf16 v[74:77], v[218:221], v[192:195], v[74:77]
	v_mfma_f32_16x16x32_bf16 v[70:73], v[224:227], v[192:195], v[70:73]
	v_mfma_f32_16x16x32_bf16 v[66:69], v[228:231], v[192:195], v[66:69]
	ds_read_b128 v[180:183], v216 offset:32768
	ds_read_b128 v[184:187], v216 offset:34816
	ds_read_b128 v[188:191], v216 offset:36864
	ds_read_b128 v[192:195], v216 offset:38912
	ds_read_b128 v[232:235], v217 offset:32768
	ds_read_b128 v[236:239], v217 offset:34816
	ds_read_b128 v[240:243], v217 offset:36864
	ds_read_b128 v[244:247], v217 offset:38912
	s_waitcnt lgkmcnt(8)
	s_nop 0
	v_mfma_f32_16x16x32_bf16 v[62:65], v[212:215], v[196:199], v[62:65]
	v_mfma_f32_16x16x32_bf16 v[58:61], v[218:221], v[196:199], v[58:61]
	v_mfma_f32_16x16x32_bf16 v[54:57], v[224:227], v[196:199], v[54:57]
	v_mfma_f32_16x16x32_bf16 v[50:53], v[228:231], v[196:199], v[50:53]
	v_mfma_f32_16x16x32_bf16 v[46:49], v[212:215], v[200:203], v[46:49]
	v_mfma_f32_16x16x32_bf16 v[42:45], v[218:221], v[200:203], v[42:45]
	v_mfma_f32_16x16x32_bf16 v[38:41], v[224:227], v[200:203], v[38:41]
	v_mfma_f32_16x16x32_bf16 v[34:37], v[228:231], v[200:203], v[34:37]
	v_mfma_f32_16x16x32_bf16 v[30:33], v[212:215], v[204:207], v[30:33]
	v_mfma_f32_16x16x32_bf16 v[26:29], v[218:221], v[204:207], v[26:29]
	v_mfma_f32_16x16x32_bf16 v[22:25], v[224:227], v[204:207], v[22:25]
	v_mfma_f32_16x16x32_bf16 v[18:21], v[228:231], v[204:207], v[18:21]
	v_mfma_f32_16x16x32_bf16 v[14:17], v[212:215], v[208:211], v[14:17]
	v_mfma_f32_16x16x32_bf16 v[10:13], v[218:221], v[208:211], v[10:13]
	v_mfma_f32_16x16x32_bf16 v[6:9], v[224:227], v[208:211], v[6:9]
	v_mfma_f32_16x16x32_bf16 v[2:5], v[228:231], v[208:211], v[2:5]
	ds_read_b128 v[196:199], v216 offset:40960
	ds_read_b128 v[200:203], v216 offset:43008
	ds_read_b128 v[204:207], v216 offset:45056
	ds_read_b128 v[208:211], v216 offset:47104
	s_waitcnt lgkmcnt(4)
	s_nop 0
	v_mfma_f32_16x16x32_bf16 v[126:129], v[232:235], v[180:183], v[126:129]
	v_mfma_f32_16x16x32_bf16 v[122:125], v[236:239], v[180:183], v[122:125]
	v_mfma_f32_16x16x32_bf16 v[118:121], v[240:243], v[180:183], v[118:121]
	v_mfma_f32_16x16x32_bf16 v[114:117], v[244:247], v[180:183], v[114:117]
	v_mfma_f32_16x16x32_bf16 v[110:113], v[232:235], v[184:187], v[110:113]
	v_mfma_f32_16x16x32_bf16 v[106:109], v[236:239], v[184:187], v[106:109]
	v_mfma_f32_16x16x32_bf16 v[102:105], v[240:243], v[184:187], v[102:105]
	v_mfma_f32_16x16x32_bf16 v[98:101], v[244:247], v[184:187], v[98:101]
	v_mfma_f32_16x16x32_bf16 v[94:97], v[232:235], v[188:191], v[94:97]
	v_mfma_f32_16x16x32_bf16 v[90:93], v[236:239], v[188:191], v[90:93]
	v_mfma_f32_16x16x32_bf16 v[86:89], v[240:243], v[188:191], v[86:89]
	v_mfma_f32_16x16x32_bf16 v[82:85], v[244:247], v[188:191], v[82:85]
	v_mfma_f32_16x16x32_bf16 v[78:81], v[232:235], v[192:195], v[78:81]
	v_mfma_f32_16x16x32_bf16 v[74:77], v[236:239], v[192:195], v[74:77]
	v_mfma_f32_16x16x32_bf16 v[70:73], v[240:243], v[192:195], v[70:73]
	v_mfma_f32_16x16x32_bf16 v[66:69], v[244:247], v[192:195], v[66:69]
	s_waitcnt vmcnt(0) lgkmcnt(0)
	s_nop 0
	s_barrier
	s_add_u32 s8, s8, 0x80
	s_addc_u32 s9, s9, 0
	s_add_u32 s98, s98, 0x80
	s_addc_u32 s99, s99, 0
	s_add_u32 s100, s100, 0x80
	s_addc_u32 s101, s101, 0
	s_cmpk_eq_i32 s8, 0x780
	s_cbranch_scc1 .Lg2_p4_tail
	ds_read_b128 v[180:183], v148
	ds_read_b128 v[184:187], v148 offset:2048
	ds_read_b128 v[188:191], v148 offset:4096
	ds_read_b128 v[192:195], v148 offset:6144
	ds_read_b128 v[212:215], v149
	ds_read_b128 v[218:221], v149 offset:2048
	ds_read_b128 v[224:227], v149 offset:4096
	ds_read_b128 v[228:231], v149 offset:6144
	v_mfma_f32_16x16x32_bf16 v[62:65], v[232:235], v[196:199], v[62:65]
	s_add_u32 m0, s96, 0x8000
	v_mfma_f32_16x16x32_bf16 v[58:61], v[236:239], v[196:199], v[58:61]
	global_load_lds_dwordx4 v140, s[98:99]
	v_mfma_f32_16x16x32_bf16 v[54:57], v[240:243], v[196:199], v[54:57]
	s_add_u32 m0, m0, 0x2000
	v_mfma_f32_16x16x32_bf16 v[50:53], v[244:247], v[196:199], v[50:53]
	global_load_lds_dwordx4 v152, s[98:99]
	v_mfma_f32_16x16x32_bf16 v[46:49], v[232:235], v[200:203], v[46:49]
	s_add_u32 m0, m0, 0x2000
	v_mfma_f32_16x16x32_bf16 v[42:45], v[236:239], v[200:203], v[42:45]
	global_load_lds_dwordx4 v156, s[98:99]
	v_mfma_f32_16x16x32_bf16 v[38:41], v[240:243], v[200:203], v[38:41]
	s_add_u32 m0, m0, 0x2000
	v_mfma_f32_16x16x32_bf16 v[34:37], v[244:247], v[200:203], v[34:37]
	global_load_lds_dwordx4 v160, s[98:99]
	v_mfma_f32_16x16x32_bf16 v[30:33], v[232:235], v[204:207], v[30:33]
	s_add_u32 m0, m0, 0xa000
	v_mfma_f32_16x16x32_bf16 v[26:29], v[236:239], v[204:207], v[26:29]
	global_load_lds_dwordx4 v164, s[100:101]
	v_mfma_f32_16x16x32_bf16 v[22:25], v[240:243], v[204:207], v[22:25]
	s_add_u32 m0, m0, 0x2000
	v_mfma_f32_16x16x32_bf16 v[18:21], v[244:247], v[204:207], v[18:21]
	global_load_lds_dwordx4 v168, s[100:101]
	v_mfma_f32_16x16x32_bf16 v[14:17], v[232:235], v[208:211], v[14:17]
	s_add_u32 m0, m0, 0x2000
	v_mfma_f32_16x16x32_bf16 v[10:13], v[236:239], v[208:211], v[10:13]
	global_load_lds_dwordx4 v172, s[100:101]
	v_mfma_f32_16x16x32_bf16 v[6:9], v[240:243], v[208:211], v[6:9]
	s_add_u32 m0, m0, 0x2000
	v_mfma_f32_16x16x32_bf16 v[2:5], v[244:247], v[208:211], v[2:5]
	global_load_lds_dwordx4 v176, s[100:101]
	s_branch .Lg2_p4_loop

.Lg2_p6_loop:
	ds_read_b128 v[198:201], v146 offset:8192
	ds_read_b128 v[202:205], v146 offset:10240
	ds_read_b128 v[206:209], v146 offset:12288
	ds_read_b128 v[210:213], v146 offset:14336
	s_waitcnt lgkmcnt(4)
	s_nop 0
	v_mfma_f32_16x16x32_bf16 v[126:129], v[218:221], v[182:185], v[126:129]
	v_mfma_f32_16x16x32_bf16 v[122:125], v[224:227], v[182:185], v[122:125]
	v_mfma_f32_16x16x32_bf16 v[118:121], v[228:231], v[182:185], v[118:121]
	v_mfma_f32_16x16x32_bf16 v[114:117], v[232:235], v[182:185], v[114:117]
	v_mfma_f32_16x16x32_bf16 v[110:113], v[218:221], v[186:189], v[110:113]
	v_mfma_f32_16x16x32_bf16 v[106:109], v[224:227], v[186:189], v[106:109]
	v_mfma_f32_16x16x32_bf16 v[102:105], v[228:231], v[186:189], v[102:105]
	v_mfma_f32_16x16x32_bf16 v[98:101], v[232:235], v[186:189], v[98:101]
	v_mfma_f32_16x16x32_bf16 v[94:97], v[218:221], v[190:193], v[94:97]
	v_mfma_f32_16x16x32_bf16 v[90:93], v[224:227], v[190:193], v[90:93]
	v_mfma_f32_16x16x32_bf16 v[86:89], v[228:231], v[190:193], v[86:89]
	v_mfma_f32_16x16x32_bf16 v[82:85], v[232:235], v[190:193], v[82:85]
	v_mfma_f32_16x16x32_bf16 v[78:81], v[218:221], v[194:197], v[78:81]
	v_mfma_f32_16x16x32_bf16 v[74:77], v[224:227], v[194:197], v[74:77]
	v_mfma_f32_16x16x32_bf16 v[70:73], v[228:231], v[194:197], v[70:73]
	v_mfma_f32_16x16x32_bf16 v[66:69], v[232:235], v[194:197], v[66:69]
	ds_read_b128 v[182:185], v216
	ds_read_b128 v[186:189], v216 offset:2048
	ds_read_b128 v[190:193], v216 offset:4096
	ds_read_b128 v[194:197], v216 offset:6144
	ds_read_b128 v[236:239], v217
	ds_read_b128 v[240:243], v217 offset:2048
	ds_read_b128 v[244:247], v217 offset:4096
	ds_read_b128 v[248:251], v217 offset:6144
	s_waitcnt lgkmcnt(8)
	s_nop 0
	v_mfma_f32_16x16x32_bf16 v[62:65], v[218:221], v[198:201], v[62:65]
	v_mfma_f32_16x16x32_bf16 v[58:61], v[224:227], v[198:201], v[58:61]
	v_mfma_f32_16x16x32_bf16 v[54:57], v[228:231], v[198:201], v[54:57]
	v_mfma_f32_16x16x32_bf16 v[50:53], v[232:235], v[198:201], v[50:53]
	v_mfma_f32_16x16x32_bf16 v[46:49], v[218:221], v[202:205], v[46:49]
	v_mfma_f32_16x16x32_bf16 v[42:45], v[224:227], v[202:205], v[42:45]
	v_mfma_f32_16x16x32_bf16 v[38:41], v[228:231], v[202:205], v[38:41]
	v_mfma_f32_16x16x32_bf16 v[34:37], v[232:235], v[202:205], v[34:37]
	v_mfma_f32_16x16x32_bf16 v[30:33], v[218:221], v[206:209], v[30:33]
	v_mfma_f32_16x16x32_bf16 v[26:29], v[224:227], v[206:209], v[26:29]
	v_mfma_f32_16x16x32_bf16 v[22:25], v[228:231], v[206:209], v[22:25]
	v_mfma_f32_16x16x32_bf16 v[18:21], v[232:235], v[206:209], v[18:21]
	v_mfma_f32_16x16x32_bf16 v[14:17], v[218:221], v[210:213], v[14:17]
	v_mfma_f32_16x16x32_bf16 v[10:13], v[224:227], v[210:213], v[10:13]
	v_mfma_f32_16x16x32_bf16 v[6:9], v[228:231], v[210:213], v[6:9]
	v_mfma_f32_16x16x32_bf16 v[2:5], v[232:235], v[210:213], v[2:5]
	ds_read_b128 v[198:201], v216 offset:8192
	ds_read_b128 v[202:205], v216 offset:10240
	ds_read_b128 v[206:209], v216 offset:12288
	ds_read_b128 v[210:213], v216 offset:14336
	s_waitcnt lgkmcnt(4)
	s_nop 0
	v_mfma_f32_16x16x32_bf16 v[126:129], v[236:239], v[182:185], v[126:129]
	v_mfma_f32_16x16x32_bf16 v[122:125], v[240:243], v[182:185], v[122:125]
	v_mfma_f32_16x16x32_bf16 v[118:121], v[244:247], v[182:185], v[118:121]
	v_mfma_f32_16x16x32_bf16 v[114:117], v[248:251], v[182:185], v[114:117]
	v_mfma_f32_16x16x32_bf16 v[110:113], v[236:239], v[186:189], v[110:113]
	v_mfma_f32_16x16x32_bf16 v[106:109], v[240:243], v[186:189], v[106:109]
	v_mfma_f32_16x16x32_bf16 v[102:105], v[244:247], v[186:189], v[102:105]
	v_mfma_f32_16x16x32_bf16 v[98:101], v[248:251], v[186:189], v[98:101]
	v_mfma_f32_16x16x32_bf16 v[94:97], v[236:239], v[190:193], v[94:97]
	v_mfma_f32_16x16x32_bf16 v[90:93], v[240:243], v[190:193], v[90:93]
	v_mfma_f32_16x16x32_bf16 v[86:89], v[244:247], v[190:193], v[86:89]
	v_mfma_f32_16x16x32_bf16 v[82:85], v[248:251], v[190:193], v[82:85]
	v_mfma_f32_16x16x32_bf16 v[78:81], v[236:239], v[194:197], v[78:81]
	v_mfma_f32_16x16x32_bf16 v[74:77], v[240:243], v[194:197], v[74:77]
	v_mfma_f32_16x16x32_bf16 v[70:73], v[244:247], v[194:197], v[70:73]
	v_mfma_f32_16x16x32_bf16 v[66:69], v[248:251], v[194:197], v[66:69]
	s_waitcnt vmcnt(0) lgkmcnt(0)
	s_nop 0
	s_barrier
	s_add_u32 s0, s0, 0x80
	s_addc_u32 s1, s1, 0
	s_add_u32 s98, s98, 0x80
	s_addc_u32 s99, s99, 0
	s_add_u32 s100, s100, 0x80
	s_addc_u32 s101, s101, 0
	s_cmpk_eq_i32 s0, 0x780
	s_cbranch_scc1 .Lg2_p6_tail
	ds_read_b128 v[182:185], v146 offset:32768
	ds_read_b128 v[186:189], v146 offset:34816
	ds_read_b128 v[190:193], v146 offset:36864
	ds_read_b128 v[194:197], v146 offset:38912
	ds_read_b128 v[218:221], v147 offset:32768
	ds_read_b128 v[224:227], v147 offset:34816
	ds_read_b128 v[228:231], v147 offset:36864
	ds_read_b128 v[232:235], v147 offset:38912
	v_mfma_f32_16x16x32_bf16 v[62:65], v[236:239], v[198:201], v[62:65]
	s_mov_b32 m0, s96
	s_nop 0
	v_mfma_f32_16x16x32_bf16 v[58:61], v[240:243], v[198:201], v[58:61]
	global_load_lds_dwordx4 v150, s[98:99]
	v_mfma_f32_16x16x32_bf16 v[54:57], v[244:247], v[198:201], v[54:57]
	s_add_u32 m0, m0, 0x2000
	v_mfma_f32_16x16x32_bf16 v[50:53], v[248:251], v[198:201], v[50:53]
	global_load_lds_dwordx4 v154, s[98:99]
	v_mfma_f32_16x16x32_bf16 v[46:49], v[236:239], v[202:205], v[46:49]
	s_add_u32 m0, m0, 0x2000
	v_mfma_f32_16x16x32_bf16 v[42:45], v[240:243], v[202:205], v[42:45]
	global_load_lds_dwordx4 v158, s[98:99]
	v_mfma_f32_16x16x32_bf16 v[38:41], v[244:247], v[202:205], v[38:41]
	s_add_u32 m0, m0, 0x2000
	v_mfma_f32_16x16x32_bf16 v[34:37], v[248:251], v[202:205], v[34:37]
	global_load_lds_dwordx4 v162, s[98:99]
	v_mfma_f32_16x16x32_bf16 v[30:33], v[236:239], v[206:209], v[30:33]
	s_add_u32 m0, m0, 0xa000
	v_mfma_f32_16x16x32_bf16 v[26:29], v[240:243], v[206:209], v[26:29]
	global_load_lds_dwordx4 v166, s[100:101]
	v_mfma_f32_16x16x32_bf16 v[22:25], v[244:247], v[206:209], v[22:25]
	s_add_u32 m0, m0, 0x2000
	v_mfma_f32_16x16x32_bf16 v[18:21], v[248:251], v[206:209], v[18:21]
	global_load_lds_dwordx4 v170, s[100:101]
	v_mfma_f32_16x16x32_bf16 v[14:17], v[236:239], v[210:213], v[14:17]
	s_add_u32 m0, m0, 0x2000
	v_mfma_f32_16x16x32_bf16 v[10:13], v[240:243], v[210:213], v[10:13]
	global_load_lds_dwordx4 v174, s[100:101]
	v_mfma_f32_16x16x32_bf16 v[6:9], v[244:247], v[210:213], v[6:9]
	s_add_u32 m0, m0, 0x2000
	v_mfma_f32_16x16x32_bf16 v[2:5], v[248:251], v[210:213], v[2:5]
	global_load_lds_dwordx4 v178, s[100:101]
	ds_read_b128 v[198:201], v146 offset:40960
	ds_read_b128 v[202:205], v146 offset:43008
	ds_read_b128 v[206:209], v146 offset:45056
	ds_read_b128 v[210:213], v146 offset:47104
	s_waitcnt lgkmcnt(4)
	s_nop 0
	v_mfma_f32_16x16x32_bf16 v[126:129], v[218:221], v[182:185], v[126:129]
	v_mfma_f32_16x16x32_bf16 v[122:125], v[224:227], v[182:185], v[122:125]
	v_mfma_f32_16x16x32_bf16 v[118:121], v[228:231], v[182:185], v[118:121]
	v_mfma_f32_16x16x32_bf16 v[114:117], v[232:235], v[182:185], v[114:117]
	v_mfma_f32_16x16x32_bf16 v[110:113], v[218:221], v[186:189], v[110:113]
	v_mfma_f32_16x16x32_bf16 v[106:109], v[224:227], v[186:189], v[106:109]
	v_mfma_f32_16x16x32_bf16 v[102:105], v[228:231], v[186:189], v[102:105]
	v_mfma_f32_16x16x32_bf16 v[98:101], v[232:235], v[186:189], v[98:101]
	v_mfma_f32_16x16x32_bf16 v[94:97], v[218:221], v[190:193], v[94:97]
	v_mfma_f32_16x16x32_bf16 v[90:93], v[224:227], v[190:193], v[90:93]
	v_mfma_f32_16x16x32_bf16 v[86:89], v[228:231], v[190:193], v[86:89]
	v_mfma_f32_16x16x32_bf16 v[82:85], v[232:235], v[190:193], v[82:85]
	v_mfma_f32_16x16x32_bf16 v[78:81], v[218:221], v[194:197], v[78:81]
	v_mfma_f32_16x16x32_bf16 v[74:77], v[224:227], v[194:197], v[74:77]
	v_mfma_f32_16x16x32_bf16 v[70:73], v[228:231], v[194:197], v[70:73]
	v_mfma_f32_16x16x32_bf16 v[66:69], v[232:235], v[194:197], v[66:69]
	ds_read_b128 v[182:185], v216 offset:32768
	ds_read_b128 v[186:189], v216 offset:34816
	ds_read_b128 v[190:193], v216 offset:36864
	ds_read_b128 v[194:197], v216 offset:38912
	ds_read_b128 v[236:239], v217 offset:32768
	ds_read_b128 v[240:243], v217 offset:34816
	ds_read_b128 v[244:247], v217 offset:36864
	ds_read_b128 v[248:251], v217 offset:38912
	s_waitcnt lgkmcnt(8)
	s_nop 0
	v_mfma_f32_16x16x32_bf16 v[62:65], v[218:221], v[198:201], v[62:65]
	v_mfma_f32_16x16x32_bf16 v[58:61], v[224:227], v[198:201], v[58:61]
	v_mfma_f32_16x16x32_bf16 v[54:57], v[228:231], v[198:201], v[54:57]
	v_mfma_f32_16x16x32_bf16 v[50:53], v[232:235], v[198:201], v[50:53]
	v_mfma_f32_16x16x32_bf16 v[46:49], v[218:221], v[202:205], v[46:49]
	v_mfma_f32_16x16x32_bf16 v[42:45], v[224:227], v[202:205], v[42:45]
	v_mfma_f32_16x16x32_bf16 v[38:41], v[228:231], v[202:205], v[38:41]
	v_mfma_f32_16x16x32_bf16 v[34:37], v[232:235], v[202:205], v[34:37]
	v_mfma_f32_16x16x32_bf16 v[30:33], v[218:221], v[206:209], v[30:33]
	v_mfma_f32_16x16x32_bf16 v[26:29], v[224:227], v[206:209], v[26:29]
	v_mfma_f32_16x16x32_bf16 v[22:25], v[228:231], v[206:209], v[22:25]
	v_mfma_f32_16x16x32_bf16 v[18:21], v[232:235], v[206:209], v[18:21]
	v_mfma_f32_16x16x32_bf16 v[14:17], v[218:221], v[210:213], v[14:17]
	v_mfma_f32_16x16x32_bf16 v[10:13], v[224:227], v[210:213], v[10:13]
	v_mfma_f32_16x16x32_bf16 v[6:9], v[228:231], v[210:213], v[6:9]
	v_mfma_f32_16x16x32_bf16 v[2:5], v[232:235], v[210:213], v[2:5]
	ds_read_b128 v[198:201], v216 offset:40960
	ds_read_b128 v[202:205], v216 offset:43008
	ds_read_b128 v[206:209], v216 offset:45056
	ds_read_b128 v[210:213], v216 offset:47104
	s_waitcnt lgkmcnt(4)
	s_nop 0
	v_mfma_f32_16x16x32_bf16 v[126:129], v[236:239], v[182:185], v[126:129]
	v_mfma_f32_16x16x32_bf16 v[122:125], v[240:243], v[182:185], v[122:125]
	v_mfma_f32_16x16x32_bf16 v[118:121], v[244:247], v[182:185], v[118:121]
	v_mfma_f32_16x16x32_bf16 v[114:117], v[248:251], v[182:185], v[114:117]
	v_mfma_f32_16x16x32_bf16 v[110:113], v[236:239], v[186:189], v[110:113]
	v_mfma_f32_16x16x32_bf16 v[106:109], v[240:243], v[186:189], v[106:109]
	v_mfma_f32_16x16x32_bf16 v[102:105], v[244:247], v[186:189], v[102:105]
	v_mfma_f32_16x16x32_bf16 v[98:101], v[248:251], v[186:189], v[98:101]
	v_mfma_f32_16x16x32_bf16 v[94:97], v[236:239], v[190:193], v[94:97]
	v_mfma_f32_16x16x32_bf16 v[90:93], v[240:243], v[190:193], v[90:93]
	v_mfma_f32_16x16x32_bf16 v[86:89], v[244:247], v[190:193], v[86:89]
	v_mfma_f32_16x16x32_bf16 v[82:85], v[248:251], v[190:193], v[82:85]
	v_mfma_f32_16x16x32_bf16 v[78:81], v[236:239], v[194:197], v[78:81]
	v_mfma_f32_16x16x32_bf16 v[74:77], v[240:243], v[194:197], v[74:77]
	v_mfma_f32_16x16x32_bf16 v[70:73], v[244:247], v[194:197], v[70:73]
	v_mfma_f32_16x16x32_bf16 v[66:69], v[248:251], v[194:197], v[66:69]
	s_waitcnt vmcnt(0) lgkmcnt(0)
	s_nop 0
	s_barrier
	s_add_u32 s0, s0, 0x80
	s_addc_u32 s1, s1, 0
	s_add_u32 s98, s98, 0x80
	s_addc_u32 s99, s99, 0
	s_add_u32 s100, s100, 0x80
	s_addc_u32 s101, s101, 0
	s_cmpk_eq_i32 s0, 0x780
	s_cbranch_scc1 .Lg2_p6_tail
	ds_read_b128 v[182:185], v146
	ds_read_b128 v[186:189], v146 offset:2048
	ds_read_b128 v[190:193], v146 offset:4096
	ds_read_b128 v[194:197], v146 offset:6144
	ds_read_b128 v[218:221], v147
	ds_read_b128 v[224:227], v147 offset:2048
	ds_read_b128 v[228:231], v147 offset:4096
	ds_read_b128 v[232:235], v147 offset:6144
	v_mfma_f32_16x16x32_bf16 v[62:65], v[236:239], v[198:201], v[62:65]
	s_add_u32 m0, s96, 0x8000
	v_mfma_f32_16x16x32_bf16 v[58:61], v[240:243], v[198:201], v[58:61]
	global_load_lds_dwordx4 v150, s[98:99]
	v_mfma_f32_16x16x32_bf16 v[54:57], v[244:247], v[198:201], v[54:57]
	s_add_u32 m0, m0, 0x2000
	v_mfma_f32_16x16x32_bf16 v[50:53], v[248:251], v[198:201], v[50:53]
	global_load_lds_dwordx4 v154, s[98:99]
	v_mfma_f32_16x16x32_bf16 v[46:49], v[236:239], v[202:205], v[46:49]
	s_add_u32 m0, m0, 0x2000
	v_mfma_f32_16x16x32_bf16 v[42:45], v[240:243], v[202:205], v[42:45]
	global_load_lds_dwordx4 v158, s[98:99]
	v_mfma_f32_16x16x32_bf16 v[38:41], v[244:247], v[202:205], v[38:41]
	s_add_u32 m0, m0, 0x2000
	v_mfma_f32_16x16x32_bf16 v[34:37], v[248:251], v[202:205], v[34:37]
	global_load_lds_dwordx4 v162, s[98:99]
	v_mfma_f32_16x16x32_bf16 v[30:33], v[236:239], v[206:209], v[30:33]
	s_add_u32 m0, m0, 0xa000
	v_mfma_f32_16x16x32_bf16 v[26:29], v[240:243], v[206:209], v[26:29]
	global_load_lds_dwordx4 v166, s[100:101]
	v_mfma_f32_16x16x32_bf16 v[22:25], v[244:247], v[206:209], v[22:25]
	s_add_u32 m0, m0, 0x2000
	v_mfma_f32_16x16x32_bf16 v[18:21], v[248:251], v[206:209], v[18:21]
	global_load_lds_dwordx4 v170, s[100:101]
	v_mfma_f32_16x16x32_bf16 v[14:17], v[236:239], v[210:213], v[14:17]
	s_add_u32 m0, m0, 0x2000
	v_mfma_f32_16x16x32_bf16 v[10:13], v[240:243], v[210:213], v[10:13]
	global_load_lds_dwordx4 v174, s[100:101]
	v_mfma_f32_16x16x32_bf16 v[6:9], v[244:247], v[210:213], v[6:9]
	s_add_u32 m0, m0, 0x2000
	v_mfma_f32_16x16x32_bf16 v[2:5], v[248:251], v[210:213], v[2:5]
	global_load_lds_dwordx4 v178, s[100:101]
	s_branch .Lg2_p6_loop

.Lg2_p7_loop:
	ds_read_b128 v[196:199], v148 offset:8192
	ds_read_b128 v[200:203], v148 offset:10240
	ds_read_b128 v[204:207], v148 offset:12288
	ds_read_b128 v[208:211], v148 offset:14336
	s_waitcnt lgkmcnt(4)
	s_nop 0
	v_mfma_f32_16x16x32_bf16 v[126:129], v[212:215], v[180:183], v[126:129]
	v_mfma_f32_16x16x32_bf16 v[122:125], v[218:221], v[180:183], v[122:125]
	v_mfma_f32_16x16x32_bf16 v[118:121], v[224:227], v[180:183], v[118:121]
	v_mfma_f32_16x16x32_bf16 v[114:117], v[228:231], v[180:183], v[114:117]
	v_mfma_f32_16x16x32_bf16 v[110:113], v[212:215], v[184:187], v[110:113]
	v_mfma_f32_16x16x32_bf16 v[106:109], v[218:221], v[184:187], v[106:109]
	v_mfma_f32_16x16x32_bf16 v[102:105], v[224:227], v[184:187], v[102:105]
	v_mfma_f32_16x16x32_bf16 v[98:101], v[228:231], v[184:187], v[98:101]
	v_mfma_f32_16x16x32_bf16 v[94:97], v[212:215], v[188:191], v[94:97]
	v_mfma_f32_16x16x32_bf16 v[90:93], v[218:221], v[188:191], v[90:93]
	v_mfma_f32_16x16x32_bf16 v[86:89], v[224:227], v[188:191], v[86:89]
	v_mfma_f32_16x16x32_bf16 v[82:85], v[228:231], v[188:191], v[82:85]
	v_mfma_f32_16x16x32_bf16 v[78:81], v[212:215], v[192:195], v[78:81]
	v_mfma_f32_16x16x32_bf16 v[74:77], v[218:221], v[192:195], v[74:77]
	v_mfma_f32_16x16x32_bf16 v[70:73], v[224:227], v[192:195], v[70:73]
	v_mfma_f32_16x16x32_bf16 v[66:69], v[228:231], v[192:195], v[66:69]
	ds_read_b128 v[180:183], v216
	ds_read_b128 v[184:187], v216 offset:2048
	ds_read_b128 v[188:191], v216 offset:4096
	ds_read_b128 v[192:195], v216 offset:6144
	ds_read_b128 v[232:235], v217
	ds_read_b128 v[236:239], v217 offset:2048
	ds_read_b128 v[240:243], v217 offset:4096
	ds_read_b128 v[244:247], v217 offset:6144
	s_waitcnt lgkmcnt(8)
	s_nop 0
	v_mfma_f32_16x16x32_bf16 v[62:65], v[212:215], v[196:199], v[62:65]
	v_mfma_f32_16x16x32_bf16 v[58:61], v[218:221], v[196:199], v[58:61]
	v_mfma_f32_16x16x32_bf16 v[54:57], v[224:227], v[196:199], v[54:57]
	v_mfma_f32_16x16x32_bf16 v[50:53], v[228:231], v[196:199], v[50:53]
	v_mfma_f32_16x16x32_bf16 v[46:49], v[212:215], v[200:203], v[46:49]
	v_mfma_f32_16x16x32_bf16 v[42:45], v[218:221], v[200:203], v[42:45]
	v_mfma_f32_16x16x32_bf16 v[38:41], v[224:227], v[200:203], v[38:41]
	v_mfma_f32_16x16x32_bf16 v[34:37], v[228:231], v[200:203], v[34:37]
	v_mfma_f32_16x16x32_bf16 v[30:33], v[212:215], v[204:207], v[30:33]
	v_mfma_f32_16x16x32_bf16 v[26:29], v[218:221], v[204:207], v[26:29]
	v_mfma_f32_16x16x32_bf16 v[22:25], v[224:227], v[204:207], v[22:25]
	v_mfma_f32_16x16x32_bf16 v[18:21], v[228:231], v[204:207], v[18:21]
	v_mfma_f32_16x16x32_bf16 v[14:17], v[212:215], v[208:211], v[14:17]
	v_mfma_f32_16x16x32_bf16 v[10:13], v[218:221], v[208:211], v[10:13]
	v_mfma_f32_16x16x32_bf16 v[6:9], v[224:227], v[208:211], v[6:9]
	v_mfma_f32_16x16x32_bf16 v[2:5], v[228:231], v[208:211], v[2:5]
	ds_read_b128 v[196:199], v216 offset:8192
	ds_read_b128 v[200:203], v216 offset:10240
	ds_read_b128 v[204:207], v216 offset:12288
	ds_read_b128 v[208:211], v216 offset:14336
	s_waitcnt lgkmcnt(4)
	s_nop 0
	v_mfma_f32_16x16x32_bf16 v[126:129], v[232:235], v[180:183], v[126:129]
	v_mfma_f32_16x16x32_bf16 v[122:125], v[236:239], v[180:183], v[122:125]
	v_mfma_f32_16x16x32_bf16 v[118:121], v[240:243], v[180:183], v[118:121]
	v_mfma_f32_16x16x32_bf16 v[114:117], v[244:247], v[180:183], v[114:117]
	v_mfma_f32_16x16x32_bf16 v[110:113], v[232:235], v[184:187], v[110:113]
	v_mfma_f32_16x16x32_bf16 v[106:109], v[236:239], v[184:187], v[106:109]
	v_mfma_f32_16x16x32_bf16 v[102:105], v[240:243], v[184:187], v[102:105]
	v_mfma_f32_16x16x32_bf16 v[98:101], v[244:247], v[184:187], v[98:101]
	v_mfma_f32_16x16x32_bf16 v[94:97], v[232:235], v[188:191], v[94:97]
	v_mfma_f32_16x16x32_bf16 v[90:93], v[236:239], v[188:191], v[90:93]
	v_mfma_f32_16x16x32_bf16 v[86:89], v[240:243], v[188:191], v[86:89]
	v_mfma_f32_16x16x32_bf16 v[82:85], v[244:247], v[188:191], v[82:85]
	v_mfma_f32_16x16x32_bf16 v[78:81], v[232:235], v[192:195], v[78:81]
	v_mfma_f32_16x16x32_bf16 v[74:77], v[236:239], v[192:195], v[74:77]
	v_mfma_f32_16x16x32_bf16 v[70:73], v[240:243], v[192:195], v[70:73]
	v_mfma_f32_16x16x32_bf16 v[66:69], v[244:247], v[192:195], v[66:69]
	s_waitcnt vmcnt(0) lgkmcnt(0)
	s_nop 0
	s_barrier
	s_add_u32 s8, s8, 0x80
	s_addc_u32 s9, s9, 0
	s_add_u32 s98, s98, 0x80
	s_addc_u32 s99, s99, 0
	s_add_u32 s100, s100, 0x80
	s_addc_u32 s101, s101, 0
	s_cmpk_eq_i32 s8, 0x1580
	s_cbranch_scc1 .Lg2_p7_tail
	ds_read_b128 v[180:183], v148 offset:32768
	ds_read_b128 v[184:187], v148 offset:34816
	ds_read_b128 v[188:191], v148 offset:36864
	ds_read_b128 v[192:195], v148 offset:38912
	ds_read_b128 v[212:215], v149 offset:32768
	ds_read_b128 v[218:221], v149 offset:34816
	ds_read_b128 v[224:227], v149 offset:36864
	ds_read_b128 v[228:231], v149 offset:38912
	v_mfma_f32_16x16x32_bf16 v[62:65], v[232:235], v[196:199], v[62:65]
	s_mov_b32 m0, s96
	s_nop 0
	v_mfma_f32_16x16x32_bf16 v[58:61], v[236:239], v[196:199], v[58:61]
	global_load_lds_dwordx4 v140, s[98:99]
	v_mfma_f32_16x16x32_bf16 v[54:57], v[240:243], v[196:199], v[54:57]
	s_add_u32 m0, m0, 0x2000
	v_mfma_f32_16x16x32_bf16 v[50:53], v[244:247], v[196:199], v[50:53]
	global_load_lds_dwordx4 v152, s[98:99]
	v_mfma_f32_16x16x32_bf16 v[46:49], v[232:235], v[200:203], v[46:49]
	s_add_u32 m0, m0, 0x2000
	v_mfma_f32_16x16x32_bf16 v[42:45], v[236:239], v[200:203], v[42:45]
	global_load_lds_dwordx4 v156, s[98:99]
	v_mfma_f32_16x16x32_bf16 v[38:41], v[240:243], v[200:203], v[38:41]
	s_add_u32 m0, m0, 0x2000
	v_mfma_f32_16x16x32_bf16 v[34:37], v[244:247], v[200:203], v[34:37]
	global_load_lds_dwordx4 v160, s[98:99]
	v_mfma_f32_16x16x32_bf16 v[30:33], v[232:235], v[204:207], v[30:33]
	s_add_u32 m0, m0, 0xa000
	v_mfma_f32_16x16x32_bf16 v[26:29], v[236:239], v[204:207], v[26:29]
	global_load_lds_dwordx4 v164, s[100:101]
	v_mfma_f32_16x16x32_bf16 v[22:25], v[240:243], v[204:207], v[22:25]
	s_add_u32 m0, m0, 0x2000
	v_mfma_f32_16x16x32_bf16 v[18:21], v[244:247], v[204:207], v[18:21]
	global_load_lds_dwordx4 v168, s[100:101]
	v_mfma_f32_16x16x32_bf16 v[14:17], v[232:235], v[208:211], v[14:17]
	s_add_u32 m0, m0, 0x2000
	v_mfma_f32_16x16x32_bf16 v[10:13], v[236:239], v[208:211], v[10:13]
	global_load_lds_dwordx4 v172, s[100:101]
	v_mfma_f32_16x16x32_bf16 v[6:9], v[240:243], v[208:211], v[6:9]
	s_add_u32 m0, m0, 0x2000
	v_mfma_f32_16x16x32_bf16 v[2:5], v[244:247], v[208:211], v[2:5]
	global_load_lds_dwordx4 v176, s[100:101]
	ds_read_b128 v[196:199], v148 offset:40960
	ds_read_b128 v[200:203], v148 offset:43008
	ds_read_b128 v[204:207], v148 offset:45056
	ds_read_b128 v[208:211], v148 offset:47104
	s_waitcnt lgkmcnt(4)
	s_nop 0
	v_mfma_f32_16x16x32_bf16 v[126:129], v[212:215], v[180:183], v[126:129]
	v_mfma_f32_16x16x32_bf16 v[122:125], v[218:221], v[180:183], v[122:125]
	v_mfma_f32_16x16x32_bf16 v[118:121], v[224:227], v[180:183], v[118:121]
	v_mfma_f32_16x16x32_bf16 v[114:117], v[228:231], v[180:183], v[114:117]
	v_mfma_f32_16x16x32_bf16 v[110:113], v[212:215], v[184:187], v[110:113]
	v_mfma_f32_16x16x32_bf16 v[106:109], v[218:221], v[184:187], v[106:109]
	v_mfma_f32_16x16x32_bf16 v[102:105], v[224:227], v[184:187], v[102:105]
	v_mfma_f32_16x16x32_bf16 v[98:101], v[228:231], v[184:187], v[98:101]
	v_mfma_f32_16x16x32_bf16 v[94:97], v[212:215], v[188:191], v[94:97]
	v_mfma_f32_16x16x32_bf16 v[90:93], v[218:221], v[188:191], v[90:93]
	v_mfma_f32_16x16x32_bf16 v[86:89], v[224:227], v[188:191], v[86:89]
	v_mfma_f32_16x16x32_bf16 v[82:85], v[228:231], v[188:191], v[82:85]
	v_mfma_f32_16x16x32_bf16 v[78:81], v[212:215], v[192:195], v[78:81]
	v_mfma_f32_16x16x32_bf16 v[74:77], v[218:221], v[192:195], v[74:77]
	v_mfma_f32_16x16x32_bf16 v[70:73], v[224:227], v[192:195], v[70:73]
	v_mfma_f32_16x16x32_bf16 v[66:69], v[228:231], v[192:195], v[66:69]
	ds_read_b128 v[180:183], v216 offset:32768
	ds_read_b128 v[184:187], v216 offset:34816
	ds_read_b128 v[188:191], v216 offset:36864
	ds_read_b128 v[192:195], v216 offset:38912
	ds_read_b128 v[232:235], v217 offset:32768
	ds_read_b128 v[236:239], v217 offset:34816
	ds_read_b128 v[240:243], v217 offset:36864
	ds_read_b128 v[244:247], v217 offset:38912
	s_waitcnt lgkmcnt(8)
	s_nop 0
	v_mfma_f32_16x16x32_bf16 v[62:65], v[212:215], v[196:199], v[62:65]
	v_mfma_f32_16x16x32_bf16 v[58:61], v[218:221], v[196:199], v[58:61]
	v_mfma_f32_16x16x32_bf16 v[54:57], v[224:227], v[196:199], v[54:57]
	v_mfma_f32_16x16x32_bf16 v[50:53], v[228:231], v[196:199], v[50:53]
	v_mfma_f32_16x16x32_bf16 v[46:49], v[212:215], v[200:203], v[46:49]
	v_mfma_f32_16x16x32_bf16 v[42:45], v[218:221], v[200:203], v[42:45]
	v_mfma_f32_16x16x32_bf16 v[38:41], v[224:227], v[200:203], v[38:41]
	v_mfma_f32_16x16x32_bf16 v[34:37], v[228:231], v[200:203], v[34:37]
	v_mfma_f32_16x16x32_bf16 v[30:33], v[212:215], v[204:207], v[30:33]
	v_mfma_f32_16x16x32_bf16 v[26:29], v[218:221], v[204:207], v[26:29]
	v_mfma_f32_16x16x32_bf16 v[22:25], v[224:227], v[204:207], v[22:25]
	v_mfma_f32_16x16x32_bf16 v[18:21], v[228:231], v[204:207], v[18:21]
	v_mfma_f32_16x16x32_bf16 v[14:17], v[212:215], v[208:211], v[14:17]
	v_mfma_f32_16x16x32_bf16 v[10:13], v[218:221], v[208:211], v[10:13]
	v_mfma_f32_16x16x32_bf16 v[6:9], v[224:227], v[208:211], v[6:9]
	v_mfma_f32_16x16x32_bf16 v[2:5], v[228:231], v[208:211], v[2:5]
	ds_read_b128 v[196:199], v216 offset:40960
	ds_read_b128 v[200:203], v216 offset:43008
	ds_read_b128 v[204:207], v216 offset:45056
	ds_read_b128 v[208:211], v216 offset:47104
	s_waitcnt lgkmcnt(4)
	s_nop 0
	v_mfma_f32_16x16x32_bf16 v[126:129], v[232:235], v[180:183], v[126:129]
	v_mfma_f32_16x16x32_bf16 v[122:125], v[236:239], v[180:183], v[122:125]
	v_mfma_f32_16x16x32_bf16 v[118:121], v[240:243], v[180:183], v[118:121]
	v_mfma_f32_16x16x32_bf16 v[114:117], v[244:247], v[180:183], v[114:117]
	v_mfma_f32_16x16x32_bf16 v[110:113], v[232:235], v[184:187], v[110:113]
	v_mfma_f32_16x16x32_bf16 v[106:109], v[236:239], v[184:187], v[106:109]
	v_mfma_f32_16x16x32_bf16 v[102:105], v[240:243], v[184:187], v[102:105]
	v_mfma_f32_16x16x32_bf16 v[98:101], v[244:247], v[184:187], v[98:101]
	v_mfma_f32_16x16x32_bf16 v[94:97], v[232:235], v[188:191], v[94:97]
	v_mfma_f32_16x16x32_bf16 v[90:93], v[236:239], v[188:191], v[90:93]
	v_mfma_f32_16x16x32_bf16 v[86:89], v[240:243], v[188:191], v[86:89]
	v_mfma_f32_16x16x32_bf16 v[82:85], v[244:247], v[188:191], v[82:85]
	v_mfma_f32_16x16x32_bf16 v[78:81], v[232:235], v[192:195], v[78:81]
	v_mfma_f32_16x16x32_bf16 v[74:77], v[236:239], v[192:195], v[74:77]
	v_mfma_f32_16x16x32_bf16 v[70:73], v[240:243], v[192:195], v[70:73]
	v_mfma_f32_16x16x32_bf16 v[66:69], v[244:247], v[192:195], v[66:69]
	s_waitcnt vmcnt(0) lgkmcnt(0)
	s_nop 0
	s_barrier
	s_add_u32 s8, s8, 0x80
	s_addc_u32 s9, s9, 0
	s_add_u32 s98, s98, 0x80
	s_addc_u32 s99, s99, 0
	s_add_u32 s100, s100, 0x80
	s_addc_u32 s101, s101, 0
	s_cmpk_eq_i32 s8, 0x1580
	s_cbranch_scc1 .Lg2_p7_tail
	ds_read_b128 v[180:183], v148
	ds_read_b128 v[184:187], v148 offset:2048
	ds_read_b128 v[188:191], v148 offset:4096
	ds_read_b128 v[192:195], v148 offset:6144
	ds_read_b128 v[212:215], v149
	ds_read_b128 v[218:221], v149 offset:2048
	ds_read_b128 v[224:227], v149 offset:4096
	ds_read_b128 v[228:231], v149 offset:6144
	v_mfma_f32_16x16x32_bf16 v[62:65], v[232:235], v[196:199], v[62:65]
	s_add_u32 m0, s96, 0x8000
	v_mfma_f32_16x16x32_bf16 v[58:61], v[236:239], v[196:199], v[58:61]
	global_load_lds_dwordx4 v140, s[98:99]
	v_mfma_f32_16x16x32_bf16 v[54:57], v[240:243], v[196:199], v[54:57]
	s_add_u32 m0, m0, 0x2000
	v_mfma_f32_16x16x32_bf16 v[50:53], v[244:247], v[196:199], v[50:53]
	global_load_lds_dwordx4 v152, s[98:99]
	v_mfma_f32_16x16x32_bf16 v[46:49], v[232:235], v[200:203], v[46:49]
	s_add_u32 m0, m0, 0x2000
	v_mfma_f32_16x16x32_bf16 v[42:45], v[236:239], v[200:203], v[42:45]
	global_load_lds_dwordx4 v156, s[98:99]
	v_mfma_f32_16x16x32_bf16 v[38:41], v[240:243], v[200:203], v[38:41]
	s_add_u32 m0, m0, 0x2000
	v_mfma_f32_16x16x32_bf16 v[34:37], v[244:247], v[200:203], v[34:37]
	global_load_lds_dwordx4 v160, s[98:99]
	v_mfma_f32_16x16x32_bf16 v[30:33], v[232:235], v[204:207], v[30:33]
	s_add_u32 m0, m0, 0xa000
	v_mfma_f32_16x16x32_bf16 v[26:29], v[236:239], v[204:207], v[26:29]
	global_load_lds_dwordx4 v164, s[100:101]
	v_mfma_f32_16x16x32_bf16 v[22:25], v[240:243], v[204:207], v[22:25]
	s_add_u32 m0, m0, 0x2000
	v_mfma_f32_16x16x32_bf16 v[18:21], v[244:247], v[204:207], v[18:21]
	global_load_lds_dwordx4 v168, s[100:101]
	v_mfma_f32_16x16x32_bf16 v[14:17], v[232:235], v[208:211], v[14:17]
	s_add_u32 m0, m0, 0x2000
	v_mfma_f32_16x16x32_bf16 v[10:13], v[236:239], v[208:211], v[10:13]
	global_load_lds_dwordx4 v172, s[100:101]
	v_mfma_f32_16x16x32_bf16 v[6:9], v[240:243], v[208:211], v[6:9]
	s_add_u32 m0, m0, 0x2000
	v_mfma_f32_16x16x32_bf16 v[2:5], v[244:247], v[208:211], v[2:5]
	global_load_lds_dwordx4 v176, s[100:101]
	s_branch .Lg2_p7_loop

.LBB0_512:
	s_ashr_i32 s14, s59, 2
	s_and_b32 s63, s59, 3
	s_cmp_lg_u32 s14, 1
	s_cselect_b64 s[12:13], -1, 0
	s_cmp_eq_u32 s14, 1
	s_cselect_b32 s6, s39, 0xc00
	s_ashr_i32 s15, s14, 31
	s_lshl_b64 s[16:17], s[14:15], 21
	s_add_u32 s68, s36, s16
	s_addc_u32 s69, s37, s17
	s_lshl_b32 s64, s62, 8
	s_lshl_b32 s66, s63, 18
	v_or_b32_e32 v2, s64, v1
	s_cmp_gt_u32 s59, 3
	v_ashrrev_i32_e32 v3, 31, v2
	s_cselect_b64 s[14:15], -1, 0
	v_lshlrev_b64 v[18:19], 11, v[2:3]
	s_and_b64 s[70:71], s[14:15], exec
	v_lshl_add_u64 v[36:37], v[178:179], 0, v[18:19]
	s_cselect_b32 s6, s6, 0
	v_lshl_add_u64 v[38:39], v[180:181], 0, v[18:19]
	global_load_dwordx4 v[10:13], v[36:37], off
	global_load_dwordx4 v[14:17], v[38:39], off
	s_lshl_b32 s6, s6, 2
	v_lshl_add_u64 v[2:3], v[182:183], 0, s[6:7]
	global_load_dwordx4 v[6:9], v[2:3], off
	s_nop 0
	global_load_dwordx4 v[2:5], v[2:3], off offset:16
	v_add_co_u32_e32 v20, vcc, s40, v36
	v_or_b32_e32 v190, s66, v188
	s_nop 0
	v_addc_co_u32_e32 v21, vcc, 0, v37, vcc
	v_add_co_u32_e32 v24, vcc, s40, v38
	v_mov_b32_e32 v203, v191
	s_nop 0
	v_addc_co_u32_e32 v25, vcc, 0, v39, vcc
	global_load_dwordx4 v[20:23], v[20:21], off
	s_nop 0
	global_load_dwordx4 v[24:27], v[24:25], off
	v_add_co_u32_e32 v28, vcc, s41, v36
	v_lshl_add_u64 v[40:41], v[190:191], 1, s[68:69]
	s_nop 0
	v_addc_co_u32_e32 v29, vcc, 0, v37, vcc
	v_add_co_u32_e32 v32, vcc, s41, v38
	v_lshl_add_u64 v[52:53], v[40:41], 0, v[202:203]
	s_nop 0
	v_addc_co_u32_e32 v33, vcc, 0, v39, vcc
	global_load_dwordx4 v[28:31], v[28:29], off
	s_nop 0
	global_load_dwordx4 v[32:35], v[32:33], off
	v_add_co_u32_e32 v48, vcc, s40, v52
	v_add_u32_e32 v190, s66, v188
	s_nop 0
	v_addc_co_u32_e32 v49, vcc, 0, v53, vcc
	v_add_co_u32_e32 v36, vcc, s42, v36
	s_mov_b32 s65, 0
	s_nop 0
	v_addc_co_u32_e32 v37, vcc, 0, v37, vcc
	v_add_co_u32_e32 v40, vcc, s42, v38
	v_lshl_add_u64 v[204:205], v[184:185], 0, v[18:19]
	s_nop 0
	v_addc_co_u32_e32 v41, vcc, 0, v39, vcc
	global_load_dwordx4 v[36:39], v[36:37], off
	s_nop 0
	global_load_dwordx4 v[40:43], v[40:41], off
	s_waitcnt vmcnt(63) expcnt(7) lgkmcnt(15)
	s_barrier
	global_load_dwordx4 v[44:47], v[52:53], off
	s_nop 0
	global_load_dwordx4 v[48:51], v[48:49], off
	v_lshl_add_u64 v[206:207], v[186:187], 0, s[6:7]
	s_waitcnt vmcnt(11)
	v_lshlrev_b32_e32 v54, 16, v10
	s_waitcnt vmcnt(10)
	v_lshlrev_b32_e32 v56, 16, v14
	v_and_b32_e32 v55, 0xffff0000, v10
	v_and_b32_e32 v57, 0xffff0000, v14
	v_lshlrev_b32_e32 v10, 16, v11
	v_lshlrev_b32_e32 v14, 16, v15
	v_and_b32_e32 v11, 0xffff0000, v11
	v_and_b32_e32 v15, 0xffff0000, v15
	s_waitcnt vmcnt(9)
	v_pk_fma_f32 v[14:15], v[8:9], v[14:15], v[10:11]
	v_lshlrev_b32_e32 v58, 16, v12
	v_cvt_pk_bf16_f32 v11, v14, v15
	v_add_co_u32_e32 v14, vcc, s41, v52
	v_lshlrev_b32_e32 v60, 16, v16
	s_nop 0
	v_addc_co_u32_e32 v15, vcc, 0, v53, vcc
	v_and_b32_e32 v59, 0xffff0000, v12
	v_and_b32_e32 v61, 0xffff0000, v16
	v_lshlrev_b32_e32 v12, 16, v13
	v_lshlrev_b32_e32 v16, 16, v17
	v_and_b32_e32 v13, 0xffff0000, v13
	v_and_b32_e32 v17, 0xffff0000, v17
	v_add_co_u32_e32 v52, vcc, s42, v52
	v_pk_fma_f32 v[54:55], v[6:7], v[56:57], v[54:55]
	s_waitcnt vmcnt(8)
	v_pk_fma_f32 v[16:17], v[4:5], v[16:17], v[12:13]
	v_addc_co_u32_e32 v53, vcc, 0, v53, vcc
	v_cvt_pk_bf16_f32 v10, v54, v55
	v_cvt_pk_bf16_f32 v13, v16, v17
	global_load_dwordx4 v[14:17], v[14:15], off
	s_nop 0
	global_load_dwordx4 v[52:55], v[52:53], off
	v_pk_fma_f32 v[56:57], v[2:3], v[60:61], v[58:59]
	s_waitcnt vmcnt(8)
	v_lshlrev_b32_e32 v58, 16, v24
	v_cvt_pk_bf16_f32 v12, v56, v57
	v_lshlrev_b32_e32 v56, 16, v20
	v_and_b32_e32 v57, 0xffff0000, v20
	v_and_b32_e32 v59, 0xffff0000, v24
	v_pk_fma_f32 v[56:57], v[6:7], v[58:59], v[56:57]
	v_lshlrev_b32_e32 v24, 16, v25
	v_cvt_pk_bf16_f32 v20, v56, v57
	v_lshlrev_b32_e32 v56, 16, v21
	v_and_b32_e32 v57, 0xffff0000, v21
	v_and_b32_e32 v25, 0xffff0000, v25
	v_pk_fma_f32 v[24:25], v[8:9], v[24:25], v[56:57]
	v_lshlrev_b32_e32 v56, 16, v26
	v_cvt_pk_bf16_f32 v21, v24, v25
	v_lshlrev_b32_e32 v24, 16, v22
	v_and_b32_e32 v25, 0xffff0000, v22
	v_and_b32_e32 v57, 0xffff0000, v26
	v_pk_fma_f32 v[24:25], v[2:3], v[56:57], v[24:25]
	v_lshlrev_b32_e32 v26, 16, v27
	v_cvt_pk_bf16_f32 v22, v24, v25
	v_lshlrev_b32_e32 v24, 16, v23
	v_and_b32_e32 v25, 0xffff0000, v23
	v_and_b32_e32 v27, 0xffff0000, v27
	v_pk_fma_f32 v[24:25], v[4:5], v[26:27], v[24:25]
	s_waitcnt vmcnt(6)
	v_lshlrev_b32_e32 v26, 16, v32
	v_cvt_pk_bf16_f32 v23, v24, v25
	v_lshlrev_b32_e32 v24, 16, v28
	v_and_b32_e32 v25, 0xffff0000, v28
	v_and_b32_e32 v27, 0xffff0000, v32
	v_pk_fma_f32 v[24:25], v[6:7], v[26:27], v[24:25]
	v_lshlrev_b32_e32 v26, 16, v29
	v_lshlrev_b32_e32 v28, 16, v33
	v_and_b32_e32 v27, 0xffff0000, v29
	v_and_b32_e32 v29, 0xffff0000, v33
	v_pk_fma_f32 v[26:27], v[8:9], v[28:29], v[26:27]
	v_cvt_pk_bf16_f32 v24, v24, v25
	v_cvt_pk_bf16_f32 v25, v26, v27
	v_lshlrev_b32_e32 v26, 16, v30
	v_lshlrev_b32_e32 v28, 16, v34
	v_and_b32_e32 v27, 0xffff0000, v30
	v_and_b32_e32 v29, 0xffff0000, v34
	v_pk_fma_f32 v[26:27], v[2:3], v[28:29], v[26:27]
	v_lshlrev_b32_e32 v28, 16, v31
	v_lshlrev_b32_e32 v30, 16, v35
	v_and_b32_e32 v29, 0xffff0000, v31
	v_and_b32_e32 v31, 0xffff0000, v35
	v_pk_fma_f32 v[28:29], v[4:5], v[30:31], v[28:29]
	v_cvt_pk_bf16_f32 v26, v26, v27
	v_cvt_pk_bf16_f32 v27, v28, v29
	s_waitcnt vmcnt(5)
	v_lshlrev_b32_e32 v28, 16, v36
	s_waitcnt vmcnt(4)
	v_lshlrev_b32_e32 v30, 16, v40
	v_and_b32_e32 v29, 0xffff0000, v36
	v_and_b32_e32 v31, 0xffff0000, v40
	v_pk_fma_f32 v[6:7], v[6:7], v[30:31], v[28:29]
	v_lshlrev_b32_e32 v28, 16, v37
	v_lshlrev_b32_e32 v30, 16, v41
	v_and_b32_e32 v29, 0xffff0000, v37
	v_and_b32_e32 v31, 0xffff0000, v41
	v_pk_fma_f32 v[8:9], v[8:9], v[30:31], v[28:29]
	v_cvt_pk_bf16_f32 v6, v6, v7
	v_cvt_pk_bf16_f32 v7, v8, v9
	v_lshlrev_b32_e32 v8, 16, v38
	v_lshlrev_b32_e32 v28, 16, v42
	v_and_b32_e32 v9, 0xffff0000, v38
	v_and_b32_e32 v29, 0xffff0000, v42
	v_pk_fma_f32 v[2:3], v[2:3], v[28:29], v[8:9]
	v_lshlrev_b32_e32 v28, 16, v43
	v_cvt_pk_bf16_f32 v8, v2, v3
	v_lshlrev_b32_e32 v2, 16, v39
	v_and_b32_e32 v3, 0xffff0000, v39
	v_and_b32_e32 v29, 0xffff0000, v43
	v_pk_fma_f32 v[2:3], v[4:5], v[28:29], v[2:3]
	s_nop 0
	v_cvt_pk_bf16_f32 v9, v2, v3
	v_lshl_add_u64 v[2:3], v[190:191], 1, s[16:17]
	v_lshl_add_u64 v[208:209], v[184:185], 0, v[2:3]
	v_mov_b32_e32 v2, 0
	ds_write_b128 v193, v[10:13]
	ds_write_b128 v193, v[20:23] offset:9216
	ds_write_b128 v193, v[24:27] offset:18432
	ds_write_b128 v193, v[6:9] offset:27648
	s_waitcnt vmcnt(3)
	ds_write_b128 v210, v[44:47]
	s_waitcnt vmcnt(2)
	ds_write_b128 v210, v[48:51] offset:9216
	s_waitcnt vmcnt(1)
	ds_write_b128 v210, v[14:17] offset:18432
	s_waitcnt vmcnt(0)
	ds_write_b128 v210, v[52:55] offset:27648
	s_mov_b64 s[16:17], 0
	v_mov_b32_e32 v3, v2
	v_mov_b32_e32 v4, v2
	v_mov_b32_e32 v5, v2
	v_mov_b32_e32 v6, v2
	v_mov_b32_e32 v7, v2
	v_mov_b32_e32 v8, v2
	v_mov_b32_e32 v9, v2
	v_mov_b32_e32 v10, v2
	v_mov_b32_e32 v11, v2
	v_mov_b32_e32 v12, v2
	v_mov_b32_e32 v13, v2
	v_mov_b32_e32 v14, v2
	v_mov_b32_e32 v15, v2
	v_mov_b32_e32 v16, v2
	v_mov_b32_e32 v17, v2
	v_mov_b32_e32 v18, v2
	v_mov_b32_e32 v19, v2
	v_mov_b32_e32 v20, v2
	v_mov_b32_e32 v21, v2
	v_mov_b32_e32 v22, v2
	v_mov_b32_e32 v23, v2
	v_mov_b32_e32 v24, v2
	v_mov_b32_e32 v25, v2
	v_mov_b32_e32 v26, v2
	v_mov_b32_e32 v27, v2
	v_mov_b32_e32 v28, v2
	v_mov_b32_e32 v29, v2
	v_mov_b32_e32 v30, v2
	v_mov_b32_e32 v31, v2
	v_mov_b32_e32 v32, v2
	v_mov_b32_e32 v33, v2
	v_mov_b32_e32 v34, v2
	v_mov_b32_e32 v35, v2
	v_mov_b32_e32 v36, v2
	v_mov_b32_e32 v37, v2
	v_mov_b32_e32 v38, v2
	v_mov_b32_e32 v39, v2
	v_mov_b32_e32 v40, v2
	v_mov_b32_e32 v41, v2
	v_mov_b32_e32 v42, v2
	v_mov_b32_e32 v43, v2
	v_mov_b32_e32 v44, v2
	v_mov_b32_e32 v45, v2
	v_mov_b32_e32 v46, v2
	v_mov_b32_e32 v47, v2
	v_mov_b32_e32 v48, v2
	v_mov_b32_e32 v49, v2
	v_mov_b32_e32 v50, v2
	v_mov_b32_e32 v51, v2
	v_mov_b32_e32 v52, v2
	v_mov_b32_e32 v53, v2
	v_mov_b32_e32 v54, v2
	v_mov_b32_e32 v55, v2
	v_mov_b32_e32 v56, v2
	v_mov_b32_e32 v57, v2
	v_mov_b32_e32 v58, v2
	v_mov_b32_e32 v59, v2
	v_mov_b32_e32 v60, v2
	v_mov_b32_e32 v61, v2
	v_mov_b32_e32 v62, v2
	v_mov_b32_e32 v63, v2
	v_mov_b32_e32 v64, v2
	v_mov_b32_e32 v65, v2
	v_mov_b32_e32 v86, v2
	v_mov_b32_e32 v87, v2
	v_mov_b32_e32 v88, v2
	v_mov_b32_e32 v89, v2
	v_mov_b32_e32 v74, v2
	v_mov_b32_e32 v75, v2
	v_mov_b32_e32 v76, v2
	v_mov_b32_e32 v77, v2
	v_mov_b32_e32 v82, v2
	v_mov_b32_e32 v83, v2
	v_mov_b32_e32 v84, v2
	v_mov_b32_e32 v85, v2
	v_mov_b32_e32 v70, v2
	v_mov_b32_e32 v71, v2
	v_mov_b32_e32 v72, v2
	v_mov_b32_e32 v73, v2
	v_mov_b32_e32 v66, v2
	s_waitcnt lgkmcnt(8)
	v_mov_b32_e32 v67, v2
	v_mov_b32_e32 v68, v2
	v_mov_b32_e32 v69, v2
	v_mov_b32_e32 v78, v2
	v_mov_b32_e32 v79, v2
	v_mov_b32_e32 v80, v2
	v_mov_b32_e32 v81, v2
	v_mov_b32_e32 v90, v2
	v_mov_b32_e32 v91, v2
	v_mov_b32_e32 v92, v2
	v_mov_b32_e32 v93, v2
	v_mov_b32_e32 v94, v2
	v_mov_b32_e32 v95, v2
	v_mov_b32_e32 v96, v2
	v_mov_b32_e32 v97, v2
	v_mov_b32_e32 v98, v2
	v_mov_b32_e32 v99, v2
	v_mov_b32_e32 v100, v2
	v_mov_b32_e32 v101, v2
	v_mov_b32_e32 v102, v2
	v_mov_b32_e32 v103, v2
	v_mov_b32_e32 v104, v2
	v_mov_b32_e32 v105, v2
	v_mov_b32_e32 v106, v2
	v_mov_b32_e32 v107, v2
	v_mov_b32_e32 v108, v2
	v_mov_b32_e32 v109, v2
	v_mov_b32_e32 v110, v2
	v_mov_b32_e32 v111, v2
	v_mov_b32_e32 v112, v2
	v_mov_b32_e32 v113, v2
	v_mov_b32_e32 v114, v2
	v_mov_b32_e32 v115, v2
	v_mov_b32_e32 v116, v2
	v_mov_b32_e32 v117, v2
	v_mov_b32_e32 v118, v2
	v_mov_b32_e32 v119, v2
	v_mov_b32_e32 v120, v2
	v_mov_b32_e32 v121, v2
	v_mov_b32_e32 v122, v2
	v_mov_b32_e32 v123, v2
	v_mov_b32_e32 v124, v2
	v_mov_b32_e32 v125, v2
	v_mov_b32_e32 v126, v2
	v_mov_b32_e32 v127, v2
	v_mov_b32_e32 v128, v2
	v_mov_b32_e32 v129, v2
	s_waitcnt lgkmcnt(0)
	s_barrier
	v_readfirstlane_b32 s97, v0
	s_bfe_u32 s97, s97, 0x40006
	s_cmp_lt_u32 s97, 4
	s_cbranch_scc1 .Lhp_p9a
	s_setprio 1
.Lhp_p9a:
.LBB0_513:
	v_lshl_add_u64 v[142:143], v[204:205], 0, s[16:17]
	s_and_b32 s6, s65, 1
	v_add_co_u32_e32 v130, vcc, s43, v142
	s_nop 1
	v_addc_co_u32_e32 v131, vcc, 0, v143, vcc
	v_add_co_u32_e32 v224, vcc, s44, v142
	s_nop 1
	v_addc_co_u32_e32 v225, vcc, 0, v143, vcc
	v_add_co_u32_e32 v134, vcc, s45, v142
	s_nop 1
	v_addc_co_u32_e32 v135, vcc, 0, v143, vcc
	v_add_co_u32_e32 v228, vcc, s46, v142
	s_nop 1
	v_addc_co_u32_e32 v229, vcc, 0, v143, vcc
	v_add_co_u32_e32 v138, vcc, s47, v142
	s_nop 1
	v_addc_co_u32_e32 v139, vcc, 0, v143, vcc
	v_add_co_u32_e32 v232, vcc, s48, v142
	s_nop 1
	v_addc_co_u32_e32 v233, vcc, 0, v143, vcc
	v_add_co_u32_e32 v236, vcc, s52, v142
	s_nop 1
	v_addc_co_u32_e32 v237, vcc, 0, v143, vcc
	v_add_co_u32_e32 v142, vcc, s49, v142
	s_nop 1
	v_addc_co_u32_e32 v143, vcc, 0, v143, vcc
	global_load_dwordx4 v[244:247], v[206:207], off offset:16
	global_load_dwordx4 v[240:243], v[206:207], off
	global_load_dwordx4 v[130:133], v[130:131], off offset:128
	global_load_dwordx4 v[224:227], v[224:225], off offset:128
	global_load_dwordx4 v[134:137], v[134:135], off offset:128
	global_load_dwordx4 v[228:231], v[228:229], off offset:128
	global_load_dwordx4 v[138:141], v[138:139], off offset:128
	global_load_dwordx4 v[232:235], v[232:233], off offset:128
	global_load_dwordx4 v[236:239], v[236:237], off offset:128
	global_load_dwordx4 v[142:145], v[142:143], off offset:128
	s_mul_i32 s66, s6, 0x9000
	v_add_u32_e32 v203, s66, v218
	v_add_u32_e32 v190, s66, v189
	s_add_i32 s65, s65, 1
	ds_read_b128 v[146:149], v203
	ds_read_b128 v[150:153], v203 offset:2304
	ds_read_b128 v[154:157], v203 offset:4608
	ds_read_b128 v[158:161], v203 offset:6912
	ds_read_b128 v[174:177], v190
	ds_read_b128 v[170:173], v190 offset:2304
	ds_read_b128 v[166:169], v190 offset:4608
	ds_read_b128 v[162:165], v190 offset:6912
	s_setprio 1
	s_waitcnt lgkmcnt(3)
	v_mfma_f32_16x16x32_bf16 v[126:129], v[146:149], v[174:177], v[126:129]
	v_mfma_f32_16x16x32_bf16 v[122:125], v[150:153], v[174:177], v[122:125]
	v_mfma_f32_16x16x32_bf16 v[118:121], v[154:157], v[174:177], v[118:121]
	v_mfma_f32_16x16x32_bf16 v[114:117], v[158:161], v[174:177], v[114:117]
	s_waitcnt lgkmcnt(2)
	v_mfma_f32_16x16x32_bf16 v[110:113], v[146:149], v[170:173], v[110:113]
	v_mfma_f32_16x16x32_bf16 v[106:109], v[150:153], v[170:173], v[106:109]
	v_mfma_f32_16x16x32_bf16 v[102:105], v[154:157], v[170:173], v[102:105]
	v_mfma_f32_16x16x32_bf16 v[98:101], v[158:161], v[170:173], v[98:101]
	s_waitcnt lgkmcnt(1)
	v_mfma_f32_16x16x32_bf16 v[94:97], v[146:149], v[166:169], v[94:97]
	v_mfma_f32_16x16x32_bf16 v[90:93], v[150:153], v[166:169], v[90:93]
	v_mfma_f32_16x16x32_bf16 v[78:81], v[154:157], v[166:169], v[78:81]
	v_mfma_f32_16x16x32_bf16 v[66:69], v[158:161], v[166:169], v[66:69]
	s_waitcnt lgkmcnt(0)
	v_mfma_f32_16x16x32_bf16 v[70:73], v[146:149], v[162:165], v[70:73]
	v_mfma_f32_16x16x32_bf16 v[82:85], v[150:153], v[162:165], v[82:85]
	v_mfma_f32_16x16x32_bf16 v[74:77], v[154:157], v[162:165], v[74:77]
	v_mfma_f32_16x16x32_bf16 v[86:89], v[158:161], v[162:165], v[86:89]
	s_setprio 0
	ds_read_b128 v[162:165], v190 offset:9216
	ds_read_b128 v[166:169], v190 offset:11520
	ds_read_b128 v[170:173], v190 offset:13824
	ds_read_b128 v[174:177], v190 offset:16128
	s_setprio 1
	s_waitcnt lgkmcnt(3)
	v_mfma_f32_16x16x32_bf16 v[62:65], v[146:149], v[162:165], v[62:65]
	v_mfma_f32_16x16x32_bf16 v[58:61], v[150:153], v[162:165], v[58:61]
	v_mfma_f32_16x16x32_bf16 v[54:57], v[154:157], v[162:165], v[54:57]
	v_mfma_f32_16x16x32_bf16 v[50:53], v[158:161], v[162:165], v[50:53]
	s_waitcnt lgkmcnt(2)
	v_mfma_f32_16x16x32_bf16 v[46:49], v[146:149], v[166:169], v[46:49]
	v_mfma_f32_16x16x32_bf16 v[42:45], v[150:153], v[166:169], v[42:45]
	v_mfma_f32_16x16x32_bf16 v[38:41], v[154:157], v[166:169], v[38:41]
	v_mfma_f32_16x16x32_bf16 v[34:37], v[158:161], v[166:169], v[34:37]
	s_waitcnt lgkmcnt(1)
	v_mfma_f32_16x16x32_bf16 v[30:33], v[146:149], v[170:173], v[30:33]
	v_mfma_f32_16x16x32_bf16 v[26:29], v[150:153], v[170:173], v[26:29]
	v_mfma_f32_16x16x32_bf16 v[22:25], v[154:157], v[170:173], v[22:25]
	v_mfma_f32_16x16x32_bf16 v[18:21], v[158:161], v[170:173], v[18:21]
	s_waitcnt lgkmcnt(0)
	v_mfma_f32_16x16x32_bf16 v[14:17], v[146:149], v[174:177], v[14:17]
	v_mfma_f32_16x16x32_bf16 v[10:13], v[150:153], v[174:177], v[10:13]
	v_mfma_f32_16x16x32_bf16 v[6:9], v[154:157], v[174:177], v[6:9]
	v_mfma_f32_16x16x32_bf16 v[2:5], v[158:161], v[174:177], v[2:5]
	s_setprio 0
	s_waitcnt vmcnt(6)
	v_lshlrev_b32_e32 v248, 16, v130
	v_and_b32_e32 v249, 0xffff0000, v130
	v_lshlrev_b32_e32 v250, 16, v224
	v_and_b32_e32 v251, 0xffff0000, v224
	v_pk_fma_f32 v[248:249], v[240:241], v[250:251], v[248:249]
	v_lshlrev_b32_e32 v252, 16, v131
	v_and_b32_e32 v253, 0xffff0000, v131
	v_lshlrev_b32_e32 v254, 16, v225
	v_and_b32_e32 v255, 0xffff0000, v225
	v_pk_fma_f32 v[252:253], v[242:243], v[254:255], v[252:253]
	v_cvt_pk_bf16_f32 v130, v248, v249
	v_lshlrev_b32_e32 v248, 16, v132
	v_and_b32_e32 v249, 0xffff0000, v132
	v_lshlrev_b32_e32 v250, 16, v226
	v_and_b32_e32 v251, 0xffff0000, v226
	v_pk_fma_f32 v[248:249], v[244:245], v[250:251], v[248:249]
	v_cvt_pk_bf16_f32 v131, v252, v253
	v_lshlrev_b32_e32 v252, 16, v133
	v_and_b32_e32 v253, 0xffff0000, v133
	v_lshlrev_b32_e32 v254, 16, v227
	v_and_b32_e32 v255, 0xffff0000, v227
	v_pk_fma_f32 v[252:253], v[246:247], v[254:255], v[252:253]
	v_cvt_pk_bf16_f32 v132, v248, v249
	s_nop 0
	v_cvt_pk_bf16_f32 v133, v252, v253
	s_waitcnt vmcnt(4)
	v_lshlrev_b32_e32 v248, 16, v134
	v_and_b32_e32 v249, 0xffff0000, v134
	v_lshlrev_b32_e32 v250, 16, v228
	v_and_b32_e32 v251, 0xffff0000, v228
	v_pk_fma_f32 v[248:249], v[240:241], v[250:251], v[248:249]
	v_lshlrev_b32_e32 v252, 16, v135
	v_and_b32_e32 v253, 0xffff0000, v135
	v_lshlrev_b32_e32 v254, 16, v229
	v_and_b32_e32 v255, 0xffff0000, v229
	v_pk_fma_f32 v[252:253], v[242:243], v[254:255], v[252:253]
	v_cvt_pk_bf16_f32 v134, v248, v249
	v_lshlrev_b32_e32 v248, 16, v136
	v_and_b32_e32 v249, 0xffff0000, v136
	v_lshlrev_b32_e32 v250, 16, v230
	v_and_b32_e32 v251, 0xffff0000, v230
	v_pk_fma_f32 v[248:249], v[244:245], v[250:251], v[248:249]
	v_cvt_pk_bf16_f32 v135, v252, v253
	v_lshlrev_b32_e32 v252, 16, v137
	v_and_b32_e32 v253, 0xffff0000, v137
	v_lshlrev_b32_e32 v254, 16, v231
	v_and_b32_e32 v255, 0xffff0000, v231
	v_pk_fma_f32 v[252:253], v[246:247], v[254:255], v[252:253]
	v_cvt_pk_bf16_f32 v136, v248, v249
	s_nop 0
	v_cvt_pk_bf16_f32 v137, v252, v253
	s_waitcnt vmcnt(2)
	v_lshlrev_b32_e32 v248, 16, v138
	v_and_b32_e32 v249, 0xffff0000, v138
	v_lshlrev_b32_e32 v250, 16, v232
	v_and_b32_e32 v251, 0xffff0000, v232
	v_pk_fma_f32 v[248:249], v[240:241], v[250:251], v[248:249]
	v_lshlrev_b32_e32 v252, 16, v139
	v_and_b32_e32 v253, 0xffff0000, v139
	v_lshlrev_b32_e32 v254, 16, v233
	v_and_b32_e32 v255, 0xffff0000, v233
	v_pk_fma_f32 v[252:253], v[242:243], v[254:255], v[252:253]
	v_cvt_pk_bf16_f32 v138, v248, v249
	v_lshlrev_b32_e32 v248, 16, v140
	v_and_b32_e32 v249, 0xffff0000, v140
	v_lshlrev_b32_e32 v250, 16, v234
	v_and_b32_e32 v251, 0xffff0000, v234
	v_pk_fma_f32 v[248:249], v[244:245], v[250:251], v[248:249]
	v_cvt_pk_bf16_f32 v139, v252, v253
	v_lshlrev_b32_e32 v252, 16, v141
	v_and_b32_e32 v253, 0xffff0000, v141
	v_lshlrev_b32_e32 v254, 16, v235
	v_and_b32_e32 v255, 0xffff0000, v235
	v_pk_fma_f32 v[252:253], v[246:247], v[254:255], v[252:253]
	v_cvt_pk_bf16_f32 v140, v248, v249
	s_nop 0
	v_cvt_pk_bf16_f32 v141, v252, v253
	s_waitcnt vmcnt(0)
	v_lshlrev_b32_e32 v248, 16, v142
	v_and_b32_e32 v249, 0xffff0000, v142
	v_lshlrev_b32_e32 v250, 16, v236
	v_and_b32_e32 v251, 0xffff0000, v236
	v_pk_fma_f32 v[248:249], v[240:241], v[250:251], v[248:249]
	v_lshlrev_b32_e32 v252, 16, v143
	v_and_b32_e32 v253, 0xffff0000, v143
	v_lshlrev_b32_e32 v254, 16, v237
	v_and_b32_e32 v255, 0xffff0000, v237
	v_pk_fma_f32 v[252:253], v[242:243], v[254:255], v[252:253]
	v_cvt_pk_bf16_f32 v142, v248, v249
	v_lshlrev_b32_e32 v248, 16, v144
	v_and_b32_e32 v249, 0xffff0000, v144
	v_lshlrev_b32_e32 v250, 16, v238
	v_and_b32_e32 v251, 0xffff0000, v238
	v_pk_fma_f32 v[248:249], v[244:245], v[250:251], v[248:249]
	v_cvt_pk_bf16_f32 v143, v252, v253
	v_lshlrev_b32_e32 v252, 16, v145
	v_and_b32_e32 v253, 0xffff0000, v145
	v_lshlrev_b32_e32 v254, 16, v239
	v_and_b32_e32 v255, 0xffff0000, v239
	v_pk_fma_f32 v[252:253], v[246:247], v[254:255], v[252:253]
	v_cvt_pk_bf16_f32 v144, v248, v249
	s_nop 0
	v_cvt_pk_bf16_f32 v145, v252, v253
	s_lshl_b32 s6, s6, 8
	s_xor_b32 s6, s6, 0x100
	s_mulk_i32 s6, 0x90
	v_add_u32_e32 v146, s6, v193
	ds_write_b128 v146, v[130:133]
	ds_write_b128 v146, v[134:137] offset:9216
	ds_write_b128 v146, v[138:141] offset:18432
	ds_write_b128 v146, v[142:145] offset:27648
	ds_read_b128 v[130:133], v203 offset:64
	ds_read_b128 v[134:137], v203 offset:2368
	ds_read_b128 v[138:141], v190 offset:64
	ds_read_b128 v[142:145], v190 offset:2368
	ds_read_b128 v[146:149], v203 offset:4672
	ds_read_b128 v[150:153], v203 offset:6976
	v_lshl_add_u64 v[158:159], v[208:209], 0, s[16:17]
	s_waitcnt lgkmcnt(3)
	v_mfma_f32_16x16x32_bf16 v[126:129], v[130:133], v[138:141], v[126:129]
	v_add_u32_e32 v203, s6, v210
	v_mfma_f32_16x16x32_bf16 v[122:125], v[134:137], v[138:141], v[122:125]
	s_waitcnt lgkmcnt(1)
	v_mfma_f32_16x16x32_bf16 v[118:121], v[146:149], v[138:141], v[118:121]
	s_waitcnt lgkmcnt(0)
	v_mfma_f32_16x16x32_bf16 v[114:117], v[150:153], v[138:141], v[114:117]
	v_mfma_f32_16x16x32_bf16 v[110:113], v[130:133], v[142:145], v[110:113]
	v_mfma_f32_16x16x32_bf16 v[106:109], v[134:137], v[142:145], v[106:109]
	v_mfma_f32_16x16x32_bf16 v[102:105], v[146:149], v[142:145], v[102:105]
	v_mfma_f32_16x16x32_bf16 v[98:101], v[150:153], v[142:145], v[98:101]
	ds_read_b128 v[138:141], v190 offset:4672
	ds_read_b128 v[142:145], v190 offset:6976
	s_waitcnt lgkmcnt(1)
	v_mfma_f32_16x16x32_bf16 v[94:97], v[130:133], v[138:141], v[94:97]
	v_mfma_f32_16x16x32_bf16 v[90:93], v[134:137], v[138:141], v[90:93]
	v_mfma_f32_16x16x32_bf16 v[78:81], v[146:149], v[138:141], v[78:81]
	v_mfma_f32_16x16x32_bf16 v[66:69], v[150:153], v[138:141], v[66:69]
	v_add_co_u32_e32 v138, vcc, s53, v158
	s_nop 1
	v_addc_co_u32_e32 v139, vcc, 0, v159, vcc
	v_add_co_u32_e32 v154, vcc, s56, v158
	s_waitcnt lgkmcnt(0)
	v_mfma_f32_16x16x32_bf16 v[70:73], v[130:133], v[142:145], v[70:73]
	v_addc_co_u32_e32 v155, vcc, 0, v159, vcc
	v_add_co_u32_e32 v160, vcc, s57, v158
	global_load_dwordx4 v[138:141], v[138:139], off offset:128
	s_nop 0
	global_load_dwordx4 v[154:157], v[154:155], off offset:128
	v_addc_co_u32_e32 v161, vcc, 0, v159, vcc
	v_add_co_u32_e32 v162, vcc, s58, v158
	v_mfma_f32_16x16x32_bf16 v[82:85], v[134:137], v[142:145], v[82:85]
	s_nop 0
	v_addc_co_u32_e32 v163, vcc, 0, v159, vcc
	global_load_dwordx4 v[158:161], v[160:161], off offset:128
	s_nop 0
	global_load_dwordx4 v[162:165], v[162:163], off offset:128
	v_mfma_f32_16x16x32_bf16 v[74:77], v[146:149], v[142:145], v[74:77]
	v_mfma_f32_16x16x32_bf16 v[86:89], v[150:153], v[142:145], v[86:89]
	s_setprio 1
	s_setprio 0
	ds_read_b128 v[142:145], v190 offset:9280
	ds_read_b128 v[166:169], v190 offset:11584
	ds_read_b128 v[170:173], v190 offset:13888
	ds_read_b128 v[174:177], v190 offset:16192
	s_setprio 1
	s_waitcnt lgkmcnt(3)
	v_mfma_f32_16x16x32_bf16 v[62:65], v[130:133], v[142:145], v[62:65]
	v_mfma_f32_16x16x32_bf16 v[58:61], v[134:137], v[142:145], v[58:61]
	v_mfma_f32_16x16x32_bf16 v[54:57], v[146:149], v[142:145], v[54:57]
	v_mfma_f32_16x16x32_bf16 v[50:53], v[150:153], v[142:145], v[50:53]
	s_waitcnt lgkmcnt(2)
	v_mfma_f32_16x16x32_bf16 v[46:49], v[130:133], v[166:169], v[46:49]
	v_mfma_f32_16x16x32_bf16 v[42:45], v[134:137], v[166:169], v[42:45]
	v_mfma_f32_16x16x32_bf16 v[38:41], v[146:149], v[166:169], v[38:41]
	v_mfma_f32_16x16x32_bf16 v[34:37], v[150:153], v[166:169], v[34:37]
	s_waitcnt lgkmcnt(1)
	v_mfma_f32_16x16x32_bf16 v[30:33], v[130:133], v[170:173], v[30:33]
	v_mfma_f32_16x16x32_bf16 v[26:29], v[134:137], v[170:173], v[26:29]
	v_mfma_f32_16x16x32_bf16 v[22:25], v[146:149], v[170:173], v[22:25]
	v_mfma_f32_16x16x32_bf16 v[18:21], v[150:153], v[170:173], v[18:21]
	s_waitcnt lgkmcnt(0)
	v_mfma_f32_16x16x32_bf16 v[14:17], v[130:133], v[174:177], v[14:17]
	v_mfma_f32_16x16x32_bf16 v[10:13], v[134:137], v[174:177], v[10:13]
	v_mfma_f32_16x16x32_bf16 v[6:9], v[146:149], v[174:177], v[6:9]
	v_mfma_f32_16x16x32_bf16 v[2:5], v[150:153], v[174:177], v[2:5]
	s_setprio 0
	s_add_u32 s16, s16, 0x80
	s_addc_u32 s17, s17, 0
	s_cmpk_lg_i32 s16, 0x780
	v_lshl_add_u64 v[206:207], v[206:207], 0, s[10:11]
	s_waitcnt vmcnt(3)
	ds_write_b128 v203, v[138:141]
	s_waitcnt vmcnt(2)
	ds_write_b128 v203, v[154:157] offset:9216
	s_waitcnt vmcnt(1)
	ds_write_b128 v203, v[158:161] offset:18432
	s_waitcnt vmcnt(0)
	ds_write_b128 v203, v[162:165] offset:27648
	s_waitcnt lgkmcnt(0)
	s_barrier
	s_cbranch_scc1 .LBB0_513
	s_setprio 0
	ds_read_b128 v[130:133], v189 offset:43776
	ds_read_b128 v[134:137], v189 offset:41472
	ds_read_b128 v[138:141], v189 offset:39168
	ds_read_b128 v[142:145], v189 offset:36864
	ds_read_b128 v[146:149], v218 offset:43776
	ds_read_b128 v[150:153], v218 offset:41472
	ds_read_b128 v[154:157], v218 offset:39168
	ds_read_b128 v[158:161], v218 offset:36864
	s_setprio 1
	s_waitcnt lgkmcnt(0)
	v_mfma_f32_16x16x32_bf16 v[126:129], v[158:161], v[142:145], v[126:129]
	v_mfma_f32_16x16x32_bf16 v[122:125], v[154:157], v[142:145], v[122:125]
	v_mfma_f32_16x16x32_bf16 v[118:121], v[150:153], v[142:145], v[118:121]
	v_mfma_f32_16x16x32_bf16 v[114:117], v[146:149], v[142:145], v[114:117]
	v_mfma_f32_16x16x32_bf16 v[110:113], v[158:161], v[138:141], v[110:113]
	v_mfma_f32_16x16x32_bf16 v[106:109], v[154:157], v[138:141], v[106:109]
	v_mfma_f32_16x16x32_bf16 v[102:105], v[150:153], v[138:141], v[102:105]
	v_mfma_f32_16x16x32_bf16 v[98:101], v[146:149], v[138:141], v[98:101]
	v_mfma_f32_16x16x32_bf16 v[94:97], v[158:161], v[134:137], v[94:97]
	v_mfma_f32_16x16x32_bf16 v[90:93], v[154:157], v[134:137], v[90:93]
	v_mfma_f32_16x16x32_bf16 v[78:81], v[150:153], v[134:137], v[78:81]
	v_mfma_f32_16x16x32_bf16 v[66:69], v[146:149], v[134:137], v[66:69]
	v_mfma_f32_16x16x32_bf16 v[70:73], v[158:161], v[130:133], v[70:73]
	v_mfma_f32_16x16x32_bf16 v[134:137], v[154:157], v[130:133], v[82:85]
	v_mfma_f32_16x16x32_bf16 v[138:141], v[150:153], v[130:133], v[74:77]
	v_mfma_f32_16x16x32_bf16 v[130:133], v[146:149], v[130:133], v[86:89]
	s_setprio 0
	s_nop 0
	ds_read_b128 v[74:77], v189 offset:46080
	ds_read_b128 v[82:85], v189 offset:48384
	ds_read_b128 v[86:89], v189 offset:50688
	ds_read_b128 v[142:145], v189 offset:52992
	s_setprio 1
	s_waitcnt lgkmcnt(3)
	v_mfma_f32_16x16x32_bf16 v[62:65], v[158:161], v[74:77], v[62:65]
	v_mfma_f32_16x16x32_bf16 v[58:61], v[154:157], v[74:77], v[58:61]
	v_mfma_f32_16x16x32_bf16 v[54:57], v[150:153], v[74:77], v[54:57]
	v_mfma_f32_16x16x32_bf16 v[50:53], v[146:149], v[74:77], v[50:53]
	s_waitcnt lgkmcnt(2)
	v_mfma_f32_16x16x32_bf16 v[46:49], v[158:161], v[82:85], v[46:49]
	v_mfma_f32_16x16x32_bf16 v[42:45], v[154:157], v[82:85], v[42:45]
	v_mfma_f32_16x16x32_bf16 v[38:41], v[150:153], v[82:85], v[38:41]
	v_mfma_f32_16x16x32_bf16 v[34:37], v[146:149], v[82:85], v[34:37]
	s_waitcnt lgkmcnt(1)
	v_mfma_f32_16x16x32_bf16 v[30:33], v[158:161], v[86:89], v[30:33]
	v_mfma_f32_16x16x32_bf16 v[26:29], v[154:157], v[86:89], v[26:29]
	v_mfma_f32_16x16x32_bf16 v[22:25], v[150:153], v[86:89], v[22:25]
	v_mfma_f32_16x16x32_bf16 v[18:21], v[146:149], v[86:89], v[18:21]
	s_waitcnt lgkmcnt(0)
	v_mfma_f32_16x16x32_bf16 v[14:17], v[158:161], v[142:145], v[14:17]
	v_mfma_f32_16x16x32_bf16 v[10:13], v[154:157], v[142:145], v[10:13]
	v_mfma_f32_16x16x32_bf16 v[6:9], v[150:153], v[142:145], v[6:9]
	v_mfma_f32_16x16x32_bf16 v[2:5], v[146:149], v[142:145], v[2:5]
	s_setprio 0
	ds_read_b128 v[142:145], v189 offset:43840
	ds_read_b128 v[74:77], v189 offset:41536
	ds_read_b128 v[82:85], v189 offset:39232
	ds_read_b128 v[86:89], v189 offset:36928
	ds_read_b128 v[146:149], v218 offset:36928
	ds_read_b128 v[150:153], v218 offset:39232
	ds_read_b128 v[154:157], v218 offset:41536
	ds_read_b128 v[158:161], v218 offset:43840
	s_setprio 1
	s_waitcnt lgkmcnt(3)
	v_mfma_f32_16x16x32_bf16 v[126:129], v[146:149], v[86:89], v[126:129]
	s_waitcnt lgkmcnt(2)
	v_mfma_f32_16x16x32_bf16 v[122:125], v[150:153], v[86:89], v[122:125]
	s_waitcnt lgkmcnt(1)
	v_mfma_f32_16x16x32_bf16 v[118:121], v[154:157], v[86:89], v[118:121]
	s_waitcnt lgkmcnt(0)
	v_mfma_f32_16x16x32_bf16 v[114:117], v[158:161], v[86:89], v[114:117]
	v_mfma_f32_16x16x32_bf16 v[110:113], v[146:149], v[82:85], v[110:113]
	v_mfma_f32_16x16x32_bf16 v[106:109], v[150:153], v[82:85], v[106:109]
	v_mfma_f32_16x16x32_bf16 v[102:105], v[154:157], v[82:85], v[102:105]
	v_mfma_f32_16x16x32_bf16 v[98:101], v[158:161], v[82:85], v[98:101]
	v_mfma_f32_16x16x32_bf16 v[94:97], v[146:149], v[74:77], v[94:97]
	v_mfma_f32_16x16x32_bf16 v[90:93], v[150:153], v[74:77], v[90:93]
	v_mfma_f32_16x16x32_bf16 v[86:89], v[154:157], v[74:77], v[78:81]
	v_mfma_f32_16x16x32_bf16 v[82:85], v[158:161], v[74:77], v[66:69]
	v_mfma_f32_16x16x32_bf16 v[78:81], v[146:149], v[142:145], v[70:73]
	v_mfma_f32_16x16x32_bf16 v[74:77], v[150:153], v[142:145], v[134:137]
	v_mfma_f32_16x16x32_bf16 v[70:73], v[154:157], v[142:145], v[138:141]
	v_mfma_f32_16x16x32_bf16 v[66:69], v[158:161], v[142:145], v[130:133]
	s_setprio 0
	s_nop 1
	ds_read_b128 v[130:133], v189 offset:46144
	ds_read_b128 v[134:137], v189 offset:48448
	ds_read_b128 v[138:141], v189 offset:50752
	ds_read_b128 v[142:145], v189 offset:53056
	s_setprio 1
	s_waitcnt lgkmcnt(3)
	v_mfma_f32_16x16x32_bf16 v[62:65], v[146:149], v[130:133], v[62:65]
	v_mfma_f32_16x16x32_bf16 v[58:61], v[150:153], v[130:133], v[58:61]
	v_mfma_f32_16x16x32_bf16 v[54:57], v[154:157], v[130:133], v[54:57]
	v_mfma_f32_16x16x32_bf16 v[50:53], v[158:161], v[130:133], v[50:53]
	s_waitcnt lgkmcnt(2)
	v_mfma_f32_16x16x32_bf16 v[46:49], v[146:149], v[134:137], v[46:49]
	v_mfma_f32_16x16x32_bf16 v[42:45], v[150:153], v[134:137], v[42:45]
	v_mfma_f32_16x16x32_bf16 v[38:41], v[154:157], v[134:137], v[38:41]
	v_mfma_f32_16x16x32_bf16 v[34:37], v[158:161], v[134:137], v[34:37]
	s_waitcnt lgkmcnt(1)
	v_mfma_f32_16x16x32_bf16 v[30:33], v[146:149], v[138:141], v[30:33]
	v_mfma_f32_16x16x32_bf16 v[26:29], v[150:153], v[138:141], v[26:29]
	v_mfma_f32_16x16x32_bf16 v[22:25], v[154:157], v[138:141], v[22:25]
	v_mfma_f32_16x16x32_bf16 v[18:21], v[158:161], v[138:141], v[18:21]
	s_waitcnt lgkmcnt(0)
	v_mfma_f32_16x16x32_bf16 v[14:17], v[146:149], v[142:145], v[14:17]
	v_mfma_f32_16x16x32_bf16 v[10:13], v[150:153], v[142:145], v[10:13]
	v_mfma_f32_16x16x32_bf16 v[6:9], v[154:157], v[142:145], v[6:9]
	v_mfma_f32_16x16x32_bf16 v[2:5], v[158:161], v[142:145], v[2:5]
	s_setprio 0
	v_lshl_or_b32 v156, s63, 8, v220
	v_lshlrev_b32_e32 v190, 1, v156
	v_lshrrev_b32_e32 v130, 4, v156
	v_mov_b32_e32 v131, v191
	v_add_u32_e32 v157, s64, v219
	v_lshl_add_u64 v[150:151], v[194:195], 0, v[190:191]
	v_lshl_add_u64 v[148:149], v[196:197], 0, v[190:191]
	v_lshl_add_u64 v[146:147], s[8:9], 0, v[130:131]
	s_mov_b64 s[16:17], -1
	s_and_b64 vcc, exec, s[14:15]
	s_barrier
	s_cbranch_vccz .LBB0_542
	s_and_b64 vcc, exec, s[12:13]
	s_cbranch_vccz .LBB0_517
	v_or_b32_e32 v130, v157, v215
	v_ashrrev_i32_e32 v131, 31, v130
	v_lshlrev_b64 v[132:133], 11, v[130:131]
	v_lshl_add_u64 v[132:133], v[150:151], 0, v[132:133]
	v_cvt_pk_bf16_f32 v134, v126, v127
	v_cvt_pk_bf16_f32 v135, v128, v129
	global_store_dwordx2 v[132:133], v[134:135], off
	v_cvt_pk_bf16_f32 v134, v122, v123
	v_cvt_pk_bf16_f32 v135, v124, v125
	global_store_dwordx2 v[132:133], v[134:135], off offset:32
	v_cvt_pk_bf16_f32 v134, v118, v119
	v_cvt_pk_bf16_f32 v135, v120, v121
	global_store_dwordx2 v[132:133], v[134:135], off offset:64
	v_cvt_pk_bf16_f32 v134, v114, v115
	v_cvt_pk_bf16_f32 v135, v116, v117
	global_store_dwordx2 v[132:133], v[134:135], off offset:96
	v_or_b32_e32 v132, 16, v130
	v_ashrrev_i32_e32 v133, 31, v132
	v_lshlrev_b64 v[132:133], 11, v[132:133]
	v_lshl_add_u64 v[132:133], v[150:151], 0, v[132:133]
	v_cvt_pk_bf16_f32 v134, v110, v111
	v_cvt_pk_bf16_f32 v135, v112, v113
	global_store_dwordx2 v[132:133], v[134:135], off
	v_cvt_pk_bf16_f32 v134, v106, v107
	v_cvt_pk_bf16_f32 v135, v108, v109
	global_store_dwordx2 v[132:133], v[134:135], off offset:32
	v_cvt_pk_bf16_f32 v134, v102, v103
	v_cvt_pk_bf16_f32 v135, v104, v105
	global_store_dwordx2 v[132:133], v[134:135], off offset:64
	v_cvt_pk_bf16_f32 v134, v98, v99
	v_cvt_pk_bf16_f32 v135, v100, v101
	global_store_dwordx2 v[132:133], v[134:135], off offset:96
	v_or_b32_e32 v132, 32, v130
	v_ashrrev_i32_e32 v133, 31, v132
	v_lshlrev_b64 v[132:133], 11, v[132:133]
	v_lshl_add_u64 v[132:133], v[150:151], 0, v[132:133]
	v_cvt_pk_bf16_f32 v134, v94, v95
	v_cvt_pk_bf16_f32 v135, v96, v97
	global_store_dwordx2 v[132:133], v[134:135], off
	v_cvt_pk_bf16_f32 v134, v90, v91
	v_cvt_pk_bf16_f32 v135, v92, v93
	v_or_b32_e32 v130, 48, v130
	global_store_dwordx2 v[132:133], v[134:135], off offset:32
	v_cvt_pk_bf16_f32 v134, v86, v87
	v_cvt_pk_bf16_f32 v135, v88, v89
	v_ashrrev_i32_e32 v131, 31, v130
	global_store_dwordx2 v[132:133], v[134:135], off offset:64
	v_cvt_pk_bf16_f32 v134, v82, v83
	v_cvt_pk_bf16_f32 v135, v84, v85
	v_lshlrev_b64 v[130:131], 11, v[130:131]
	global_store_dwordx2 v[132:133], v[134:135], off offset:96
	v_lshl_add_u64 v[130:131], v[150:151], 0, v[130:131]
	v_cvt_pk_bf16_f32 v132, v78, v79
	v_cvt_pk_bf16_f32 v133, v80, v81
	global_store_dwordx2 v[130:131], v[132:133], off
	v_cvt_pk_bf16_f32 v132, v74, v75
	v_cvt_pk_bf16_f32 v133, v76, v77
	global_store_dwordx2 v[130:131], v[132:133], off offset:32
	v_cvt_pk_bf16_f32 v132, v70, v71
	v_cvt_pk_bf16_f32 v133, v72, v73
	global_store_dwordx2 v[130:131], v[132:133], off offset:64
	v_cvt_pk_bf16_f32 v132, v66, v67
	v_cvt_pk_bf16_f32 v133, v68, v69
	global_store_dwordx2 v[130:131], v[132:133], off offset:96
	s_mov_b64 s[16:17], 0

.LBB0_552:
	s_cmp_lg_u32 s47, 0
	s_cselect_b64 s[12:13], -1, 0
	s_cmp_lg_u32 s47, 1
	s_cselect_b64 s[10:11], -1, 0
	s_cmp_eq_u32 s47, 1
	s_cselect_b32 s0, s17, 0x1400
	s_cselect_b32 s1, s29, 0x2c80000
	s_lshl_b32 s49, s48, 8
	v_or_b32_e32 v2, s49, v1
	v_ashrrev_i32_e32 v3, 31, v2
	v_lshlrev_b64 v[18:19], 11, v[2:3]
	v_lshl_add_u64 v[36:37], v[178:179], 0, v[18:19]
	s_cmp_eq_u32 s47, 0
	v_add_co_u32_e32 v20, vcc, s36, v36
	v_lshl_add_u64 v[38:39], v[180:181], 0, v[18:19]
	s_cselect_b32 s0, 0x400, s0
	v_addc_co_u32_e32 v21, vcc, 0, v37, vcc
	global_load_dwordx4 v[10:13], v[36:37], off
	global_load_dwordx4 v[14:17], v[38:39], off
	s_cselect_b32 s14, 0x2c00000, s1
	s_lshl_b32 s6, s0, 2
	v_add_co_u32_e32 v24, vcc, s36, v38
	v_lshl_add_u64 v[6:7], v[182:183], 0, s[6:7]
	s_nop 0
	v_addc_co_u32_e32 v25, vcc, 0, v39, vcc
	global_load_dwordx4 v[2:5], v[6:7], off offset:16
	s_nop 0
	global_load_dwordx4 v[6:9], v[6:7], off
	s_nop 0
	global_load_dwordx4 v[20:23], v[20:21], off
	s_nop 0
	global_load_dwordx4 v[24:27], v[24:25], off
	v_add_co_u32_e32 v28, vcc, s37, v36
	v_add_co_u32_e64 v36, s[0:1], s38, v36
	s_nop 0
	v_addc_co_u32_e32 v29, vcc, 0, v37, vcc
	v_add_co_u32_e32 v32, vcc, s37, v38
	v_addc_co_u32_e64 v37, s[0:1], 0, v37, s[0:1]
	s_nop 0
	v_addc_co_u32_e32 v33, vcc, 0, v39, vcc
	global_load_dwordx4 v[28:31], v[28:29], off
	s_nop 0
	global_load_dwordx4 v[32:35], v[32:33], off
	v_add_co_u32_e64 v40, s[0:1], s38, v38
	s_mov_b32 s15, 0
	s_nop 0
	v_addc_co_u32_e64 v41, s[0:1], 0, v39, s[0:1]
	global_load_dwordx4 v[36:39], v[36:37], off
	s_nop 0
	global_load_dwordx4 v[40:43], v[40:41], off
	v_lshl_add_u64 v[82:83], v[74:75], 0, s[14:15]
	v_add_co_u32_e32 v48, vcc, 0x20000, v82
	s_waitcnt lgkmcnt(0)
	s_nop 0
	v_addc_co_u32_e32 v49, vcc, 0, v83, vcc
	s_barrier
	global_load_dwordx4 v[44:47], v[82:83], off
	s_nop 0
	global_load_dwordx4 v[48:51], v[48:49], off
	v_lshl_add_u64 v[84:85], v[184:185], 0, v[18:19]
	v_lshl_add_u64 v[86:87], v[186:187], 0, s[6:7]
	s_mov_b64 s[0:1], 0
	s_waitcnt vmcnt(11)
	v_lshlrev_b32_e32 v56, 16, v12
	s_waitcnt vmcnt(10)
	v_lshlrev_b32_e32 v58, 16, v16
	v_and_b32_e32 v57, 0xffff0000, v12
	v_and_b32_e32 v59, 0xffff0000, v16
	v_lshlrev_b32_e32 v12, 16, v13
	v_lshlrev_b32_e32 v16, 16, v17
	v_and_b32_e32 v13, 0xffff0000, v13
	v_and_b32_e32 v17, 0xffff0000, v17
	v_lshlrev_b32_e32 v52, 16, v10
	v_lshlrev_b32_e32 v54, 16, v14
	v_and_b32_e32 v53, 0xffff0000, v10
	v_and_b32_e32 v55, 0xffff0000, v14
	v_lshlrev_b32_e32 v10, 16, v11
	v_lshlrev_b32_e32 v14, 16, v15
	v_and_b32_e32 v11, 0xffff0000, v11
	v_and_b32_e32 v15, 0xffff0000, v15
	s_waitcnt vmcnt(9)
	v_pk_fma_f32 v[16:17], v[4:5], v[16:17], v[12:13]
	s_waitcnt vmcnt(8)
	v_pk_fma_f32 v[52:53], v[6:7], v[54:55], v[52:53]
	v_pk_fma_f32 v[14:15], v[8:9], v[14:15], v[10:11]
	v_pk_fma_f32 v[54:55], v[2:3], v[58:59], v[56:57]
	s_waitcnt vmcnt(7)
	v_lshlrev_b32_e32 v56, 16, v20
	s_waitcnt vmcnt(6)
	v_lshlrev_b32_e32 v58, 16, v24
	v_and_b32_e32 v57, 0xffff0000, v20
	v_cvt_pk_bf16_f32 v13, v16, v17
	v_and_b32_e32 v59, 0xffff0000, v24
	v_lshlrev_b32_e32 v16, 16, v21
	v_lshlrev_b32_e32 v20, 16, v25
	v_and_b32_e32 v17, 0xffff0000, v21
	v_and_b32_e32 v21, 0xffff0000, v25
	v_cvt_pk_bf16_f32 v11, v14, v15
	v_pk_fma_f32 v[14:15], v[6:7], v[58:59], v[56:57]
	v_pk_fma_f32 v[16:17], v[8:9], v[20:21], v[16:17]
	v_cvt_pk_bf16_f32 v14, v14, v15
	v_cvt_pk_bf16_f32 v15, v16, v17
	v_lshlrev_b32_e32 v16, 16, v22
	v_lshlrev_b32_e32 v20, 16, v26
	v_and_b32_e32 v17, 0xffff0000, v22
	v_and_b32_e32 v21, 0xffff0000, v26
	v_pk_fma_f32 v[16:17], v[2:3], v[20:21], v[16:17]
	v_lshlrev_b32_e32 v20, 16, v23
	v_lshlrev_b32_e32 v22, 16, v27
	v_and_b32_e32 v21, 0xffff0000, v23
	v_and_b32_e32 v23, 0xffff0000, v27
	v_pk_fma_f32 v[20:21], v[4:5], v[22:23], v[20:21]
	v_cvt_pk_bf16_f32 v16, v16, v17
	v_cvt_pk_bf16_f32 v17, v20, v21
	s_waitcnt vmcnt(5)
	v_lshlrev_b32_e32 v20, 16, v28
	s_waitcnt vmcnt(4)
	v_lshlrev_b32_e32 v22, 16, v32
	v_and_b32_e32 v21, 0xffff0000, v28
	v_and_b32_e32 v23, 0xffff0000, v32
	v_pk_fma_f32 v[20:21], v[6:7], v[22:23], v[20:21]
	v_lshlrev_b32_e32 v22, 16, v29
	v_lshlrev_b32_e32 v24, 16, v33
	v_and_b32_e32 v23, 0xffff0000, v29
	v_and_b32_e32 v25, 0xffff0000, v33
	v_pk_fma_f32 v[22:23], v[8:9], v[24:25], v[22:23]
	v_cvt_pk_bf16_f32 v20, v20, v21
	v_cvt_pk_bf16_f32 v21, v22, v23
	v_lshlrev_b32_e32 v22, 16, v30
	v_lshlrev_b32_e32 v24, 16, v34
	v_and_b32_e32 v23, 0xffff0000, v30
	v_and_b32_e32 v25, 0xffff0000, v34
	v_pk_fma_f32 v[22:23], v[2:3], v[24:25], v[22:23]
	v_lshlrev_b32_e32 v24, 16, v31
	v_lshlrev_b32_e32 v26, 16, v35
	v_and_b32_e32 v25, 0xffff0000, v31
	v_and_b32_e32 v27, 0xffff0000, v35
	v_pk_fma_f32 v[24:25], v[4:5], v[26:27], v[24:25]
	v_cvt_pk_bf16_f32 v22, v22, v23
	v_cvt_pk_bf16_f32 v23, v24, v25
	s_waitcnt vmcnt(3)
	v_lshlrev_b32_e32 v24, 16, v36
	s_waitcnt vmcnt(2)
	v_lshlrev_b32_e32 v26, 16, v40
	v_and_b32_e32 v25, 0xffff0000, v36
	v_and_b32_e32 v27, 0xffff0000, v40
	v_pk_fma_f32 v[6:7], v[6:7], v[26:27], v[24:25]
	v_lshlrev_b32_e32 v24, 16, v37
	v_lshlrev_b32_e32 v26, 16, v41
	v_and_b32_e32 v25, 0xffff0000, v37
	v_and_b32_e32 v27, 0xffff0000, v41
	v_pk_fma_f32 v[8:9], v[8:9], v[26:27], v[24:25]
	v_cvt_pk_bf16_f32 v6, v6, v7
	v_cvt_pk_bf16_f32 v7, v8, v9
	v_lshlrev_b32_e32 v8, 16, v38
	v_lshlrev_b32_e32 v24, 16, v42
	v_and_b32_e32 v9, 0xffff0000, v38
	v_and_b32_e32 v25, 0xffff0000, v42
	v_pk_fma_f32 v[2:3], v[2:3], v[24:25], v[8:9]
	v_lshlrev_b32_e32 v24, 16, v43
	v_cvt_pk_bf16_f32 v8, v2, v3
	v_lshlrev_b32_e32 v2, 16, v39
	v_and_b32_e32 v3, 0xffff0000, v39
	v_and_b32_e32 v25, 0xffff0000, v43
	v_cvt_pk_bf16_f32 v10, v52, v53
	v_cvt_pk_bf16_f32 v12, v54, v55
	v_pk_fma_f32 v[2:3], v[4:5], v[24:25], v[2:3]
	s_nop 0
	v_cvt_pk_bf16_f32 v9, v2, v3
	ds_write_b128 v193, v[10:13]
	ds_write_b128 v193, v[14:17] offset:9216
	ds_write_b128 v193, v[20:23] offset:18432
	ds_write_b128 v193, v[6:9] offset:27648
	s_waitcnt vmcnt(1)
	ds_write_b128 v210, v[44:47]
	s_waitcnt vmcnt(0)
	ds_write_b128 v210, v[48:51] offset:9216
	v_mov_b32_e32 v6, 0
	v_mov_b32_e32 v7, v6
	v_mov_b32_e32 v8, v6
	v_mov_b32_e32 v9, v6
	v_mov_b32_e32 v14, v6
	v_mov_b32_e32 v15, v6
	v_mov_b32_e32 v16, v6
	v_mov_b32_e32 v17, v6
	v_mov_b32_e32 v2, v6
	v_mov_b32_e32 v3, v6
	v_mov_b32_e32 v4, v6
	v_mov_b32_e32 v5, v6
	v_mov_b32_e32 v10, v6
	v_mov_b32_e32 v11, v6
	v_mov_b32_e32 v12, v6
	v_mov_b32_e32 v13, v6
	v_mov_b32_e32 v18, v6
	v_mov_b32_e32 v19, v6
	v_mov_b32_e32 v20, v6
	v_mov_b32_e32 v21, v6
	v_mov_b32_e32 v22, v6
	v_mov_b32_e32 v23, v6
	v_mov_b32_e32 v24, v6
	v_mov_b32_e32 v25, v6
	v_mov_b32_e32 v26, v6
	v_mov_b32_e32 v27, v6
	v_mov_b32_e32 v28, v6
	v_mov_b32_e32 v29, v6
	v_mov_b32_e32 v30, v6
	v_mov_b32_e32 v31, v6
	v_mov_b32_e32 v32, v6
	v_mov_b32_e32 v33, v6
	v_mov_b32_e32 v34, v6
	v_mov_b32_e32 v35, v6
	v_mov_b32_e32 v36, v6
	v_mov_b32_e32 v37, v6
	v_mov_b32_e32 v38, v6
	v_mov_b32_e32 v39, v6
	v_mov_b32_e32 v40, v6
	v_mov_b32_e32 v41, v6
	v_mov_b32_e32 v42, v6
	v_mov_b32_e32 v43, v6
	v_mov_b32_e32 v44, v6
	v_mov_b32_e32 v45, v6
	v_mov_b32_e32 v46, v6
	v_mov_b32_e32 v47, v6
	v_mov_b32_e32 v48, v6
	v_mov_b32_e32 v49, v6
	v_mov_b32_e32 v50, v6
	v_mov_b32_e32 v51, v6
	v_mov_b32_e32 v52, v6
	v_mov_b32_e32 v53, v6
	v_mov_b32_e32 v54, v6
	v_mov_b32_e32 v55, v6
	v_mov_b32_e32 v56, v6
	v_mov_b32_e32 v57, v6
	v_mov_b32_e32 v58, v6
	v_mov_b32_e32 v59, v6
	v_mov_b32_e32 v60, v6
	v_mov_b32_e32 v61, v6
	v_mov_b32_e32 v62, v6
	v_mov_b32_e32 v63, v6
	v_mov_b32_e32 v64, v6
	v_mov_b32_e32 v65, v6
	s_waitcnt lgkmcnt(0)
	s_barrier
	v_readfirstlane_b32 s97, v0
	s_bfe_u32 s97, s97, 0x40006
	s_cmp_lt_u32 s97, 4
	s_cbranch_scc1 .Lhp_p9b
	s_setprio 1
.Lhp_p9b:
.LBB0_553:
	v_lshl_add_u64 v[92:93], v[84:85], 0, s[0:1]
	v_add_co_u32_e32 v94, vcc, s39, v92
	global_load_dwordx4 v[66:69], v[86:87], off offset:16
	global_load_dwordx4 v[70:73], v[86:87], off
	v_addc_co_u32_e32 v95, vcc, 0, v93, vcc
	v_add_co_u32_e32 v96, vcc, s40, v92
	s_and_b32 s6, s15, 1
	s_nop 0
	v_addc_co_u32_e32 v97, vcc, 0, v93, vcc
	v_add_co_u32_e32 v100, vcc, s41, v92
	s_mul_i32 s52, s6, 0x4800
	s_nop 0
	v_addc_co_u32_e32 v101, vcc, 0, v93, vcc
	v_add_co_u32_e32 v104, vcc, s42, v92
	s_mul_i32 s14, s6, 0x9000
	s_nop 0
	v_addc_co_u32_e32 v105, vcc, 0, v93, vcc
	v_add_co_u32_e32 v108, vcc, s43, v92
	v_add_u32_e32 v192, s52, v89
	s_nop 0
	v_addc_co_u32_e32 v109, vcc, 0, v93, vcc
	v_add_co_u32_e32 v112, vcc, s44, v92
	v_add_u32_e32 v91, s14, v88
	s_nop 0
	v_addc_co_u32_e32 v113, vcc, 0, v93, vcc
	v_add_co_u32_e32 v116, vcc, s45, v92
	s_add_i32 s15, s15, 1
	s_nop 0
	v_addc_co_u32_e32 v117, vcc, 0, v93, vcc
	v_add_co_u32_e32 v120, vcc, s46, v92
	s_nop 1
	v_addc_co_u32_e32 v121, vcc, 0, v93, vcc
	global_load_dwordx4 v[92:95], v[94:95], off offset:128
	s_nop 0
	global_load_dwordx4 v[96:99], v[96:97], off offset:128
	s_nop 0
	global_load_dwordx4 v[100:103], v[100:101], off offset:128
	s_nop 0
	global_load_dwordx4 v[104:107], v[104:105], off offset:128
	s_nop 0
	global_load_dwordx4 v[108:111], v[108:109], off offset:128
	s_nop 0
	global_load_dwordx4 v[112:115], v[112:113], off offset:128
	s_nop 0
	global_load_dwordx4 v[116:119], v[116:117], off offset:128
	s_nop 0
	global_load_dwordx4 v[120:123], v[120:121], off offset:128
	ds_read_b128 v[124:127], v192
	ds_read_b128 v[128:131], v192 offset:2304
	ds_read_b128 v[132:135], v192 offset:4608
	ds_read_b128 v[136:139], v192 offset:6912
	ds_read_b128 v[140:143], v91
	ds_read_b128 v[144:147], v91 offset:2304
	ds_read_b128 v[148:151], v91 offset:4608
	ds_read_b128 v[152:155], v91 offset:6912
	s_waitcnt vmcnt(7)
	v_lshlrev_b32_e32 v156, 16, v92
	s_waitcnt vmcnt(6)
	v_lshlrev_b32_e32 v158, 16, v96
	v_and_b32_e32 v157, 0xffff0000, v92
	v_and_b32_e32 v159, 0xffff0000, v96
	v_lshlrev_b32_e32 v92, 16, v93
	v_lshlrev_b32_e32 v96, 16, v97
	v_and_b32_e32 v93, 0xffff0000, v93
	v_and_b32_e32 v97, 0xffff0000, v97
	v_lshlrev_b32_e32 v160, 16, v94
	v_lshlrev_b32_e32 v162, 16, v98
	v_and_b32_e32 v161, 0xffff0000, v94
	v_and_b32_e32 v163, 0xffff0000, v98
	v_lshlrev_b32_e32 v94, 16, v95
	v_lshlrev_b32_e32 v98, 16, v99
	v_and_b32_e32 v95, 0xffff0000, v95
	v_and_b32_e32 v99, 0xffff0000, v99
	s_waitcnt vmcnt(5)
	v_lshlrev_b32_e32 v164, 16, v100
	s_waitcnt vmcnt(4)
	v_lshlrev_b32_e32 v166, 16, v104
	v_and_b32_e32 v165, 0xffff0000, v100
	v_and_b32_e32 v167, 0xffff0000, v104
	v_lshlrev_b32_e32 v100, 16, v101
	v_lshlrev_b32_e32 v104, 16, v105
	v_and_b32_e32 v101, 0xffff0000, v101
	v_and_b32_e32 v105, 0xffff0000, v105
	v_lshlrev_b32_e32 v168, 16, v102
	v_lshlrev_b32_e32 v170, 16, v106
	v_and_b32_e32 v169, 0xffff0000, v102
	v_and_b32_e32 v171, 0xffff0000, v106
	v_lshlrev_b32_e32 v102, 16, v103
	v_lshlrev_b32_e32 v106, 16, v107
	v_and_b32_e32 v103, 0xffff0000, v103
	v_and_b32_e32 v107, 0xffff0000, v107
	s_waitcnt vmcnt(3)
	v_lshlrev_b32_e32 v172, 16, v108
	s_waitcnt vmcnt(2)
	v_lshlrev_b32_e32 v174, 16, v112
	v_and_b32_e32 v173, 0xffff0000, v108
	v_and_b32_e32 v175, 0xffff0000, v112
	v_lshlrev_b32_e32 v108, 16, v109
	v_lshlrev_b32_e32 v112, 16, v113
	v_and_b32_e32 v109, 0xffff0000, v109
	v_and_b32_e32 v113, 0xffff0000, v113
	v_lshlrev_b32_e32 v176, 16, v110
	v_lshlrev_b32_e32 v188, 16, v114
	v_and_b32_e32 v177, 0xffff0000, v110
	v_and_b32_e32 v189, 0xffff0000, v114
	v_lshlrev_b32_e32 v110, 16, v111
	v_lshlrev_b32_e32 v114, 16, v115
	v_and_b32_e32 v111, 0xffff0000, v111
	v_and_b32_e32 v115, 0xffff0000, v115
	s_waitcnt vmcnt(1)
	v_lshlrev_b32_e32 v190, 16, v116
	s_waitcnt vmcnt(0)
	v_lshlrev_b32_e32 v194, 16, v120
	v_and_b32_e32 v191, 0xffff0000, v116
	v_and_b32_e32 v195, 0xffff0000, v120
	v_lshlrev_b32_e32 v116, 16, v117
	v_lshlrev_b32_e32 v120, 16, v121
	v_and_b32_e32 v117, 0xffff0000, v117
	v_and_b32_e32 v121, 0xffff0000, v121
	v_lshlrev_b32_e32 v196, 16, v118
	v_lshlrev_b32_e32 v198, 16, v122
	v_and_b32_e32 v197, 0xffff0000, v118
	v_and_b32_e32 v199, 0xffff0000, v122
	v_lshlrev_b32_e32 v118, 16, v119
	v_lshlrev_b32_e32 v122, 16, v123
	v_and_b32_e32 v119, 0xffff0000, v119
	v_and_b32_e32 v123, 0xffff0000, v123
	v_pk_fma_f32 v[156:157], v[70:71], v[158:159], v[156:157]
	v_pk_fma_f32 v[92:93], v[72:73], v[96:97], v[92:93]
	v_pk_fma_f32 v[96:97], v[66:67], v[162:163], v[160:161]
	v_pk_fma_f32 v[94:95], v[68:69], v[98:99], v[94:95]
	v_pk_fma_f32 v[98:99], v[70:71], v[166:167], v[164:165]
	v_pk_fma_f32 v[100:101], v[72:73], v[104:105], v[100:101]
	v_pk_fma_f32 v[104:105], v[66:67], v[170:171], v[168:169]
	v_pk_fma_f32 v[102:103], v[68:69], v[106:107], v[102:103]
	v_pk_fma_f32 v[106:107], v[70:71], v[174:175], v[172:173]
	v_pk_fma_f32 v[108:109], v[72:73], v[112:113], v[108:109]
	v_pk_fma_f32 v[112:113], v[66:67], v[188:189], v[176:177]
	v_pk_fma_f32 v[110:111], v[68:69], v[114:115], v[110:111]
	v_pk_fma_f32 v[114:115], v[70:71], v[194:195], v[190:191]
	v_pk_fma_f32 v[116:117], v[72:73], v[120:121], v[116:117]
	v_pk_fma_f32 v[120:121], v[66:67], v[198:199], v[196:197]
	v_pk_fma_f32 v[118:119], v[68:69], v[122:123], v[118:119]
	v_cvt_pk_bf16_f32 v66, v156, v157
	v_cvt_pk_bf16_f32 v67, v92, v93
	v_cvt_pk_bf16_f32 v68, v96, v97
	v_cvt_pk_bf16_f32 v69, v94, v95
	v_cvt_pk_bf16_f32 v70, v98, v99
	v_cvt_pk_bf16_f32 v71, v100, v101
	v_cvt_pk_bf16_f32 v72, v104, v105
	v_cvt_pk_bf16_f32 v73, v102, v103
	v_cvt_pk_bf16_f32 v92, v106, v107
	v_cvt_pk_bf16_f32 v93, v108, v109
	v_cvt_pk_bf16_f32 v94, v112, v113
	v_cvt_pk_bf16_f32 v95, v110, v111
	v_cvt_pk_bf16_f32 v96, v114, v115
	v_cvt_pk_bf16_f32 v97, v116, v117
	v_cvt_pk_bf16_f32 v98, v120, v121
	v_cvt_pk_bf16_f32 v99, v118, v119
	s_setprio 1
	s_waitcnt lgkmcnt(3)
	v_mfma_f32_16x16x32_bf16 v[62:65], v[124:127], v[140:143], v[62:65]
	v_mfma_f32_16x16x32_bf16 v[58:61], v[128:131], v[140:143], v[58:61]
	v_mfma_f32_16x16x32_bf16 v[54:57], v[132:135], v[140:143], v[54:57]
	v_mfma_f32_16x16x32_bf16 v[50:53], v[136:139], v[140:143], v[50:53]
	s_waitcnt lgkmcnt(2)
	v_mfma_f32_16x16x32_bf16 v[46:49], v[124:127], v[144:147], v[46:49]
	v_mfma_f32_16x16x32_bf16 v[42:45], v[128:131], v[144:147], v[42:45]
	v_mfma_f32_16x16x32_bf16 v[38:41], v[132:135], v[144:147], v[38:41]
	v_mfma_f32_16x16x32_bf16 v[34:37], v[136:139], v[144:147], v[34:37]
	s_waitcnt lgkmcnt(1)
	v_mfma_f32_16x16x32_bf16 v[30:33], v[124:127], v[148:151], v[30:33]
	v_mfma_f32_16x16x32_bf16 v[26:29], v[128:131], v[148:151], v[26:29]
	v_mfma_f32_16x16x32_bf16 v[22:25], v[132:135], v[148:151], v[22:25]
	v_mfma_f32_16x16x32_bf16 v[18:21], v[136:139], v[148:151], v[18:21]
	s_waitcnt lgkmcnt(0)
	v_mfma_f32_16x16x32_bf16 v[10:13], v[124:127], v[152:155], v[10:13]
	v_mfma_f32_16x16x32_bf16 v[2:5], v[128:131], v[152:155], v[2:5]
	v_mfma_f32_16x16x32_bf16 v[14:17], v[132:135], v[152:155], v[14:17]
	v_mfma_f32_16x16x32_bf16 v[6:9], v[136:139], v[152:155], v[6:9]
	s_setprio 0
	s_lshl_b32 s14, s6, 8
	s_xor_b32 s14, s14, 0x100
	s_mulk_i32 s14, 0x90
	v_add_u32_e32 v100, s14, v193
	ds_write_b128 v100, v[66:69]
	ds_write_b128 v100, v[70:73] offset:9216
	ds_write_b128 v100, v[92:95] offset:18432
	ds_write_b128 v100, v[96:99] offset:27648
	ds_read_b128 v[66:69], v192 offset:64
	ds_read_b128 v[70:73], v192 offset:2368
	ds_read_b128 v[92:95], v91 offset:64
	ds_read_b128 v[96:99], v91 offset:2368
	ds_read_b128 v[100:103], v192 offset:4672
	ds_read_b128 v[104:107], v192 offset:6976
	s_lshl_b32 s6, s6, 7
	s_waitcnt lgkmcnt(3)
	v_mfma_f32_16x16x32_bf16 v[62:65], v[66:69], v[92:95], v[62:65]
	s_xor_b32 s6, s6, 0x80
	s_mulk_i32 s6, 0x90
	v_mfma_f32_16x16x32_bf16 v[58:61], v[70:73], v[92:95], v[58:61]
	s_waitcnt lgkmcnt(1)
	v_mfma_f32_16x16x32_bf16 v[54:57], v[100:103], v[92:95], v[54:57]
	s_waitcnt lgkmcnt(0)
	v_mfma_f32_16x16x32_bf16 v[50:53], v[104:107], v[92:95], v[50:53]
	v_mfma_f32_16x16x32_bf16 v[46:49], v[66:69], v[96:99], v[46:49]
	v_mfma_f32_16x16x32_bf16 v[42:45], v[70:73], v[96:99], v[42:45]
	v_mfma_f32_16x16x32_bf16 v[38:41], v[100:103], v[96:99], v[38:41]
	v_mfma_f32_16x16x32_bf16 v[34:37], v[104:107], v[96:99], v[34:37]
	ds_read_b128 v[92:95], v91 offset:4672
	ds_read_b128 v[96:99], v91 offset:6976
	v_add_u32_e32 v91, s6, v210
	s_waitcnt lgkmcnt(1)
	v_mfma_f32_16x16x32_bf16 v[30:33], v[66:69], v[92:95], v[30:33]
	s_waitcnt lgkmcnt(0)
	v_mfma_f32_16x16x32_bf16 v[10:13], v[66:69], v[96:99], v[10:13]
	v_lshl_add_u64 v[66:67], v[82:83], 0, s[0:1]
	v_mfma_f32_16x16x32_bf16 v[26:29], v[70:73], v[92:95], v[26:29]
	v_mfma_f32_16x16x32_bf16 v[2:5], v[70:73], v[96:99], v[2:5]
	v_add_co_u32_e32 v70, vcc, s36, v66
	s_nop 1
	v_addc_co_u32_e32 v71, vcc, 0, v67, vcc
	global_load_dwordx4 v[66:69], v[66:67], off offset:128
	s_nop 0
	global_load_dwordx4 v[70:73], v[70:71], off offset:128
	v_mfma_f32_16x16x32_bf16 v[22:25], v[100:103], v[92:95], v[22:25]
	v_mfma_f32_16x16x32_bf16 v[18:21], v[104:107], v[92:95], v[18:21]
	v_mfma_f32_16x16x32_bf16 v[14:17], v[100:103], v[96:99], v[14:17]
	v_mfma_f32_16x16x32_bf16 v[6:9], v[104:107], v[96:99], v[6:9]
	s_setprio 1
	s_setprio 0
	s_add_u32 s0, s0, 0x80
	s_addc_u32 s1, s1, 0
	s_cmpk_lg_i32 s0, 0x780
	v_lshl_add_u64 v[86:87], v[86:87], 0, s[8:9]
	s_waitcnt vmcnt(1)
	ds_write_b128 v91, v[66:69]
	s_waitcnt vmcnt(0)
	ds_write_b128 v91, v[70:73] offset:9216
	s_waitcnt lgkmcnt(0)
	s_barrier
	s_cbranch_scc1 .LBB0_553
	s_setprio 0
	ds_read_b128 v[66:69], v88 offset:43776
	ds_read_b128 v[70:73], v88 offset:41472
	ds_read_b128 v[82:85], v88 offset:39168
	ds_read_b128 v[92:95], v88 offset:36864
	ds_read_b128 v[96:99], v89 offset:25344
	ds_read_b128 v[100:103], v89 offset:23040
	ds_read_b128 v[104:107], v89 offset:20736
	ds_read_b128 v[108:111], v89 offset:18432
	s_setprio 1
	s_waitcnt lgkmcnt(0)
	v_mfma_f32_16x16x32_bf16 v[62:65], v[108:111], v[92:95], v[62:65]
	v_mfma_f32_16x16x32_bf16 v[58:61], v[104:107], v[92:95], v[58:61]
	v_mfma_f32_16x16x32_bf16 v[54:57], v[100:103], v[92:95], v[54:57]
	v_mfma_f32_16x16x32_bf16 v[50:53], v[96:99], v[92:95], v[50:53]
	v_mfma_f32_16x16x32_bf16 v[46:49], v[108:111], v[82:85], v[46:49]
	v_mfma_f32_16x16x32_bf16 v[42:45], v[104:107], v[82:85], v[42:45]
	v_mfma_f32_16x16x32_bf16 v[38:41], v[100:103], v[82:85], v[38:41]
	v_mfma_f32_16x16x32_bf16 v[34:37], v[96:99], v[82:85], v[34:37]
	v_mfma_f32_16x16x32_bf16 v[30:33], v[108:111], v[70:73], v[30:33]
	v_mfma_f32_16x16x32_bf16 v[26:29], v[104:107], v[70:73], v[26:29]
	v_mfma_f32_16x16x32_bf16 v[22:25], v[100:103], v[70:73], v[22:25]
	v_mfma_f32_16x16x32_bf16 v[18:21], v[96:99], v[70:73], v[18:21]
	v_mfma_f32_16x16x32_bf16 v[10:13], v[108:111], v[66:69], v[10:13]
	v_mfma_f32_16x16x32_bf16 v[2:5], v[104:107], v[66:69], v[2:5]
	v_mfma_f32_16x16x32_bf16 v[70:73], v[100:103], v[66:69], v[14:17]
	v_mfma_f32_16x16x32_bf16 v[66:69], v[96:99], v[66:69], v[6:9]
	s_setprio 0
	ds_read_b128 v[82:85], v88 offset:43840
	s_nop 0
	ds_read_b128 v[6:9], v88 offset:41536
	ds_read_b128 v[14:17], v88 offset:39232
	ds_read_b128 v[92:95], v88 offset:36928
	ds_read_b128 v[96:99], v89 offset:18496
	ds_read_b128 v[100:103], v89 offset:20800
	ds_read_b128 v[104:107], v89 offset:23104
	ds_read_b128 v[108:111], v89 offset:25408
	s_setprio 1
	s_waitcnt lgkmcnt(3)
	v_mfma_f32_16x16x32_bf16 v[62:65], v[96:99], v[92:95], v[62:65]
	s_waitcnt lgkmcnt(2)
	v_mfma_f32_16x16x32_bf16 v[58:61], v[100:103], v[92:95], v[58:61]
	s_waitcnt lgkmcnt(1)
	v_mfma_f32_16x16x32_bf16 v[54:57], v[104:107], v[92:95], v[54:57]
	s_waitcnt lgkmcnt(0)
	v_mfma_f32_16x16x32_bf16 v[50:53], v[108:111], v[92:95], v[50:53]
	v_mfma_f32_16x16x32_bf16 v[46:49], v[96:99], v[14:17], v[46:49]
	v_mfma_f32_16x16x32_bf16 v[42:45], v[100:103], v[14:17], v[42:45]
	v_mfma_f32_16x16x32_bf16 v[38:41], v[104:107], v[14:17], v[38:41]
	v_mfma_f32_16x16x32_bf16 v[34:37], v[108:111], v[14:17], v[34:37]
	v_mfma_f32_16x16x32_bf16 v[30:33], v[96:99], v[6:9], v[30:33]
	v_mfma_f32_16x16x32_bf16 v[26:29], v[100:103], v[6:9], v[26:29]
	v_mfma_f32_16x16x32_bf16 v[22:25], v[104:107], v[6:9], v[22:25]
	v_mfma_f32_16x16x32_bf16 v[18:21], v[108:111], v[6:9], v[18:21]
	v_mfma_f32_16x16x32_bf16 v[14:17], v[96:99], v[82:85], v[10:13]
	v_mfma_f32_16x16x32_bf16 v[10:13], v[100:103], v[82:85], v[2:5]
	v_mfma_f32_16x16x32_bf16 v[6:9], v[104:107], v[82:85], v[70:73]
	v_mfma_f32_16x16x32_bf16 v[2:5], v[108:111], v[82:85], v[66:69]
	s_setprio 0
	s_nop 1
	v_add_u32_e32 v66, s49, v90
	v_ashrrev_i32_e32 v67, 31, v66
	v_lshlrev_b64 v[68:69], 8, v[66:67]
	s_mov_b64 s[0:1], -1
	s_and_b64 vcc, exec, s[12:13]
	s_barrier
	s_cbranch_vccz .LBB0_560
	s_and_b64 vcc, exec, s[10:11]
	s_cbranch_vccz .LBB0_557
	v_mul_f32_e32 v67, 0xbfb8aa3b, v62
	v_mul_f32_e32 v70, 0xbfb8aa3b, v63
	v_exp_f32_e32 v67, v67
	v_exp_f32_e32 v72, v70
	v_mul_f32_e32 v73, 0xbfb8aa3b, v64
	v_mul_f32_e32 v82, 0xbfb8aa3b, v65
	v_add_f32_e32 v67, 1.0, v67
	v_add_f32_e32 v72, 1.0, v72
	v_mul_f32_e32 v83, 0xbfb8aa3b, v58
	v_mul_f32_e32 v84, 0xbfb8aa3b, v59
	v_rcp_f32_e32 v67, v67
	v_exp_f32_e32 v73, v73
	v_exp_f32_e32 v82, v82
	v_rcp_f32_e32 v72, v72
	v_exp_f32_e32 v83, v83
	v_exp_f32_e32 v84, v84
	v_add_f32_e32 v73, 1.0, v73
	v_add_f32_e32 v82, 1.0, v82
	v_cvt_pk_bf16_f32 v72, v67, v72
	v_add_f32_e32 v67, 1.0, v83
	v_add_f32_e32 v83, 1.0, v84
	v_mul_f32_e32 v84, 0xbfb8aa3b, v60
	v_mul_f32_e32 v85, 0xbfb8aa3b, v61
	v_rcp_f32_e32 v73, v73
	v_rcp_f32_e32 v82, v82
	v_exp_f32_e32 v84, v84
	v_exp_f32_e32 v85, v85
	v_rcp_f32_e32 v67, v67
	v_rcp_f32_e32 v83, v83
	v_lshl_add_u64 v[70:71], v[76:77], 0, v[68:69]
	v_add_f32_e32 v84, 1.0, v84
	v_add_f32_e32 v85, 1.0, v85
	v_cvt_pk_bf16_f32 v73, v73, v82
	v_rcp_f32_e32 v84, v84
	v_rcp_f32_e32 v85, v85
	global_store_dwordx2 v[70:71], v[72:73], off
	v_cvt_pk_bf16_f32 v72, v67, v83
	v_mul_f32_e32 v67, 0xbfb8aa3b, v54
	v_mul_f32_e32 v82, 0xbfb8aa3b, v55
	v_exp_f32_e32 v67, v67
	v_exp_f32_e32 v82, v82
	v_cvt_pk_bf16_f32 v73, v84, v85
	global_store_dwordx2 v[70:71], v[72:73], off offset:32
	v_add_f32_e32 v67, 1.0, v67
	v_add_f32_e32 v72, 1.0, v82
	v_mul_f32_e32 v83, 0xbfb8aa3b, v50
	v_mul_f32_e32 v84, 0xbfb8aa3b, v51
	v_rcp_f32_e32 v67, v67
	v_rcp_f32_e32 v72, v72
	v_exp_f32_e32 v83, v83
	v_exp_f32_e32 v84, v84
	v_mul_f32_e32 v73, 0xbfb8aa3b, v56
	v_mul_f32_e32 v82, 0xbfb8aa3b, v57
	v_exp_f32_e32 v73, v73
	v_exp_f32_e32 v82, v82
	v_cvt_pk_bf16_f32 v72, v67, v72
	v_add_f32_e32 v67, 1.0, v83
	v_add_f32_e32 v83, 1.0, v84
	v_mul_f32_e32 v84, 0xbfb8aa3b, v52
	v_mul_f32_e32 v85, 0xbfb8aa3b, v53
	v_exp_f32_e32 v84, v84
	v_exp_f32_e32 v85, v85
	v_add_f32_e32 v73, 1.0, v73
	v_add_f32_e32 v82, 1.0, v82
	v_rcp_f32_e32 v73, v73
	v_rcp_f32_e32 v82, v82
	v_add_f32_e32 v84, 1.0, v84
	v_add_f32_e32 v85, 1.0, v85
	v_rcp_f32_e32 v67, v67
	v_rcp_f32_e32 v83, v83
	v_rcp_f32_e32 v84, v84
	v_rcp_f32_e32 v85, v85
	v_cvt_pk_bf16_f32 v73, v73, v82
	global_store_dwordx2 v[70:71], v[72:73], off offset:64
	v_cvt_pk_bf16_f32 v72, v67, v83
	v_cvt_pk_bf16_f32 v73, v84, v85
	global_store_dwordx2 v[70:71], v[72:73], off offset:96
	v_mul_f32_e32 v67, 0xbfb8aa3b, v46
	v_mul_f32_e32 v72, 0xbfb8aa3b, v47
	v_exp_f32_e32 v67, v67
	v_exp_f32_e32 v72, v72
	v_mul_f32_e32 v73, 0xbfb8aa3b, v48
	v_mul_f32_e32 v82, 0xbfb8aa3b, v49
	v_add_f32_e32 v67, 1.0, v67
	v_add_f32_e32 v72, 1.0, v72
	v_mul_f32_e32 v83, 0xbfb8aa3b, v42
	v_mul_f32_e32 v84, 0xbfb8aa3b, v43
	v_rcp_f32_e32 v67, v67
	v_exp_f32_e32 v73, v73
	v_exp_f32_e32 v82, v82
	v_rcp_f32_e32 v72, v72
	v_exp_f32_e32 v83, v83
	v_exp_f32_e32 v84, v84
	v_add_f32_e32 v73, 1.0, v73
	v_add_f32_e32 v82, 1.0, v82
	v_cvt_pk_bf16_f32 v72, v67, v72
	v_add_f32_e32 v67, 1.0, v83
	v_add_f32_e32 v83, 1.0, v84
	v_mul_f32_e32 v84, 0xbfb8aa3b, v44
	v_mul_f32_e32 v85, 0xbfb8aa3b, v45
	v_rcp_f32_e32 v73, v73
	v_rcp_f32_e32 v82, v82
	v_exp_f32_e32 v84, v84
	v_exp_f32_e32 v85, v85
	v_or_b32_e32 v70, 16, v66
	v_rcp_f32_e32 v67, v67
	v_rcp_f32_e32 v83, v83
	v_ashrrev_i32_e32 v71, 31, v70
	v_lshlrev_b64 v[70:71], 8, v[70:71]
	v_lshl_add_u64 v[70:71], v[76:77], 0, v[70:71]
	v_add_f32_e32 v84, 1.0, v84
	v_add_f32_e32 v85, 1.0, v85
	v_cvt_pk_bf16_f32 v73, v73, v82
	v_rcp_f32_e32 v84, v84
	v_rcp_f32_e32 v85, v85
	global_store_dwordx2 v[70:71], v[72:73], off
	v_cvt_pk_bf16_f32 v72, v67, v83
	v_mul_f32_e32 v67, 0xbfb8aa3b, v38
	v_mul_f32_e32 v82, 0xbfb8aa3b, v39
	v_exp_f32_e32 v67, v67
	v_exp_f32_e32 v82, v82
	v_cvt_pk_bf16_f32 v73, v84, v85
	global_store_dwordx2 v[70:71], v[72:73], off offset:32
	v_add_f32_e32 v67, 1.0, v67
	v_add_f32_e32 v72, 1.0, v82
	v_mul_f32_e32 v83, 0xbfb8aa3b, v34
	v_mul_f32_e32 v84, 0xbfb8aa3b, v35
	v_rcp_f32_e32 v67, v67
	v_rcp_f32_e32 v72, v72
	v_exp_f32_e32 v83, v83
	v_exp_f32_e32 v84, v84
	v_mul_f32_e32 v73, 0xbfb8aa3b, v40
	v_mul_f32_e32 v82, 0xbfb8aa3b, v41
	v_exp_f32_e32 v73, v73
	v_exp_f32_e32 v82, v82
	v_cvt_pk_bf16_f32 v72, v67, v72
	v_add_f32_e32 v67, 1.0, v83
	v_add_f32_e32 v83, 1.0, v84
	v_mul_f32_e32 v84, 0xbfb8aa3b, v36
	v_mul_f32_e32 v85, 0xbfb8aa3b, v37
	v_exp_f32_e32 v84, v84
	v_exp_f32_e32 v85, v85
	v_add_f32_e32 v73, 1.0, v73
	v_add_f32_e32 v82, 1.0, v82
	v_rcp_f32_e32 v73, v73
	v_rcp_f32_e32 v82, v82
	v_add_f32_e32 v84, 1.0, v84
	v_add_f32_e32 v85, 1.0, v85
	v_rcp_f32_e32 v67, v67
	v_rcp_f32_e32 v83, v83
	v_rcp_f32_e32 v84, v84
	v_rcp_f32_e32 v85, v85
	v_cvt_pk_bf16_f32 v73, v73, v82
	global_store_dwordx2 v[70:71], v[72:73], off offset:64
	v_cvt_pk_bf16_f32 v72, v67, v83
	v_cvt_pk_bf16_f32 v73, v84, v85
	global_store_dwordx2 v[70:71], v[72:73], off offset:96
	v_mul_f32_e32 v67, 0xbfb8aa3b, v30
	v_mul_f32_e32 v72, 0xbfb8aa3b, v31
	v_exp_f32_e32 v67, v67
	v_exp_f32_e32 v72, v72
	v_mul_f32_e32 v73, 0xbfb8aa3b, v32
	v_mul_f32_e32 v82, 0xbfb8aa3b, v33
	v_add_f32_e32 v67, 1.0, v67
	v_add_f32_e32 v72, 1.0, v72
	v_mul_f32_e32 v83, 0xbfb8aa3b, v26
	v_mul_f32_e32 v84, 0xbfb8aa3b, v27
	v_rcp_f32_e32 v67, v67
	v_exp_f32_e32 v73, v73
	v_exp_f32_e32 v82, v82
	v_rcp_f32_e32 v72, v72
	v_exp_f32_e32 v83, v83
	v_exp_f32_e32 v84, v84
	v_add_f32_e32 v73, 1.0, v73
	v_add_f32_e32 v82, 1.0, v82
	v_cvt_pk_bf16_f32 v72, v67, v72
	v_add_f32_e32 v67, 1.0, v83
	v_add_f32_e32 v83, 1.0, v84
	v_mul_f32_e32 v84, 0xbfb8aa3b, v28
	v_mul_f32_e32 v85, 0xbfb8aa3b, v29
	v_rcp_f32_e32 v73, v73
	v_rcp_f32_e32 v82, v82
	v_exp_f32_e32 v84, v84
	v_exp_f32_e32 v85, v85
	v_or_b32_e32 v70, 32, v66
	v_rcp_f32_e32 v67, v67
	v_rcp_f32_e32 v83, v83
	v_ashrrev_i32_e32 v71, 31, v70
	v_lshlrev_b64 v[70:71], 8, v[70:71]
	v_lshl_add_u64 v[70:71], v[76:77], 0, v[70:71]
	v_add_f32_e32 v84, 1.0, v84
	v_add_f32_e32 v85, 1.0, v85
	v_cvt_pk_bf16_f32 v73, v73, v82
	v_rcp_f32_e32 v84, v84
	v_rcp_f32_e32 v85, v85
	global_store_dwordx2 v[70:71], v[72:73], off
	v_cvt_pk_bf16_f32 v72, v67, v83
	v_mul_f32_e32 v67, 0xbfb8aa3b, v22
	v_mul_f32_e32 v82, 0xbfb8aa3b, v23
	v_exp_f32_e32 v67, v67
	v_exp_f32_e32 v82, v82
	v_cvt_pk_bf16_f32 v73, v84, v85
	global_store_dwordx2 v[70:71], v[72:73], off offset:32
	v_add_f32_e32 v67, 1.0, v67
	v_add_f32_e32 v72, 1.0, v82
	v_mul_f32_e32 v83, 0xbfb8aa3b, v18
	v_mul_f32_e32 v84, 0xbfb8aa3b, v19
	v_rcp_f32_e32 v67, v67
	v_rcp_f32_e32 v72, v72
	v_exp_f32_e32 v83, v83
	v_exp_f32_e32 v84, v84
	v_mul_f32_e32 v73, 0xbfb8aa3b, v24
	v_mul_f32_e32 v82, 0xbfb8aa3b, v25
	v_exp_f32_e32 v73, v73
	v_exp_f32_e32 v82, v82
	v_cvt_pk_bf16_f32 v72, v67, v72
	v_add_f32_e32 v67, 1.0, v83
	v_add_f32_e32 v83, 1.0, v84
	v_mul_f32_e32 v84, 0xbfb8aa3b, v20
	v_mul_f32_e32 v85, 0xbfb8aa3b, v21
	v_exp_f32_e32 v84, v84
	v_exp_f32_e32 v85, v85
	v_add_f32_e32 v73, 1.0, v73
	v_add_f32_e32 v82, 1.0, v82
	v_rcp_f32_e32 v73, v73
	v_rcp_f32_e32 v82, v82
	v_add_f32_e32 v84, 1.0, v84
	v_add_f32_e32 v85, 1.0, v85
	v_rcp_f32_e32 v67, v67
	v_rcp_f32_e32 v83, v83
	v_rcp_f32_e32 v84, v84
	v_rcp_f32_e32 v85, v85
	v_cvt_pk_bf16_f32 v73, v73, v82
	global_store_dwordx2 v[70:71], v[72:73], off offset:64
	v_cvt_pk_bf16_f32 v72, v67, v83
	v_cvt_pk_bf16_f32 v73, v84, v85
	global_store_dwordx2 v[70:71], v[72:73], off offset:96
	v_mul_f32_e32 v73, 0xbfb8aa3b, v16
	v_mul_f32_e32 v82, 0xbfb8aa3b, v17
	v_mul_f32_e32 v67, 0xbfb8aa3b, v14
	v_mul_f32_e32 v71, 0xbfb8aa3b, v15
	v_exp_f32_e32 v73, v73
	v_exp_f32_e32 v82, v82
	v_exp_f32_e32 v67, v67
	v_exp_f32_e32 v72, v71
	v_add_f32_e32 v73, 1.0, v73
	v_add_f32_e32 v82, 1.0, v82
	v_add_f32_e32 v67, 1.0, v67
	v_add_f32_e32 v72, 1.0, v72
	v_rcp_f32_e32 v73, v73
	v_rcp_f32_e32 v82, v82
	v_rcp_f32_e32 v67, v67
	v_rcp_f32_e32 v72, v72
	v_or_b32_e32 v70, 48, v66
	v_cvt_pk_bf16_f32 v73, v73, v82
	v_mul_f32_e32 v82, 0xbfb8aa3b, v11
	v_cvt_pk_bf16_f32 v72, v67, v72
	v_mul_f32_e32 v67, 0xbfb8aa3b, v10
	v_exp_f32_e32 v82, v82
	v_ashrrev_i32_e32 v71, 31, v70
	v_exp_f32_e32 v67, v67
	v_lshlrev_b64 v[70:71], 8, v[70:71]
	v_lshl_add_u64 v[70:71], v[76:77], 0, v[70:71]
	global_store_dwordx2 v[70:71], v[72:73], off
	v_add_f32_e32 v72, 1.0, v82
	v_mul_f32_e32 v73, 0xbfb8aa3b, v12
	v_mul_f32_e32 v82, 0xbfb8aa3b, v13
	v_add_f32_e32 v67, 1.0, v67
	v_exp_f32_e32 v73, v73
	v_exp_f32_e32 v82, v82
	v_mul_f32_e32 v83, 0xbfb8aa3b, v6
	v_mul_f32_e32 v84, 0xbfb8aa3b, v7
	v_rcp_f32_e32 v67, v67
	v_rcp_f32_e32 v72, v72
	v_exp_f32_e32 v83, v83
	v_exp_f32_e32 v84, v84
	v_add_f32_e32 v73, 1.0, v73
	v_add_f32_e32 v82, 1.0, v82
	v_rcp_f32_e32 v73, v73
	v_rcp_f32_e32 v82, v82
	v_cvt_pk_bf16_f32 v72, v67, v72
	v_add_f32_e32 v67, 1.0, v83
	v_add_f32_e32 v83, 1.0, v84
	v_mul_f32_e32 v84, 0xbfb8aa3b, v8
	v_mul_f32_e32 v85, 0xbfb8aa3b, v9
	v_rcp_f32_e32 v67, v67
	v_exp_f32_e32 v84, v84
	v_exp_f32_e32 v85, v85
	v_rcp_f32_e32 v83, v83
	v_cvt_pk_bf16_f32 v73, v73, v82
	v_add_f32_e32 v84, 1.0, v84
	v_add_f32_e32 v85, 1.0, v85
	global_store_dwordx2 v[70:71], v[72:73], off offset:32
	v_cvt_pk_bf16_f32 v72, v67, v83
	v_mul_f32_e32 v67, 0xbfb8aa3b, v2
	v_rcp_f32_e32 v84, v84
	v_rcp_f32_e32 v85, v85
	v_exp_f32_e32 v67, v67
	v_mul_f32_e32 v82, 0xbfb8aa3b, v3
	v_exp_f32_e32 v82, v82
	v_cvt_pk_bf16_f32 v73, v84, v85
	v_add_f32_e32 v67, 1.0, v67
	global_store_dwordx2 v[70:71], v[72:73], off offset:64
	v_rcp_f32_e32 v73, v67
	v_add_f32_e32 v67, 1.0, v82
	v_mul_f32_e32 v72, 0xbfb8aa3b, v4
	v_mul_f32_e32 v82, 0xbfb8aa3b, v5
	v_exp_f32_e32 v72, v72
	v_exp_f32_e32 v82, v82
	v_rcp_f32_e32 v83, v67
	s_mov_b64 s[0:1], 0
	v_add_f32_e32 v67, 1.0, v72
	v_add_f32_e32 v72, 1.0, v82
	v_cvt_pk_bf16_f32 v73, v73, v83
	v_rcp_f32_e32 v67, v67
	v_rcp_f32_e32 v72, v72
	global_store_dword v[70:71], v73, off offset:96

.LBB0_621:
	v_mov_b32_e32 v3, v2
	s_cmpk_gt_u32 s2, 0x7ff
	s_cbranch_scc1 .LBB0_624
	v_lshlrev_b32_e32 v4, 4, v2
	v_and_b32_e32 v4, 0x70, v4
	v_mov_b32_e32 v5, 0
	v_lshl_add_u64 v[6:7], s[86:87], 0, v[4:5]
	s_mov_b64 s[4:5], 0x2f950000
	v_lshl_add_u64 v[98:99], v[6:7], 0, s[4:5]
	s_mov_b64 s[4:5], 0x2d40000
	v_and_b32_e32 v8, 15, v2
	v_lshrrev_b32_e32 v1, 3, v2
	v_lshl_add_u64 v[100:101], v[6:7], 0, s[4:5]
	v_lshrrev_b32_e32 v7, 1, v2
	s_movk_i32 s5, 0x1c0
	v_mul_u32_u24_e32 v6, 0x48, v1
	v_and_or_b32 v7, v7, s5, v8
	v_and_b32_e32 v8, 48, v2
	v_and_b32_e32 v2, 0x4f, v2
	v_lshlrev_b32_e32 v6, 1, v6
	s_add_i32 s4, 0, 0x12000
	v_mul_u32_u24_e32 v2, 0x90, v2
	v_add3_u32 v141, s4, v6, v4
	v_add3_u32 v143, s4, v2, v8
	s_add_i32 s4, 0, 0x16800
	s_lshr_b32 s3, s2, 3
	s_waitcnt lgkmcnt(0)
	s_and_b32 s16, s2, 7
	v_add3_u32 v140, 0, v6, v4
	v_add3_u32 v144, s4, v6, v4
	v_lshrrev_b32_e32 v4, 2, v3
	s_add_u32 s4, s86, 0x4450000
	v_and_b32_e32 v146, 12, v4
	v_mbcnt_lo_u32_b32 v4, -1, 0
	v_mul_u32_u24_e32 v7, 0x90, v7
	s_addc_u32 s5, s87, 0
	v_mbcnt_hi_u32_b32 v4, -1, v4
	v_add3_u32 v142, 0, v7, v8
	s_add_u32 s6, s86, 0xc850000
	v_and_b32_e32 v7, 64, v4
	s_addc_u32 s7, s87, 0
	v_xor_b32_e32 v6, 16, v4
	v_add_u32_e32 v7, 64, v7
	s_add_u32 s8, s86, 0x3410000
	v_cmp_lt_i32_e32 vcc, v6, v7
	s_addc_u32 s9, s87, 0
	v_ashrrev_i32_e32 v2, 1, v3
	v_cndmask_b32_e32 v6, v4, v6, vcc
	s_add_u32 s10, s86, 0x25450000
	v_lshlrev_b32_e32 v147, 2, v6
	v_xor_b32_e32 v6, 32, v4
	v_and_b32_e32 v2, 0xffffffc0, v2
	s_addc_u32 s11, s87, 0
	v_cmp_lt_i32_e32 vcc, v6, v7
	s_mul_i32 s17, s16, 0x2100
	s_add_u32 s12, s86, 0x14c50000
	v_cndmask_b32_e32 v4, v4, v6, vcc
	v_add_u32_e32 v2, s17, v2
	s_addc_u32 s13, s87, 0
	v_lshlrev_b32_e32 v148, 2, v4
	s_ashr_i32 s14, s33, 3
	v_lshlrev_b32_e32 v4, 2, v146
	v_and_or_b32 v149, v3, 15, v2
	v_add_u32_e32 v2, s17, v1
	v_and_b32_e32 v145, 64, v3
	v_lshl_add_u64 v[102:103], s[24:25], 0, v[4:5]
	v_lshl_add_u64 v[104:105], s[26:27], 0, v[4:5]
	s_lshl_b32 s15, s3, 8
	s_lshl_b32 s16, s14, 8
	v_add_u32_e32 v150, 0x100, v2
	s_movk_i32 s17, 0x4000
	s_mov_b32 s18, 0x8000
	s_mov_b32 s19, 0xc000
	s_mov_b32 s20, 0x3e0f83e1
	v_mov_b32_e32 v151, 0x3a27c5ac
	s_mov_b32 s21, 0x800000
	s_mov_b32 s22, 0x420000
	v_readfirstlane_b32 s97, v0
	s_bfe_u32 s97, s97, 0x40006
	s_cmp_lt_u32 s97, 4
	s_cbranch_scc1 .Lhp_p11
	s_setprio 1
.Lhp_p11:
.LBB0_623:
	s_ashr_i32 s23, s3, 31
	s_lshr_b32 s23, s23, 27
	s_add_i32 s23, s3, s23
	s_lshr_b32 s25, s23, 5
	s_andn2_b32 s23, s23, 31
	s_sub_i32 s23, s3, s23
	s_ashr_i32 s24, s23, 31
	s_lshr_b32 s24, s24, 30
	s_add_i32 s23, s23, s24
	s_ashr_i32 s26, s23, 2
	s_lshl_b32 s24, s26, 10
	s_mul_i32 s23, s25, 0x1c00
	s_add_i32 s25, s24, s23
	s_sub_i32 s27, s15, s25
	v_add_u32_e32 v2, s27, v150
	v_ashrrev_i32_e32 v3, 31, v2
	v_lshlrev_b64 v[2:3], 8, v[2:3]
	v_lshl_add_u64 v[26:27], v[98:99], 0, v[2:3]
	v_add_co_u32_e32 v28, vcc, s17, v26
	s_lshl_b32 s26, s26, 7
	s_nop 0
	v_addc_co_u32_e32 v29, vcc, 0, v27, vcc
	v_or_b32_e32 v2, s26, v1
	v_add_co_u32_e32 v30, vcc, s18, v26
	v_ashrrev_i32_e32 v3, 31, v2
	s_nop 0
	v_addc_co_u32_e32 v31, vcc, 0, v27, vcc
	v_lshlrev_b64 v[2:3], 8, v[2:3]
	v_add_co_u32_e32 v32, vcc, s19, v26
	v_lshl_add_u64 v[90:91], v[100:101], 0, v[2:3]
	s_nop 0
	v_addc_co_u32_e32 v33, vcc, 0, v27, vcc
	v_add_co_u32_e32 v92, vcc, s17, v90
	global_load_dwordx4 v[2:5], v[26:27], off
	global_load_dwordx4 v[6:9], v[28:29], off
	global_load_dwordx4 v[10:13], v[30:31], off
	global_load_dwordx4 v[14:17], v[32:33], off
	s_waitcnt vmcnt(63) expcnt(7) lgkmcnt(15)
	s_barrier
	v_addc_co_u32_e32 v93, vcc, 0, v91, vcc
	global_load_dwordx4 v[18:21], v[90:91], off
	global_load_dwordx4 v[22:25], v[92:93], off
	s_waitcnt vmcnt(5)
	ds_write_b128 v140, v[2:5]
	s_waitcnt vmcnt(4)
	ds_write_b128 v140, v[6:9] offset:9216
	s_waitcnt vmcnt(3)
	ds_write_b128 v140, v[10:13] offset:18432
	s_waitcnt vmcnt(2)
	ds_write_b128 v140, v[14:17] offset:27648
	s_waitcnt vmcnt(1)
	ds_write_b128 v141, v[18:21]
	s_waitcnt vmcnt(0)
	ds_write_b128 v141, v[22:25] offset:9216
	s_waitcnt lgkmcnt(0)
	s_barrier
	global_load_dwordx4 v[2:5], v[26:27], off offset:128
	global_load_dwordx4 v[6:9], v[28:29], off offset:128
	global_load_dwordx4 v[10:13], v[30:31], off offset:128
	global_load_dwordx4 v[14:17], v[32:33], off offset:128
	ds_read_b128 v[18:21], v143
	ds_read_b128 v[22:25], v143 offset:2304
	ds_read_b128 v[26:29], v143 offset:4608
	ds_read_b128 v[30:33], v143 offset:6912
	ds_read_b128 v[34:37], v142
	ds_read_b128 v[38:41], v142 offset:2304
	ds_read_b128 v[42:45], v142 offset:4608
	ds_read_b128 v[46:49], v142 offset:6912
	s_setprio 1
	s_waitcnt lgkmcnt(3)
	v_mfma_f32_16x16x32_bf16 v[50:53], v[18:21], v[34:37], 0
	v_mfma_f32_16x16x32_bf16 v[54:57], v[22:25], v[34:37], 0
	v_mfma_f32_16x16x32_bf16 v[58:61], v[26:29], v[34:37], 0
	v_mfma_f32_16x16x32_bf16 v[34:37], v[30:33], v[34:37], 0
	s_waitcnt lgkmcnt(2)
	v_mfma_f32_16x16x32_bf16 v[62:65], v[18:21], v[38:41], 0
	v_mfma_f32_16x16x32_bf16 v[66:69], v[22:25], v[38:41], 0
	v_mfma_f32_16x16x32_bf16 v[70:73], v[26:29], v[38:41], 0
	v_mfma_f32_16x16x32_bf16 v[38:41], v[30:33], v[38:41], 0
	s_waitcnt lgkmcnt(1)
	v_mfma_f32_16x16x32_bf16 v[74:77], v[18:21], v[42:45], 0
	v_mfma_f32_16x16x32_bf16 v[78:81], v[22:25], v[42:45], 0
	v_mfma_f32_16x16x32_bf16 v[82:85], v[26:29], v[42:45], 0
	v_mfma_f32_16x16x32_bf16 v[42:45], v[30:33], v[42:45], 0
	s_waitcnt lgkmcnt(0)
	v_mfma_f32_16x16x32_bf16 v[18:21], v[18:21], v[46:49], 0
	v_mfma_f32_16x16x32_bf16 v[22:25], v[22:25], v[46:49], 0
	v_mfma_f32_16x16x32_bf16 v[26:29], v[26:29], v[46:49], 0
	v_mfma_f32_16x16x32_bf16 v[30:33], v[30:33], v[46:49], 0
	s_setprio 0
	global_load_dwordx4 v[46:49], v[90:91], off offset:128
	global_load_dwordx4 v[86:89], v[92:93], off offset:128
	s_waitcnt vmcnt(5)
	ds_write_b128 v140, v[2:5] offset:36864
	s_waitcnt vmcnt(4)
	ds_write_b128 v140, v[6:9] offset:46080
	s_waitcnt vmcnt(3)
	ds_write_b128 v140, v[10:13] offset:55296
	s_waitcnt vmcnt(2)
	ds_write_b128 v140, v[14:17] offset:64512
	ds_read_b128 v[2:5], v143 offset:64
	ds_read_b128 v[6:9], v143 offset:2368
	ds_read_b128 v[10:13], v143 offset:4672
	ds_read_b128 v[14:17], v143 offset:6976
	ds_read_b128 v[90:93], v142 offset:64
	ds_read_b128 v[94:97], v142 offset:2368
	ds_read_b128 v[106:109], v142 offset:4672
	ds_read_b128 v[110:113], v142 offset:6976
	s_setprio 1
	s_waitcnt lgkmcnt(3)
	v_mfma_f32_16x16x32_bf16 v[50:53], v[2:5], v[90:93], v[50:53]
	v_mfma_f32_16x16x32_bf16 v[54:57], v[6:9], v[90:93], v[54:57]
	v_mfma_f32_16x16x32_bf16 v[58:61], v[10:13], v[90:93], v[58:61]
	v_mfma_f32_16x16x32_bf16 v[34:37], v[14:17], v[90:93], v[34:37]
	s_waitcnt lgkmcnt(2)
	v_mfma_f32_16x16x32_bf16 v[62:65], v[2:5], v[94:97], v[62:65]
	v_mfma_f32_16x16x32_bf16 v[66:69], v[6:9], v[94:97], v[66:69]
	v_mfma_f32_16x16x32_bf16 v[70:73], v[10:13], v[94:97], v[70:73]
	v_mfma_f32_16x16x32_bf16 v[38:41], v[14:17], v[94:97], v[38:41]
	s_waitcnt lgkmcnt(1)
	v_mfma_f32_16x16x32_bf16 v[74:77], v[2:5], v[106:109], v[74:77]
	v_mfma_f32_16x16x32_bf16 v[78:81], v[6:9], v[106:109], v[78:81]
	v_mfma_f32_16x16x32_bf16 v[82:85], v[10:13], v[106:109], v[82:85]
	v_mfma_f32_16x16x32_bf16 v[42:45], v[14:17], v[106:109], v[42:45]
	s_waitcnt lgkmcnt(0)
	v_mfma_f32_16x16x32_bf16 v[2:5], v[2:5], v[110:113], v[18:21]
	v_mfma_f32_16x16x32_bf16 v[6:9], v[6:9], v[110:113], v[22:25]
	v_mfma_f32_16x16x32_bf16 v[10:13], v[10:13], v[110:113], v[26:29]
	v_mfma_f32_16x16x32_bf16 v[14:17], v[14:17], v[110:113], v[30:33]
	s_setprio 0
	s_waitcnt vmcnt(1)
	ds_write_b128 v144, v[46:49]
	s_waitcnt vmcnt(0)
	ds_write_b128 v144, v[86:89] offset:9216
	s_waitcnt lgkmcnt(0)
	s_barrier
	ds_read_b128 v[18:21], v143 offset:18432
	ds_read_b128 v[22:25], v143 offset:20736
	ds_read_b128 v[26:29], v143 offset:23040
	ds_read_b128 v[30:33], v143 offset:25344
	ds_read_b128 v[46:49], v142 offset:36864
	ds_read_b128 v[86:89], v142 offset:39168
	ds_read_b128 v[90:93], v142 offset:41472
	ds_read_b128 v[94:97], v142 offset:43776
	s_setprio 1
	s_waitcnt lgkmcnt(3)
	v_mfma_f32_16x16x32_bf16 v[50:53], v[18:21], v[46:49], v[50:53]
	v_mfma_f32_16x16x32_bf16 v[54:57], v[22:25], v[46:49], v[54:57]
	v_mfma_f32_16x16x32_bf16 v[106:109], v[26:29], v[46:49], v[58:61]
	v_mfma_f32_16x16x32_bf16 v[34:37], v[30:33], v[46:49], v[34:37]
	s_waitcnt lgkmcnt(2)
	v_mfma_f32_16x16x32_bf16 v[46:49], v[18:21], v[86:89], v[62:65]
	v_mfma_f32_16x16x32_bf16 v[66:69], v[22:25], v[86:89], v[66:69]
	v_mfma_f32_16x16x32_bf16 v[70:73], v[26:29], v[86:89], v[70:73]
	v_mfma_f32_16x16x32_bf16 v[86:89], v[30:33], v[86:89], v[38:41]
	s_waitcnt lgkmcnt(1)
	v_mfma_f32_16x16x32_bf16 v[74:77], v[18:21], v[90:93], v[74:77]
	v_mfma_f32_16x16x32_bf16 v[78:81], v[22:25], v[90:93], v[78:81]
	v_mfma_f32_16x16x32_bf16 v[82:85], v[26:29], v[90:93], v[82:85]
	v_mfma_f32_16x16x32_bf16 v[90:93], v[30:33], v[90:93], v[42:45]
	s_waitcnt lgkmcnt(0)
	v_mfma_f32_16x16x32_bf16 v[2:5], v[18:21], v[94:97], v[2:5]
	v_mfma_f32_16x16x32_bf16 v[6:9], v[22:25], v[94:97], v[6:9]
	v_mfma_f32_16x16x32_bf16 v[110:113], v[26:29], v[94:97], v[10:13]
	v_mfma_f32_16x16x32_bf16 v[94:97], v[30:33], v[94:97], v[14:17]
	s_setprio 0
	ds_read_b128 v[114:117], v142 offset:43840
	ds_read_b128 v[10:13], v142 offset:41536
	ds_read_b128 v[14:17], v142 offset:39232
	ds_read_b128 v[18:21], v142 offset:36928
	ds_read_b128 v[118:121], v143 offset:18496
	ds_read_b128 v[122:125], v143 offset:20800
	ds_read_b128 v[126:129], v143 offset:23104
	ds_read_b128 v[130:133], v143 offset:25408
	s_setprio 1
	s_waitcnt lgkmcnt(3)
	v_mfma_f32_16x16x32_bf16 v[62:65], v[118:121], v[18:21], v[50:53]
	s_waitcnt lgkmcnt(2)
	v_mfma_f32_16x16x32_bf16 v[58:61], v[122:125], v[18:21], v[54:57]
	s_waitcnt lgkmcnt(1)
	v_mfma_f32_16x16x32_bf16 v[54:57], v[126:129], v[18:21], v[106:109]
	s_waitcnt lgkmcnt(0)
	v_mfma_f32_16x16x32_bf16 v[50:53], v[130:133], v[18:21], v[34:37]
	v_mfma_f32_16x16x32_bf16 v[46:49], v[118:121], v[14:17], v[46:49]
	v_mfma_f32_16x16x32_bf16 v[42:45], v[122:125], v[14:17], v[66:69]
	v_mfma_f32_16x16x32_bf16 v[38:41], v[126:129], v[14:17], v[70:73]
	v_mfma_f32_16x16x32_bf16 v[34:37], v[130:133], v[14:17], v[86:89]
	v_mfma_f32_16x16x32_bf16 v[30:33], v[118:121], v[10:13], v[74:77]
	v_mfma_f32_16x16x32_bf16 v[26:29], v[122:125], v[10:13], v[78:81]
	v_mfma_f32_16x16x32_bf16 v[22:25], v[126:129], v[10:13], v[82:85]
	v_mfma_f32_16x16x32_bf16 v[18:21], v[130:133], v[10:13], v[90:93]
	v_mfma_f32_16x16x32_bf16 v[14:17], v[118:121], v[114:117], v[2:5]
	v_mfma_f32_16x16x32_bf16 v[10:13], v[122:125], v[114:117], v[6:9]
	v_mfma_f32_16x16x32_bf16 v[6:9], v[126:129], v[114:117], v[110:113]
	v_mfma_f32_16x16x32_bf16 v[2:5], v[130:133], v[114:117], v[94:97]
	s_setprio 0
	v_add_u32_e32 v116, s15, v149
	v_subrev_u32_e32 v72, s25, v116
	v_or_b32_e32 v66, s26, v145
	v_add_u32_e32 v106, 0x100, v72
	v_ashrrev_i32_e32 v68, 6, v66
	v_add_u32_e32 v108, 0x110, v72
	v_add_u32_e32 v110, 0x120, v72
	v_add_u32_e32 v112, 0x130, v72
	v_mul_hi_i32 v117, v106, s20
	v_ashrrev_i32_e32 v107, 31, v106
	v_ashrrev_i32_e32 v67, 31, v66
	v_ashrrev_i32_e32 v69, 31, v68
	v_mul_hi_i32 v120, v108, s20
	v_mul_hi_i32 v122, v110, s20
	v_mul_hi_i32 v124, v112, s20
	v_lshrrev_b32_e32 v126, 31, v117
	v_ashrrev_i32_e32 v117, 11, v117
	v_lshlrev_b64 v[118:119], 6, v[106:107]
	v_or_b32_e32 v70, v66, v146
	v_lshlrev_b64 v[66:67], 2, v[66:67]
	v_lshlrev_b64 v[114:115], 2, v[68:69]
	v_lshrrev_b32_e32 v127, 31, v120
	v_ashrrev_i32_e32 v130, 11, v120
	v_lshrrev_b32_e32 v131, 31, v122
	v_ashrrev_i32_e32 v134, 11, v122
	v_lshrrev_b32_e32 v135, 31, v124
	v_ashrrev_i32_e32 v136, 11, v124
	v_add_u32_e32 v126, v117, v126
	v_lshl_add_u64 v[118:119], s[8:9], 0, v[118:119]
	v_ashrrev_i32_e32 v71, 31, v70
	v_lshl_add_u64 v[72:73], v[102:103], 0, v[66:67]
	v_lshl_add_u64 v[86:87], v[104:105], 0, v[66:67]
	v_ashrrev_i32_e32 v109, 31, v108
	v_ashrrev_i32_e32 v113, 31, v112
	v_lshlrev_b64 v[106:107], 11, v[106:107]
	v_add_u32_e32 v130, v130, v127
	v_add_u32_e32 v154, v134, v131
	v_add_u32_e32 v156, v136, v135
	v_mul_i32_i24_e32 v117, 0xffffdf00, v126
	v_lshl_add_u64 v[118:119], v[118:119], 0, v[114:115]
	s_barrier
	v_lshlrev_b64 v[152:153], 1, v[70:71]
	global_load_dwordx4 v[74:77], v[72:73], off
	global_load_dwordx4 v[66:69], v[72:73], off offset:64
	global_load_dwordx4 v[90:93], v[86:87], off
	global_load_dwordx4 v[82:85], v[86:87], off offset:64
	global_load_dwordx4 v[78:81], v[72:73], off offset:128
	s_nop 0
	global_load_dwordx4 v[70:73], v[72:73], off offset:192
	s_nop 0
	global_load_dwordx4 v[94:97], v[86:87], off offset:128
	s_nop 0
	global_load_dwordx4 v[86:89], v[86:87], off offset:192
	v_lshlrev_b64 v[120:121], 6, v[108:109]
	v_lshlrev_b64 v[108:109], 11, v[108:109]
	v_lshlrev_b64 v[124:125], 6, v[112:113]
	v_lshlrev_b64 v[112:113], 11, v[112:113]
	v_lshl_add_u64 v[128:129], s[10:11], 0, v[106:107]
	v_mul_i32_i24_e32 v164, 0xffffdf00, v130
	v_mul_i32_i24_e32 v165, 0xffffdf00, v154
	v_mul_i32_i24_e32 v166, 0xffffdf00, v156
	v_subrev_u32_e32 v117, s24, v117
	global_load_dword v180, v[118:119], off
	v_add_co_u32_e32 v118, vcc, s22, v118
	v_ashrrev_i32_e32 v111, 31, v110
	v_lshl_add_u64 v[106:107], s[12:13], 0, v[106:107]
	v_lshl_add_u64 v[132:133], s[10:11], 0, v[108:109]
	v_lshl_add_u64 v[108:109], s[12:13], 0, v[108:109]
	v_lshl_add_u64 v[160:161], s[10:11], 0, v[112:113]
	v_lshl_add_u64 v[162:163], s[12:13], 0, v[112:113]
	v_lshl_add_u64 v[128:129], v[128:129], 0, v[152:153]
	v_addc_co_u32_e32 v119, vcc, 0, v119, vcc
	v_subrev_u32_e32 v168, s24, v164
	v_subrev_u32_e32 v169, s24, v165
	v_subrev_u32_e32 v170, s24, v166
	v_subrev_u32_e32 v117, s23, v117
	v_lshlrev_b64 v[122:123], 6, v[110:111]
	v_lshlrev_b64 v[110:111], 11, v[110:111]
	v_lshl_add_u64 v[158:159], s[8:9], 0, v[124:125]
	v_lshl_add_u64 v[136:137], v[106:107], 0, v[152:153]
	v_lshl_add_u64 v[124:125], v[108:109], 0, v[152:153]
	v_lshl_add_u64 v[108:109], v[160:161], 0, v[152:153]
	v_lshl_add_u64 v[106:107], v[162:163], 0, v[152:153]
	global_load_dwordx2 v[160:161], v[128:129], off offset:64
	global_load_dwordx2 v[162:163], v[128:129], off offset:96
	global_load_dword v181, v[118:119], off
	global_load_dwordx2 v[164:165], v[128:129], off
	global_load_dwordx2 v[166:167], v[128:129], off offset:32
	v_subrev_u32_e32 v119, s23, v168
	v_subrev_u32_e32 v129, s23, v169
	v_subrev_u32_e32 v169, s23, v170
	v_add_u32_e32 v118, v116, v117
	v_lshl_add_u64 v[138:139], s[10:11], 0, v[110:111]
	v_lshl_add_u64 v[110:111], s[12:13], 0, v[110:111]
	v_ashrrev_i32_e32 v127, 31, v126
	v_add3_u32 v128, v116, v119, 16
	v_add3_u32 v168, v116, v129, 32
	v_add3_u32 v116, v116, v169, 48
	v_ashrrev_i32_e32 v119, 31, v118
	v_ashrrev_i32_e32 v131, 31, v130
	v_ashrrev_i32_e32 v155, 31, v154
	v_lshl_add_u64 v[112:113], v[110:111], 0, v[152:153]
	v_ashrrev_i32_e32 v157, 31, v156
	v_lshl_add_u64 v[110:111], v[158:159], 0, v[114:115]
	v_lshlrev_b64 v[158:159], 23, v[126:127]
	v_ashrrev_i32_e32 v129, 31, v128
	v_ashrrev_i32_e32 v169, 31, v168
	v_ashrrev_i32_e32 v117, 31, v116
	v_lshlrev_b64 v[118:119], 10, v[118:119]
	v_lshlrev_b64 v[130:131], 23, v[130:131]
	v_lshlrev_b64 v[154:155], 23, v[154:155]
	v_lshlrev_b64 v[156:157], 23, v[156:157]
	v_lshlrev_b64 v[128:129], 10, v[128:129]
	v_lshlrev_b64 v[168:169], 10, v[168:169]
	v_lshlrev_b64 v[116:117], 10, v[116:117]
	v_lshl_add_u64 v[118:119], v[118:119], 0, v[158:159]
	v_lshl_add_u64 v[128:129], v[128:129], 0, v[130:131]
	v_lshl_add_u64 v[130:131], v[168:169], 0, v[154:155]
	v_lshl_add_u64 v[116:117], v[116:117], 0, v[156:157]
	v_lshlrev_b64 v[118:119], 1, v[118:119]
	v_lshlrev_b64 v[128:129], 1, v[128:129]
	v_lshlrev_b64 v[130:131], 1, v[130:131]
	v_lshlrev_b64 v[116:117], 1, v[116:117]
	v_lshl_add_u64 v[154:155], s[4:5], 0, v[118:119]
	v_lshl_add_u64 v[118:119], s[6:7], 0, v[118:119]
	v_lshl_add_u64 v[120:121], s[8:9], 0, v[120:121]
	v_lshl_add_u64 v[156:157], s[4:5], 0, v[128:129]
	v_lshl_add_u64 v[128:129], s[6:7], 0, v[128:129]
	v_lshl_add_u64 v[158:159], s[4:5], 0, v[130:131]
	v_lshl_add_u64 v[130:131], s[6:7], 0, v[130:131]
	v_lshl_add_u64 v[168:169], s[4:5], 0, v[116:117]
	v_lshl_add_u64 v[116:117], s[6:7], 0, v[116:117]
	v_lshl_add_u64 v[154:155], v[154:155], 0, v[152:153]
	v_lshl_add_u64 v[170:171], v[118:119], 0, v[152:153]
	v_lshl_add_u64 v[134:135], v[120:121], 0, v[114:115]
	v_lshl_add_u64 v[132:133], v[132:133], 0, v[152:153]
	v_lshl_add_u64 v[120:121], v[138:139], 0, v[152:153]
	v_lshl_add_u64 v[156:157], v[156:157], 0, v[152:153]
	v_lshl_add_u64 v[172:173], v[128:129], 0, v[152:153]
	v_lshl_add_u64 v[128:129], v[158:159], 0, v[152:153]
	v_lshl_add_u64 v[130:131], v[130:131], 0, v[152:153]
	v_lshl_add_u64 v[118:119], v[168:169], 0, v[152:153]
	v_lshl_add_u64 v[116:117], v[116:117], 0, v[152:153]
	global_load_dwordx2 v[152:153], v[154:155], off
	global_load_dwordx2 v[158:159], v[170:171], off
	global_load_dwordx2 v[168:169], v[154:155], off offset:32
	global_load_dwordx2 v[174:175], v[170:171], off offset:32
	global_load_dwordx2 v[176:177], v[154:155], off offset:64
	global_load_dwordx2 v[178:179], v[170:171], off offset:64
	s_nop 0
	global_load_dwordx2 v[154:155], v[154:155], off offset:96
	s_nop 0
	global_load_dwordx2 v[170:171], v[170:171], off offset:96
	v_lshl_add_u64 v[122:123], s[8:9], 0, v[122:123]
	v_add_co_u32_e32 v138, vcc, s22, v134
	v_lshl_add_u64 v[122:123], v[122:123], 0, v[114:115]
	s_nop 0
	v_addc_co_u32_e32 v139, vcc, 0, v135, vcc
	v_add_co_u32_e32 v126, vcc, s22, v122
	s_add_i32 s3, s3, s14
	s_nop 0
	v_addc_co_u32_e32 v127, vcc, 0, v123, vcc
	v_add_co_u32_e32 v114, vcc, s22, v110
	v_add_u32_e32 v149, s16, v149
	s_nop 0
	v_addc_co_u32_e32 v115, vcc, 0, v111, vcc
	v_add_u32_e32 v150, s16, v150
	s_cmpk_lt_i32 s3, 0x100
	s_waitcnt vmcnt(10)
	v_add_f32_e32 v180, v180, v181
	s_waitcnt vmcnt(9)
	v_lshlrev_b32_e32 v182, 16, v164
	v_and_b32_e32 v183, 0xffff0000, v164
	v_lshlrev_b32_e32 v164, 16, v165
	v_and_b32_e32 v165, 0xffff0000, v165
	s_waitcnt vmcnt(8)
	v_lshlrev_b32_e32 v184, 16, v166
	v_and_b32_e32 v185, 0xffff0000, v166
	v_lshlrev_b32_e32 v166, 16, v167
	v_and_b32_e32 v167, 0xffff0000, v167
	s_waitcnt vmcnt(7)
	v_lshlrev_b32_e32 v186, 16, v152
	v_and_b32_e32 v187, 0xffff0000, v152
	v_lshlrev_b32_e32 v152, 16, v153
	v_and_b32_e32 v153, 0xffff0000, v153
	s_waitcnt vmcnt(6)
	v_lshlrev_b32_e32 v188, 16, v158
	v_and_b32_e32 v189, 0xffff0000, v158
	v_lshlrev_b32_e32 v158, 16, v159
	v_and_b32_e32 v159, 0xffff0000, v159
	s_waitcnt vmcnt(5)
	v_lshlrev_b32_e32 v190, 16, v168
	v_and_b32_e32 v191, 0xffff0000, v168
	v_lshlrev_b32_e32 v168, 16, v169
	v_and_b32_e32 v169, 0xffff0000, v169
	s_waitcnt vmcnt(4)
	v_lshlrev_b32_e32 v192, 16, v174
	v_and_b32_e32 v193, 0xffff0000, v174
	v_lshlrev_b32_e32 v174, 16, v175
	v_and_b32_e32 v175, 0xffff0000, v175
	v_pk_add_f32 v[152:153], v[152:153], v[158:159]
	v_pk_add_f32 v[158:159], v[186:187], v[188:189]
	v_pk_add_f32 v[168:169], v[168:169], v[174:175]
	v_pk_add_f32 v[174:175], v[190:191], v[192:193]
	s_waitcnt vmcnt(3)
	v_lshlrev_b32_e32 v194, 16, v176
	v_and_b32_e32 v195, 0xffff0000, v176
	v_lshlrev_b32_e32 v176, 16, v177
	v_and_b32_e32 v177, 0xffff0000, v177
	s_waitcnt vmcnt(2)
	v_lshlrev_b32_e32 v196, 16, v178
	v_and_b32_e32 v197, 0xffff0000, v178
	v_lshlrev_b32_e32 v178, 16, v179
	v_and_b32_e32 v179, 0xffff0000, v179
	s_waitcnt vmcnt(1)
	v_lshlrev_b32_e32 v198, 16, v154
	v_and_b32_e32 v199, 0xffff0000, v154
	v_lshlrev_b32_e32 v154, 16, v155
	v_and_b32_e32 v155, 0xffff0000, v155
	s_waitcnt vmcnt(0)
	v_lshlrev_b32_e32 v200, 16, v170
	v_and_b32_e32 v201, 0xffff0000, v170
	v_lshlrev_b32_e32 v170, 16, v171
	v_and_b32_e32 v171, 0xffff0000, v171
	v_mov_b32_e32 v186, v158
	v_mov_b32_e32 v187, v174
	v_mov_b32_e32 v188, v159
	v_mov_b32_e32 v189, v175
	v_pk_add_f32 v[176:177], v[176:177], v[178:179]
	v_pk_add_f32 v[178:179], v[194:195], v[196:197]
	v_pk_add_f32 v[154:155], v[154:155], v[170:171]
	v_pk_add_f32 v[170:171], v[198:199], v[200:201]
	v_mov_b32_e32 v190, v152
	v_mov_b32_e32 v191, v168
	v_pk_add_f32 v[186:187], v[186:187], v[188:189]
	v_mov_b32_e32 v192, v153
	v_mov_b32_e32 v193, v169
	v_mov_b32_e32 v194, v178
	v_mov_b32_e32 v195, v170
	v_mov_b32_e32 v196, v179
	v_mov_b32_e32 v197, v171
	v_pk_add_f32 v[186:187], v[190:191], v[186:187]
	v_mov_b32_e32 v198, v176
	v_mov_b32_e32 v199, v154
	v_pk_add_f32 v[188:189], v[194:195], v[196:197]
	v_pk_add_f32 v[186:187], v[192:193], v[186:187]
	v_mov_b32_e32 v200, v177
	v_mov_b32_e32 v201, v155
	v_pk_add_f32 v[188:189], v[198:199], v[188:189]
	v_add_f32_e32 v181, 0, v186
	v_pk_add_f32 v[188:189], v[200:201], v[188:189]
	v_add_f32_e32 v181, v181, v187
	v_add_f32_e32 v181, v181, v188
	v_add_f32_e32 v181, v181, v189
	ds_bpermute_b32 v186, v147, v181
	s_waitcnt lgkmcnt(0)
	v_add_f32_e32 v181, v181, v186
	ds_bpermute_b32 v186, v148, v181
	s_waitcnt lgkmcnt(0)
	v_add_f32_e32 v181, v181, v186
	v_fmamk_f32 v159, v181, 0xbc800000, v159
	v_fmamk_f32 v175, v181, 0xbc800000, v175
	v_fmac_f32_e32 v158, 0xbc800000, v181
	v_fmac_f32_e32 v174, 0xbc800000, v181
	v_fmamk_f32 v179, v181, 0xbc800000, v179
	v_fmamk_f32 v171, v181, 0xbc800000, v171
	v_mov_b32_e32 v188, v159
	v_mov_b32_e32 v189, v175
	v_fmac_f32_e32 v152, 0xbc800000, v181
	v_fmac_f32_e32 v168, 0xbc800000, v181
	v_fmac_f32_e32 v178, 0xbc800000, v181
	v_fmac_f32_e32 v170, 0xbc800000, v181
	v_mov_b32_e32 v186, v158
	v_mov_b32_e32 v187, v174
	v_mov_b32_e32 v196, v171
	v_mov_b32_e32 v197, v179
	v_pk_mul_f32 v[188:189], v[188:189], v[188:189]
	v_fmamk_f32 v153, v181, 0xbc800000, v153
	v_fmamk_f32 v169, v181, 0xbc800000, v169
	v_fmac_f32_e32 v176, 0xbc800000, v181
	v_fmac_f32_e32 v154, 0xbc800000, v181
	v_mov_b32_e32 v190, v152
	v_mov_b32_e32 v191, v168
	v_mov_b32_e32 v194, v170
	v_mov_b32_e32 v195, v178
	v_pk_mul_f32 v[196:197], v[196:197], v[196:197]
	v_pk_fma_f32 v[186:187], v[186:187], v[186:187], v[188:189]
	v_fmamk_f32 v177, v181, 0xbc800000, v177
	v_fmamk_f32 v155, v181, 0xbc800000, v155
	v_mov_b32_e32 v192, v153
	v_mov_b32_e32 v193, v169
	v_mov_b32_e32 v198, v154
	v_mov_b32_e32 v199, v176
	v_pk_fma_f32 v[188:189], v[194:195], v[194:195], v[196:197]
	v_pk_fma_f32 v[186:187], v[190:191], v[190:191], v[186:187]
	v_mov_b32_e32 v200, v155
	v_mov_b32_e32 v201, v177
	v_pk_fma_f32 v[188:189], v[198:199], v[198:199], v[188:189]
	v_pk_fma_f32 v[186:187], v[192:193], v[192:193], v[186:187]
	v_pk_fma_f32 v[188:189], v[200:201], v[200:201], v[188:189]
	v_add_f32_e32 v181, v186, v187
	v_add_f32_e32 v181, v189, v181
	v_add_f32_e32 v181, v188, v181
	ds_bpermute_b32 v186, v147, v181
	s_waitcnt lgkmcnt(0)
	v_add_f32_e32 v181, v181, v186
	ds_bpermute_b32 v186, v148, v181
	s_waitcnt lgkmcnt(0)
	v_add_f32_e32 v181, v181, v186
	v_fmamk_f32 v181, v181, 0x3c800000, v151
	v_mul_f32_e32 v186, 0x4b800000, v181
	v_cmp_gt_f32_e32 vcc, s21, v181
	s_nop 1
	v_cndmask_b32_e32 v181, v181, v186, vcc
	v_rsq_f32_e32 v181, v181
	s_nop 0
	v_mul_f32_e32 v186, 0x45800000, v181
	v_cndmask_b32_e32 v186, v181, v186, vcc
	v_pk_mul_f32 v[158:159], v[158:159], v[186:187] op_sel_hi:[1,0]
	v_pk_mul_f32 v[152:153], v[152:153], v[186:187] op_sel_hi:[1,0]
	v_pk_mul_f32 v[174:175], v[174:175], v[186:187] op_sel_hi:[1,0]
	v_pk_mul_f32 v[168:169], v[168:169], v[186:187] op_sel_hi:[1,0]
	v_pk_fma_f32 v[152:153], v[76:77], v[152:153], v[92:93]
	v_pk_fma_f32 v[158:159], v[74:75], v[158:159], v[90:91]
	v_pk_fma_f32 v[168:169], v[68:69], v[168:169], v[84:85]
	v_pk_fma_f32 v[174:175], v[66:67], v[174:175], v[82:83]
	v_pk_fma_f32 v[158:159], v[180:181], v[182:183], v[158:159] op_sel_hi:[0,1,1]
	v_pk_fma_f32 v[152:153], v[180:181], v[164:165], v[152:153] op_sel_hi:[0,1,1]
	v_pk_fma_f32 v[164:165], v[180:181], v[184:185], v[174:175] op_sel_hi:[0,1,1]
	v_pk_fma_f32 v[166:167], v[180:181], v[166:167], v[168:169] op_sel_hi:[0,1,1]
	v_pk_mul_f32 v[64:65], v[64:65], v[152:153]
	v_pk_mul_f32 v[62:63], v[62:63], v[158:159]
	v_pk_mul_f32 v[178:179], v[178:179], v[186:187] op_sel_hi:[1,0]
	v_pk_mul_f32 v[176:177], v[176:177], v[186:187] op_sel_hi:[1,0]
	v_pk_mul_f32 v[60:61], v[60:61], v[166:167]
	v_pk_mul_f32 v[58:59], v[58:59], v[164:165]
	v_cvt_pk_bf16_f32 v62, v62, v63
	v_cvt_pk_bf16_f32 v63, v64, v65
	v_pk_mul_f32 v[170:171], v[170:171], v[186:187] op_sel_hi:[1,0]
	v_pk_mul_f32 v[154:155], v[154:155], v[186:187] op_sel_hi:[1,0]
	v_pk_fma_f32 v[176:177], v[80:81], v[176:177], v[96:97]
	v_pk_fma_f32 v[178:179], v[78:79], v[178:179], v[94:95]
	v_cvt_pk_bf16_f32 v58, v58, v59
	v_cvt_pk_bf16_f32 v59, v60, v61
	global_store_dwordx2 v[136:137], v[62:63], off
	global_store_dwordx2 v[136:137], v[58:59], off offset:32
	v_lshlrev_b32_e32 v60, 16, v160
	v_and_b32_e32 v61, 0xffff0000, v160
	v_lshlrev_b32_e32 v62, 16, v161
	v_and_b32_e32 v63, 0xffff0000, v161
	v_pk_fma_f32 v[154:155], v[72:73], v[154:155], v[88:89]
	v_pk_fma_f32 v[170:171], v[70:71], v[170:171], v[86:87]
	v_lshlrev_b32_e32 v64, 16, v162
	v_and_b32_e32 v65, 0xffff0000, v162
	v_lshlrev_b32_e32 v152, 16, v163
	v_and_b32_e32 v153, 0xffff0000, v163
	v_pk_fma_f32 v[60:61], v[180:181], v[60:61], v[178:179] op_sel_hi:[0,1,1]
	v_pk_fma_f32 v[62:63], v[180:181], v[62:63], v[176:177] op_sel_hi:[0,1,1]
	v_pk_fma_f32 v[64:65], v[180:181], v[64:65], v[170:171] op_sel_hi:[0,1,1]
	v_pk_fma_f32 v[152:153], v[180:181], v[152:153], v[154:155] op_sel_hi:[0,1,1]
	v_pk_mul_f32 v[56:57], v[56:57], v[62:63]
	v_pk_mul_f32 v[54:55], v[54:55], v[60:61]
	v_pk_mul_f32 v[52:53], v[52:53], v[152:153]
	v_pk_mul_f32 v[50:51], v[50:51], v[64:65]
	v_cvt_pk_bf16_f32 v54, v54, v55
	v_cvt_pk_bf16_f32 v55, v56, v57
	global_load_dwordx2 v[58:59], v[132:133], off
	v_cvt_pk_bf16_f32 v50, v50, v51
	v_cvt_pk_bf16_f32 v51, v52, v53
	global_store_dwordx2 v[136:137], v[54:55], off offset:64
	global_store_dwordx2 v[136:137], v[50:51], off offset:96
	global_load_dwordx2 v[50:51], v[156:157], off
	s_nop 0
	global_load_dwordx2 v[52:53], v[172:173], off
	global_load_dwordx2 v[54:55], v[156:157], off offset:32
	global_load_dwordx2 v[56:57], v[172:173], off offset:32
	global_load_dwordx2 v[60:61], v[156:157], off offset:64
	global_load_dwordx2 v[62:63], v[172:173], off offset:64
	global_load_dwordx2 v[64:65], v[156:157], off offset:96
	global_load_dwordx2 v[136:137], v[172:173], off offset:96
	global_load_dword v170, v[134:135], off
	global_load_dword v171, v[138:139], off
	s_nop 0
	global_load_dwordx2 v[134:135], v[132:133], off offset:32
	global_load_dwordx2 v[138:139], v[132:133], off offset:64
	s_nop 0
	global_load_dwordx2 v[132:133], v[132:133], off offset:96
	s_waitcnt vmcnt(12)
	v_lshlrev_b32_e32 v154, 16, v50
	v_and_b32_e32 v155, 0xffff0000, v50
	v_lshlrev_b32_e32 v50, 16, v51
	v_and_b32_e32 v51, 0xffff0000, v51
	s_waitcnt vmcnt(11)
	v_lshlrev_b32_e32 v156, 16, v52
	v_and_b32_e32 v157, 0xffff0000, v52
	v_lshlrev_b32_e32 v52, 16, v53
	v_and_b32_e32 v53, 0xffff0000, v53
	s_waitcnt vmcnt(10)
	v_lshlrev_b32_e32 v158, 16, v54
	v_and_b32_e32 v159, 0xffff0000, v54
	v_lshlrev_b32_e32 v54, 16, v55
	v_and_b32_e32 v55, 0xffff0000, v55
	s_waitcnt vmcnt(9)
	v_lshlrev_b32_e32 v160, 16, v56
	v_and_b32_e32 v161, 0xffff0000, v56
	v_lshlrev_b32_e32 v56, 16, v57
	v_and_b32_e32 v57, 0xffff0000, v57
	v_pk_add_f32 v[50:51], v[50:51], v[52:53]
	v_pk_add_f32 v[52:53], v[154:155], v[156:157]
	v_pk_add_f32 v[54:55], v[54:55], v[56:57]
	v_pk_add_f32 v[56:57], v[158:159], v[160:161]
	s_waitcnt vmcnt(8)
	v_lshlrev_b32_e32 v162, 16, v60
	v_and_b32_e32 v163, 0xffff0000, v60
	v_lshlrev_b32_e32 v60, 16, v61
	v_and_b32_e32 v61, 0xffff0000, v61
	s_waitcnt vmcnt(7)
	v_lshlrev_b32_e32 v164, 16, v62
	v_and_b32_e32 v165, 0xffff0000, v62
	v_lshlrev_b32_e32 v62, 16, v63
	v_and_b32_e32 v63, 0xffff0000, v63
	s_waitcnt vmcnt(6)
	v_lshlrev_b32_e32 v166, 16, v64
	v_and_b32_e32 v167, 0xffff0000, v64
	v_lshlrev_b32_e32 v64, 16, v65
	v_and_b32_e32 v65, 0xffff0000, v65
	s_waitcnt vmcnt(5)
	v_lshlrev_b32_e32 v168, 16, v136
	v_and_b32_e32 v169, 0xffff0000, v136
	v_lshlrev_b32_e32 v136, 16, v137
	v_and_b32_e32 v137, 0xffff0000, v137
	v_mov_b32_e32 v154, v52
	v_mov_b32_e32 v155, v56
	v_mov_b32_e32 v156, v53
	v_mov_b32_e32 v157, v57
	v_pk_add_f32 v[60:61], v[60:61], v[62:63]
	v_pk_add_f32 v[62:63], v[162:163], v[164:165]
	v_pk_add_f32 v[64:65], v[64:65], v[136:137]
	v_pk_add_f32 v[136:137], v[166:167], v[168:169]
	v_mov_b32_e32 v158, v50
	v_mov_b32_e32 v159, v54
	v_pk_add_f32 v[154:155], v[154:155], v[156:157]
	v_mov_b32_e32 v160, v51
	v_mov_b32_e32 v161, v55
	v_mov_b32_e32 v162, v62
	v_mov_b32_e32 v163, v136
	v_mov_b32_e32 v164, v63
	v_mov_b32_e32 v165, v137
	v_pk_add_f32 v[154:155], v[158:159], v[154:155]
	v_mov_b32_e32 v166, v60
	v_mov_b32_e32 v167, v64
	v_pk_add_f32 v[156:157], v[162:163], v[164:165]
	v_pk_add_f32 v[154:155], v[160:161], v[154:155]
	v_mov_b32_e32 v168, v61
	v_mov_b32_e32 v169, v65
	v_pk_add_f32 v[156:157], v[166:167], v[156:157]
	v_add_f32_e32 v154, 0, v154
	v_pk_add_f32 v[156:157], v[168:169], v[156:157]
	v_add_f32_e32 v154, v154, v155
	v_add_f32_e32 v154, v154, v156
	v_add_f32_e32 v154, v154, v157
	ds_bpermute_b32 v155, v147, v154
	v_lshlrev_b32_e32 v152, 16, v58
	v_and_b32_e32 v153, 0xffff0000, v58
	v_lshlrev_b32_e32 v58, 16, v59
	v_and_b32_e32 v59, 0xffff0000, v59
	s_waitcnt lgkmcnt(0)
	v_add_f32_e32 v154, v154, v155
	ds_bpermute_b32 v155, v148, v154
	s_waitcnt vmcnt(3)
	v_add_f32_e32 v170, v170, v171
	s_waitcnt vmcnt(2)
	v_lshlrev_b32_e32 v172, 16, v134
	v_and_b32_e32 v173, 0xffff0000, v134
	v_lshlrev_b32_e32 v134, 16, v135
	s_waitcnt lgkmcnt(0)
	v_add_f32_e32 v154, v154, v155
	v_fmamk_f32 v53, v154, 0xbc800000, v53
	v_fmamk_f32 v57, v154, 0xbc800000, v57
	v_fmac_f32_e32 v52, 0xbc800000, v154
	v_fmac_f32_e32 v56, 0xbc800000, v154
	v_fmamk_f32 v63, v154, 0xbc800000, v63
	v_fmamk_f32 v137, v154, 0xbc800000, v137
	v_mov_b32_e32 v156, v53
	v_mov_b32_e32 v157, v57
	v_fmamk_f32 v51, v154, 0xbc800000, v51
	v_fmac_f32_e32 v50, 0xbc800000, v154
	v_fmamk_f32 v55, v154, 0xbc800000, v55
	v_fmac_f32_e32 v54, 0xbc800000, v154
	v_fmamk_f32 v61, v154, 0xbc800000, v61
	v_fmac_f32_e32 v60, 0xbc800000, v154
	v_fmac_f32_e32 v62, 0xbc800000, v154
	v_fmamk_f32 v65, v154, 0xbc800000, v65
	v_fmac_f32_e32 v64, 0xbc800000, v154
	v_fmac_f32_e32 v136, 0xbc800000, v154
	v_mov_b32_e32 v154, v52
	v_mov_b32_e32 v155, v56
	v_mov_b32_e32 v164, v137
	v_mov_b32_e32 v165, v63
	v_pk_mul_f32 v[156:157], v[156:157], v[156:157]
	v_mov_b32_e32 v158, v50
	v_mov_b32_e32 v159, v54
	v_mov_b32_e32 v162, v136
	v_mov_b32_e32 v163, v62
	v_pk_mul_f32 v[164:165], v[164:165], v[164:165]
	v_pk_fma_f32 v[154:155], v[154:155], v[154:155], v[156:157]
	v_mov_b32_e32 v160, v51
	v_mov_b32_e32 v161, v55
	v_mov_b32_e32 v166, v64
	v_mov_b32_e32 v167, v60
	v_pk_fma_f32 v[156:157], v[162:163], v[162:163], v[164:165]
	v_pk_fma_f32 v[154:155], v[158:159], v[158:159], v[154:155]
	v_mov_b32_e32 v168, v65
	v_mov_b32_e32 v169, v61
	v_pk_fma_f32 v[156:157], v[166:167], v[166:167], v[156:157]
	v_pk_fma_f32 v[154:155], v[160:161], v[160:161], v[154:155]
	v_pk_fma_f32 v[156:157], v[168:169], v[168:169], v[156:157]
	v_add_f32_e32 v154, v154, v155
	v_add_f32_e32 v154, v157, v154
	v_add_f32_e32 v154, v156, v154
	ds_bpermute_b32 v155, v147, v154
	v_and_b32_e32 v135, 0xffff0000, v135
	s_waitcnt vmcnt(1)
	v_lshlrev_b32_e32 v174, 16, v138
	v_and_b32_e32 v175, 0xffff0000, v138
	v_lshlrev_b32_e32 v138, 16, v139
	s_waitcnt lgkmcnt(0)
	v_add_f32_e32 v154, v154, v155
	ds_bpermute_b32 v155, v148, v154
	v_and_b32_e32 v139, 0xffff0000, v139
	s_waitcnt lgkmcnt(0)
	v_add_f32_e32 v154, v154, v155
	v_fmamk_f32 v154, v154, 0x3c800000, v151
	v_mul_f32_e32 v155, 0x4b800000, v154
	v_cmp_gt_f32_e32 vcc, s21, v154
	s_nop 1
	v_cndmask_b32_e32 v154, v154, v155, vcc
	v_rsq_f32_e32 v154, v154
	s_nop 0
	v_mul_f32_e32 v155, 0x45800000, v154
	v_cndmask_b32_e32 v154, v154, v155, vcc
	v_pk_mul_f32 v[52:53], v[52:53], v[154:155] op_sel_hi:[1,0]
	v_pk_mul_f32 v[50:51], v[50:51], v[154:155] op_sel_hi:[1,0]
	v_pk_mul_f32 v[56:57], v[56:57], v[154:155] op_sel_hi:[1,0]
	v_pk_mul_f32 v[54:55], v[54:55], v[154:155] op_sel_hi:[1,0]
	v_pk_mul_f32 v[62:63], v[62:63], v[154:155] op_sel_hi:[1,0]
	v_pk_mul_f32 v[60:61], v[60:61], v[154:155] op_sel_hi:[1,0]
	v_pk_fma_f32 v[50:51], v[76:77], v[50:51], v[92:93]
	v_pk_fma_f32 v[52:53], v[74:75], v[52:53], v[90:91]
	v_pk_fma_f32 v[54:55], v[68:69], v[54:55], v[84:85]
	v_pk_fma_f32 v[56:57], v[66:67], v[56:57], v[82:83]
	v_pk_fma_f32 v[60:61], v[80:81], v[60:61], v[96:97]
	v_pk_fma_f32 v[62:63], v[78:79], v[62:63], v[94:95]
	v_pk_fma_f32 v[52:53], v[170:171], v[152:153], v[52:53] op_sel_hi:[0,1,1]
	v_pk_fma_f32 v[50:51], v[170:171], v[58:59], v[50:51] op_sel_hi:[0,1,1]
	v_pk_fma_f32 v[56:57], v[170:171], v[172:173], v[56:57] op_sel_hi:[0,1,1]
	v_pk_fma_f32 v[54:55], v[170:171], v[134:135], v[54:55] op_sel_hi:[0,1,1]
	v_pk_fma_f32 v[58:59], v[170:171], v[174:175], v[62:63] op_sel_hi:[0,1,1]
	v_pk_fma_f32 v[60:61], v[170:171], v[138:139], v[60:61] op_sel_hi:[0,1,1]
	v_pk_mul_f32 v[48:49], v[48:49], v[50:51]
	v_pk_mul_f32 v[46:47], v[46:47], v[52:53]
	v_pk_mul_f32 v[44:45], v[44:45], v[54:55]
	v_pk_mul_f32 v[42:43], v[42:43], v[56:57]
	v_pk_mul_f32 v[136:137], v[136:137], v[154:155] op_sel_hi:[1,0]
	v_pk_mul_f32 v[64:65], v[64:65], v[154:155] op_sel_hi:[1,0]
	v_pk_mul_f32 v[40:41], v[40:41], v[60:61]
	v_pk_mul_f32 v[38:39], v[38:39], v[58:59]
	v_cvt_pk_bf16_f32 v46, v46, v47
	v_cvt_pk_bf16_f32 v47, v48, v49
	v_cvt_pk_bf16_f32 v42, v42, v43
	v_cvt_pk_bf16_f32 v43, v44, v45
	v_pk_fma_f32 v[64:65], v[72:73], v[64:65], v[88:89]
	v_pk_fma_f32 v[136:137], v[70:71], v[136:137], v[86:87]
	v_cvt_pk_bf16_f32 v38, v38, v39
	v_cvt_pk_bf16_f32 v39, v40, v41
	global_store_dwordx2 v[124:125], v[46:47], off
	global_store_dwordx2 v[124:125], v[42:43], off offset:32
	global_store_dwordx2 v[124:125], v[38:39], off offset:64
	s_waitcnt vmcnt(3)
	v_lshlrev_b32_e32 v42, 16, v132
	v_and_b32_e32 v43, 0xffff0000, v132
	v_lshlrev_b32_e32 v44, 16, v133
	v_and_b32_e32 v45, 0xffff0000, v133
	v_pk_fma_f32 v[42:43], v[170:171], v[42:43], v[136:137] op_sel_hi:[0,1,1]
	v_pk_fma_f32 v[44:45], v[170:171], v[44:45], v[64:65] op_sel_hi:[0,1,1]
	v_pk_mul_f32 v[36:37], v[36:37], v[44:45]
	v_pk_mul_f32 v[34:35], v[34:35], v[42:43]
	global_load_dwordx2 v[38:39], v[120:121], off
	global_load_dwordx2 v[40:41], v[120:121], off offset:64
	v_cvt_pk_bf16_f32 v34, v34, v35
	v_cvt_pk_bf16_f32 v35, v36, v37
	global_store_dwordx2 v[124:125], v[34:35], off offset:96
	global_load_dwordx2 v[34:35], v[128:129], off
	s_nop 0
	global_load_dwordx2 v[36:37], v[130:131], off
	global_load_dwordx2 v[42:43], v[128:129], off offset:32
	global_load_dwordx2 v[44:45], v[130:131], off offset:32
	global_load_dwordx2 v[46:47], v[128:129], off offset:64
	global_load_dwordx2 v[48:49], v[130:131], off offset:64
	global_load_dwordx2 v[50:51], v[128:129], off offset:96
	global_load_dwordx2 v[52:53], v[130:131], off offset:96
	global_load_dword v132, v[122:123], off
	global_load_dword v133, v[126:127], off
	global_load_dwordx2 v[54:55], v[120:121], off offset:32
	global_load_dwordx2 v[56:57], v[120:121], off offset:96
	s_waitcnt vmcnt(11)
	v_lshlrev_b32_e32 v62, 16, v34
	v_and_b32_e32 v63, 0xffff0000, v34
	v_lshlrev_b32_e32 v34, 16, v35
	v_and_b32_e32 v35, 0xffff0000, v35
	s_waitcnt vmcnt(10)
	v_lshlrev_b32_e32 v64, 16, v36
	v_and_b32_e32 v65, 0xffff0000, v36
	v_lshlrev_b32_e32 v36, 16, v37
	v_and_b32_e32 v37, 0xffff0000, v37
	s_waitcnt vmcnt(9)
	v_lshlrev_b32_e32 v120, 16, v42
	v_and_b32_e32 v121, 0xffff0000, v42
	v_lshlrev_b32_e32 v42, 16, v43
	v_and_b32_e32 v43, 0xffff0000, v43
	s_waitcnt vmcnt(8)
	v_lshlrev_b32_e32 v122, 16, v44
	v_and_b32_e32 v123, 0xffff0000, v44
	v_lshlrev_b32_e32 v44, 16, v45
	v_and_b32_e32 v45, 0xffff0000, v45
	v_pk_add_f32 v[34:35], v[34:35], v[36:37]
	v_pk_add_f32 v[36:37], v[62:63], v[64:65]
	v_pk_add_f32 v[42:43], v[42:43], v[44:45]
	v_pk_add_f32 v[44:45], v[120:121], v[122:123]
	s_waitcnt vmcnt(7)
	v_lshlrev_b32_e32 v124, 16, v46
	v_and_b32_e32 v125, 0xffff0000, v46
	v_lshlrev_b32_e32 v46, 16, v47
	v_and_b32_e32 v47, 0xffff0000, v47
	s_waitcnt vmcnt(6)
	v_lshlrev_b32_e32 v126, 16, v48
	v_and_b32_e32 v127, 0xffff0000, v48
	v_lshlrev_b32_e32 v48, 16, v49
	v_and_b32_e32 v49, 0xffff0000, v49
	s_waitcnt vmcnt(5)
	v_lshlrev_b32_e32 v128, 16, v50
	v_and_b32_e32 v129, 0xffff0000, v50
	v_lshlrev_b32_e32 v50, 16, v51
	v_and_b32_e32 v51, 0xffff0000, v51
	s_waitcnt vmcnt(4)
	v_lshlrev_b32_e32 v130, 16, v52
	v_and_b32_e32 v131, 0xffff0000, v52
	v_lshlrev_b32_e32 v52, 16, v53
	v_and_b32_e32 v53, 0xffff0000, v53
	v_mov_b32_e32 v62, v36
	v_mov_b32_e32 v63, v44
	v_mov_b32_e32 v64, v37
	v_mov_b32_e32 v65, v45
	v_pk_add_f32 v[46:47], v[46:47], v[48:49]
	v_pk_add_f32 v[48:49], v[124:125], v[126:127]
	v_pk_add_f32 v[50:51], v[50:51], v[52:53]
	v_pk_add_f32 v[52:53], v[128:129], v[130:131]
	v_mov_b32_e32 v120, v34
	v_mov_b32_e32 v121, v42
	v_pk_add_f32 v[62:63], v[62:63], v[64:65]
	v_mov_b32_e32 v122, v35
	v_mov_b32_e32 v123, v43
	v_mov_b32_e32 v124, v48
	v_mov_b32_e32 v125, v52
	v_mov_b32_e32 v126, v49
	v_mov_b32_e32 v127, v53
	v_pk_add_f32 v[62:63], v[120:121], v[62:63]
	v_mov_b32_e32 v128, v46
	v_mov_b32_e32 v129, v50
	v_pk_add_f32 v[64:65], v[124:125], v[126:127]
	v_pk_add_f32 v[62:63], v[122:123], v[62:63]
	v_mov_b32_e32 v130, v47
	v_mov_b32_e32 v131, v51
	v_pk_add_f32 v[64:65], v[128:129], v[64:65]
	v_add_f32_e32 v62, 0, v62
	v_pk_add_f32 v[64:65], v[130:131], v[64:65]
	v_add_f32_e32 v62, v62, v63
	v_add_f32_e32 v62, v62, v64
	v_add_f32_e32 v62, v62, v65
	ds_bpermute_b32 v63, v147, v62
	v_lshlrev_b32_e32 v58, 16, v38
	v_and_b32_e32 v59, 0xffff0000, v38
	v_lshlrev_b32_e32 v38, 16, v39
	v_and_b32_e32 v39, 0xffff0000, v39
	s_waitcnt lgkmcnt(0)
	v_add_f32_e32 v62, v62, v63
	ds_bpermute_b32 v63, v148, v62
	s_waitcnt vmcnt(2)
	v_add_f32_e32 v132, v132, v133
	v_lshlrev_b32_e32 v60, 16, v40
	v_and_b32_e32 v61, 0xffff0000, v40
	v_lshlrev_b32_e32 v40, 16, v41
	s_waitcnt lgkmcnt(0)
	v_add_f32_e32 v62, v62, v63
	v_fmamk_f32 v37, v62, 0xbc800000, v37
	v_fmamk_f32 v45, v62, 0xbc800000, v45
	v_fmac_f32_e32 v36, 0xbc800000, v62
	v_fmac_f32_e32 v44, 0xbc800000, v62
	v_fmamk_f32 v49, v62, 0xbc800000, v49
	v_fmamk_f32 v53, v62, 0xbc800000, v53
	v_mov_b32_e32 v64, v37
	v_mov_b32_e32 v65, v45
	v_fmamk_f32 v35, v62, 0xbc800000, v35
	v_fmac_f32_e32 v34, 0xbc800000, v62
	v_fmamk_f32 v43, v62, 0xbc800000, v43
	v_fmac_f32_e32 v42, 0xbc800000, v62
	v_fmamk_f32 v47, v62, 0xbc800000, v47
	v_fmac_f32_e32 v46, 0xbc800000, v62
	v_fmac_f32_e32 v48, 0xbc800000, v62
	v_fmamk_f32 v51, v62, 0xbc800000, v51
	v_fmac_f32_e32 v50, 0xbc800000, v62
	v_fmac_f32_e32 v52, 0xbc800000, v62
	v_mov_b32_e32 v62, v36
	v_mov_b32_e32 v63, v44
	v_mov_b32_e32 v126, v53
	v_mov_b32_e32 v127, v49
	v_pk_mul_f32 v[64:65], v[64:65], v[64:65]
	v_mov_b32_e32 v120, v34
	v_mov_b32_e32 v121, v42
	v_mov_b32_e32 v124, v52
	v_mov_b32_e32 v125, v48
	v_pk_mul_f32 v[126:127], v[126:127], v[126:127]
	v_pk_fma_f32 v[62:63], v[62:63], v[62:63], v[64:65]
	v_mov_b32_e32 v122, v35
	v_mov_b32_e32 v123, v43
	v_mov_b32_e32 v128, v50
	v_mov_b32_e32 v129, v46
	v_pk_fma_f32 v[64:65], v[124:125], v[124:125], v[126:127]
	v_pk_fma_f32 v[62:63], v[120:121], v[120:121], v[62:63]
	v_mov_b32_e32 v130, v51
	v_mov_b32_e32 v131, v47
	v_pk_fma_f32 v[64:65], v[128:129], v[128:129], v[64:65]
	v_pk_fma_f32 v[62:63], v[122:123], v[122:123], v[62:63]
	v_pk_fma_f32 v[64:65], v[130:131], v[130:131], v[64:65]
	v_add_f32_e32 v62, v62, v63
	v_add_f32_e32 v62, v65, v62
	v_add_f32_e32 v62, v64, v62
	ds_bpermute_b32 v63, v147, v62
	v_and_b32_e32 v41, 0xffff0000, v41
	s_waitcnt vmcnt(1)
	v_lshlrev_b32_e32 v134, 16, v54
	v_and_b32_e32 v135, 0xffff0000, v54
	v_lshlrev_b32_e32 v54, 16, v55
	s_waitcnt lgkmcnt(0)
	v_add_f32_e32 v62, v62, v63
	ds_bpermute_b32 v63, v148, v62
	v_and_b32_e32 v55, 0xffff0000, v55
	s_waitcnt vmcnt(0)
	v_lshlrev_b32_e32 v136, 16, v56
	v_and_b32_e32 v137, 0xffff0000, v56
	v_lshlrev_b32_e32 v56, 16, v57
	s_waitcnt lgkmcnt(0)
	v_add_f32_e32 v62, v62, v63
	v_fmamk_f32 v62, v62, 0x3c800000, v151
	v_mul_f32_e32 v63, 0x4b800000, v62
	v_cmp_gt_f32_e32 vcc, s21, v62
	v_and_b32_e32 v57, 0xffff0000, v57
	s_nop 0
	v_cndmask_b32_e32 v62, v62, v63, vcc
	v_rsq_f32_e32 v62, v62
	s_nop 0
	v_mul_f32_e32 v63, 0x45800000, v62
	v_cndmask_b32_e32 v62, v62, v63, vcc
	v_pk_mul_f32 v[36:37], v[36:37], v[62:63] op_sel_hi:[1,0]
	v_pk_mul_f32 v[34:35], v[34:35], v[62:63] op_sel_hi:[1,0]
	v_pk_mul_f32 v[44:45], v[44:45], v[62:63] op_sel_hi:[1,0]
	v_pk_mul_f32 v[42:43], v[42:43], v[62:63] op_sel_hi:[1,0]
	v_pk_mul_f32 v[48:49], v[48:49], v[62:63] op_sel_hi:[1,0]
	v_pk_mul_f32 v[46:47], v[46:47], v[62:63] op_sel_hi:[1,0]
	v_pk_mul_f32 v[52:53], v[52:53], v[62:63] op_sel_hi:[1,0]
	v_pk_mul_f32 v[50:51], v[50:51], v[62:63] op_sel_hi:[1,0]
	v_pk_fma_f32 v[34:35], v[76:77], v[34:35], v[92:93]
	v_pk_fma_f32 v[36:37], v[74:75], v[36:37], v[90:91]
	v_pk_fma_f32 v[42:43], v[68:69], v[42:43], v[84:85]
	v_pk_fma_f32 v[44:45], v[66:67], v[44:45], v[82:83]
	v_pk_fma_f32 v[46:47], v[80:81], v[46:47], v[96:97]
	v_pk_fma_f32 v[48:49], v[78:79], v[48:49], v[94:95]
	v_pk_fma_f32 v[50:51], v[72:73], v[50:51], v[88:89]
	v_pk_fma_f32 v[52:53], v[70:71], v[52:53], v[86:87]
	v_pk_fma_f32 v[36:37], v[132:133], v[58:59], v[36:37] op_sel_hi:[0,1,1]
	v_pk_fma_f32 v[34:35], v[132:133], v[38:39], v[34:35] op_sel_hi:[0,1,1]
	v_pk_fma_f32 v[38:39], v[132:133], v[134:135], v[44:45] op_sel_hi:[0,1,1]
	v_pk_fma_f32 v[42:43], v[132:133], v[54:55], v[42:43] op_sel_hi:[0,1,1]
	v_pk_fma_f32 v[44:45], v[132:133], v[60:61], v[48:49] op_sel_hi:[0,1,1]
	v_pk_fma_f32 v[40:41], v[132:133], v[40:41], v[46:47] op_sel_hi:[0,1,1]
	v_pk_fma_f32 v[46:47], v[132:133], v[136:137], v[52:53] op_sel_hi:[0,1,1]
	v_pk_fma_f32 v[48:49], v[132:133], v[56:57], v[50:51] op_sel_hi:[0,1,1]
	v_pk_mul_f32 v[32:33], v[32:33], v[34:35]
	v_pk_mul_f32 v[30:31], v[30:31], v[36:37]
	v_pk_mul_f32 v[28:29], v[28:29], v[42:43]
	v_pk_mul_f32 v[26:27], v[26:27], v[38:39]
	v_pk_mul_f32 v[24:25], v[24:25], v[40:41]
	v_pk_mul_f32 v[22:23], v[22:23], v[44:45]
	v_pk_mul_f32 v[20:21], v[20:21], v[48:49]
	v_pk_mul_f32 v[18:19], v[18:19], v[46:47]
	v_cvt_pk_bf16_f32 v30, v30, v31
	v_cvt_pk_bf16_f32 v31, v32, v33
	v_cvt_pk_bf16_f32 v26, v26, v27
	v_cvt_pk_bf16_f32 v27, v28, v29
	v_cvt_pk_bf16_f32 v22, v22, v23
	v_cvt_pk_bf16_f32 v23, v24, v25
	v_cvt_pk_bf16_f32 v18, v18, v19
	v_cvt_pk_bf16_f32 v19, v20, v21
	global_store_dwordx2 v[112:113], v[30:31], off
	global_store_dwordx2 v[112:113], v[26:27], off offset:32
	global_store_dwordx2 v[112:113], v[22:23], off offset:64
	global_store_dwordx2 v[112:113], v[18:19], off offset:96
	global_load_dwordx2 v[18:19], v[118:119], off
	s_nop 0
	global_load_dwordx2 v[20:21], v[116:117], off
	global_load_dwordx2 v[22:23], v[118:119], off offset:32
	global_load_dwordx2 v[24:25], v[116:117], off offset:32
	global_load_dwordx2 v[26:27], v[118:119], off offset:64
	global_load_dwordx2 v[28:29], v[116:117], off offset:64
	global_load_dwordx2 v[30:31], v[118:119], off offset:96
	global_load_dwordx2 v[32:33], v[116:117], off offset:96
	global_load_dword v58, v[110:111], off
	global_load_dword v59, v[114:115], off
	global_load_dwordx2 v[34:35], v[108:109], off
	global_load_dwordx2 v[36:37], v[108:109], off offset:32
	global_load_dwordx2 v[38:39], v[108:109], off offset:64
	global_load_dwordx2 v[40:41], v[108:109], off offset:96
	s_waitcnt vmcnt(13)
	v_lshlrev_b32_e32 v42, 16, v18
	v_and_b32_e32 v43, 0xffff0000, v18
	v_lshlrev_b32_e32 v18, 16, v19
	v_and_b32_e32 v19, 0xffff0000, v19
	s_waitcnt vmcnt(12)
	v_lshlrev_b32_e32 v44, 16, v20
	v_and_b32_e32 v45, 0xffff0000, v20
	v_lshlrev_b32_e32 v20, 16, v21
	v_and_b32_e32 v21, 0xffff0000, v21
	s_waitcnt vmcnt(11)
	v_lshlrev_b32_e32 v46, 16, v22
	v_and_b32_e32 v47, 0xffff0000, v22
	v_lshlrev_b32_e32 v22, 16, v23
	v_and_b32_e32 v23, 0xffff0000, v23
	s_waitcnt vmcnt(10)
	v_lshlrev_b32_e32 v48, 16, v24
	v_and_b32_e32 v49, 0xffff0000, v24
	v_lshlrev_b32_e32 v24, 16, v25
	v_and_b32_e32 v25, 0xffff0000, v25
	v_pk_add_f32 v[18:19], v[18:19], v[20:21]
	v_pk_add_f32 v[20:21], v[42:43], v[44:45]
	v_pk_add_f32 v[22:23], v[22:23], v[24:25]
	v_pk_add_f32 v[24:25], v[46:47], v[48:49]
	s_waitcnt vmcnt(9)
	v_lshlrev_b32_e32 v50, 16, v26
	v_and_b32_e32 v51, 0xffff0000, v26
	v_lshlrev_b32_e32 v26, 16, v27
	v_and_b32_e32 v27, 0xffff0000, v27
	s_waitcnt vmcnt(8)
	v_lshlrev_b32_e32 v52, 16, v28
	v_and_b32_e32 v53, 0xffff0000, v28
	v_lshlrev_b32_e32 v28, 16, v29
	v_and_b32_e32 v29, 0xffff0000, v29
	s_waitcnt vmcnt(7)
	v_lshlrev_b32_e32 v54, 16, v30
	v_and_b32_e32 v55, 0xffff0000, v30
	v_lshlrev_b32_e32 v30, 16, v31
	v_and_b32_e32 v31, 0xffff0000, v31
	s_waitcnt vmcnt(6)
	v_lshlrev_b32_e32 v56, 16, v32
	v_and_b32_e32 v57, 0xffff0000, v32
	v_lshlrev_b32_e32 v32, 16, v33
	v_and_b32_e32 v33, 0xffff0000, v33
	v_mov_b32_e32 v42, v20
	v_mov_b32_e32 v43, v24
	v_mov_b32_e32 v44, v21
	v_mov_b32_e32 v45, v25
	v_pk_add_f32 v[26:27], v[26:27], v[28:29]
	v_pk_add_f32 v[28:29], v[50:51], v[52:53]
	v_pk_add_f32 v[30:31], v[30:31], v[32:33]
	v_pk_add_f32 v[32:33], v[54:55], v[56:57]
	v_mov_b32_e32 v46, v18
	v_mov_b32_e32 v47, v22
	v_pk_add_f32 v[42:43], v[42:43], v[44:45]
	v_mov_b32_e32 v48, v19
	v_mov_b32_e32 v49, v23
	v_mov_b32_e32 v50, v28
	v_mov_b32_e32 v51, v32
	v_mov_b32_e32 v52, v29
	v_mov_b32_e32 v53, v33
	v_pk_add_f32 v[42:43], v[46:47], v[42:43]
	v_mov_b32_e32 v54, v26
	v_mov_b32_e32 v55, v30
	v_pk_add_f32 v[44:45], v[50:51], v[52:53]
	v_pk_add_f32 v[42:43], v[48:49], v[42:43]
	v_mov_b32_e32 v56, v27
	v_mov_b32_e32 v57, v31
	v_pk_add_f32 v[44:45], v[54:55], v[44:45]
	v_add_f32_e32 v42, 0, v42
	v_pk_add_f32 v[44:45], v[56:57], v[44:45]
	v_add_f32_e32 v42, v42, v43
	v_add_f32_e32 v42, v42, v44
	v_add_f32_e32 v42, v42, v45
	ds_bpermute_b32 v43, v147, v42
	s_waitcnt vmcnt(4)
	v_add_f32_e32 v58, v58, v59
	s_waitcnt vmcnt(3)
	v_lshlrev_b32_e32 v60, 16, v34
	v_and_b32_e32 v61, 0xffff0000, v34
	v_lshlrev_b32_e32 v34, 16, v35
	s_waitcnt lgkmcnt(0)
	v_add_f32_e32 v42, v42, v43
	ds_bpermute_b32 v43, v148, v42
	v_and_b32_e32 v35, 0xffff0000, v35
	s_waitcnt vmcnt(2)
	v_lshlrev_b32_e32 v62, 16, v36
	v_and_b32_e32 v63, 0xffff0000, v36
	v_lshlrev_b32_e32 v36, 16, v37
	s_waitcnt lgkmcnt(0)
	v_add_f32_e32 v42, v42, v43
	v_fmamk_f32 v21, v42, 0xbc800000, v21
	v_fmamk_f32 v25, v42, 0xbc800000, v25
	v_fmac_f32_e32 v20, 0xbc800000, v42
	v_fmac_f32_e32 v24, 0xbc800000, v42
	v_fmamk_f32 v29, v42, 0xbc800000, v29
	v_fmamk_f32 v33, v42, 0xbc800000, v33
	v_mov_b32_e32 v44, v21
	v_mov_b32_e32 v45, v25
	v_fmamk_f32 v19, v42, 0xbc800000, v19
	v_fmac_f32_e32 v18, 0xbc800000, v42
	v_fmamk_f32 v23, v42, 0xbc800000, v23
	v_fmac_f32_e32 v22, 0xbc800000, v42
	v_fmamk_f32 v27, v42, 0xbc800000, v27
	v_fmac_f32_e32 v26, 0xbc800000, v42
	v_fmac_f32_e32 v28, 0xbc800000, v42
	v_fmamk_f32 v31, v42, 0xbc800000, v31
	v_fmac_f32_e32 v30, 0xbc800000, v42
	v_fmac_f32_e32 v32, 0xbc800000, v42
	v_mov_b32_e32 v42, v20
	v_mov_b32_e32 v43, v24
	v_mov_b32_e32 v52, v33
	v_mov_b32_e32 v53, v29
	v_pk_mul_f32 v[44:45], v[44:45], v[44:45]
	v_mov_b32_e32 v46, v18
	v_mov_b32_e32 v47, v22
	v_mov_b32_e32 v50, v32
	v_mov_b32_e32 v51, v28
	v_pk_mul_f32 v[52:53], v[52:53], v[52:53]
	v_pk_fma_f32 v[42:43], v[42:43], v[42:43], v[44:45]
	v_mov_b32_e32 v48, v19
	v_mov_b32_e32 v49, v23
	v_mov_b32_e32 v54, v30
	v_mov_b32_e32 v55, v26
	v_pk_fma_f32 v[44:45], v[50:51], v[50:51], v[52:53]
	v_pk_fma_f32 v[42:43], v[46:47], v[46:47], v[42:43]
	v_mov_b32_e32 v56, v31
	v_mov_b32_e32 v57, v27
	v_pk_fma_f32 v[44:45], v[54:55], v[54:55], v[44:45]
	v_pk_fma_f32 v[42:43], v[48:49], v[48:49], v[42:43]
	v_pk_fma_f32 v[44:45], v[56:57], v[56:57], v[44:45]
	v_add_f32_e32 v42, v42, v43
	v_add_f32_e32 v42, v45, v42
	v_add_f32_e32 v42, v44, v42
	ds_bpermute_b32 v43, v147, v42
	v_and_b32_e32 v37, 0xffff0000, v37
	s_waitcnt vmcnt(1)
	v_lshlrev_b32_e32 v64, 16, v38
	v_and_b32_e32 v65, 0xffff0000, v38
	v_lshlrev_b32_e32 v38, 16, v39
	s_waitcnt lgkmcnt(0)
	v_add_f32_e32 v42, v42, v43
	ds_bpermute_b32 v43, v148, v42
	v_and_b32_e32 v39, 0xffff0000, v39
	s_waitcnt vmcnt(0)
	v_lshlrev_b32_e32 v108, 16, v40
	v_and_b32_e32 v109, 0xffff0000, v40
	v_lshlrev_b32_e32 v40, 16, v41
	s_waitcnt lgkmcnt(0)
	v_add_f32_e32 v42, v42, v43
	v_fmamk_f32 v42, v42, 0x3c800000, v151
	v_mul_f32_e32 v43, 0x4b800000, v42
	v_cmp_gt_f32_e32 vcc, s21, v42
	v_and_b32_e32 v41, 0xffff0000, v41
	s_nop 0
	v_cndmask_b32_e32 v42, v42, v43, vcc
	v_rsq_f32_e32 v42, v42
	s_nop 0
	v_mul_f32_e32 v43, 0x45800000, v42
	v_cndmask_b32_e32 v42, v42, v43, vcc
	v_pk_mul_f32 v[20:21], v[20:21], v[42:43] op_sel_hi:[1,0]
	v_pk_mul_f32 v[18:19], v[18:19], v[42:43] op_sel_hi:[1,0]
	v_pk_mul_f32 v[24:25], v[24:25], v[42:43] op_sel_hi:[1,0]
	v_pk_mul_f32 v[22:23], v[22:23], v[42:43] op_sel_hi:[1,0]
	v_pk_mul_f32 v[28:29], v[28:29], v[42:43] op_sel_hi:[1,0]
	v_pk_mul_f32 v[26:27], v[26:27], v[42:43] op_sel_hi:[1,0]
	v_pk_mul_f32 v[32:33], v[32:33], v[42:43] op_sel_hi:[1,0]
	v_pk_mul_f32 v[30:31], v[30:31], v[42:43] op_sel_hi:[1,0]
	v_pk_fma_f32 v[18:19], v[76:77], v[18:19], v[92:93]
	v_pk_fma_f32 v[20:21], v[74:75], v[20:21], v[90:91]
	v_pk_fma_f32 v[22:23], v[68:69], v[22:23], v[84:85]
	v_pk_fma_f32 v[24:25], v[66:67], v[24:25], v[82:83]
	v_pk_fma_f32 v[26:27], v[80:81], v[26:27], v[96:97]
	v_pk_fma_f32 v[28:29], v[78:79], v[28:29], v[94:95]
	v_pk_fma_f32 v[30:31], v[72:73], v[30:31], v[88:89]
	v_pk_fma_f32 v[32:33], v[70:71], v[32:33], v[86:87]
	v_pk_fma_f32 v[20:21], v[58:59], v[60:61], v[20:21] op_sel_hi:[0,1,1]
	v_pk_fma_f32 v[18:19], v[58:59], v[34:35], v[18:19] op_sel_hi:[0,1,1]
	v_pk_fma_f32 v[24:25], v[58:59], v[62:63], v[24:25] op_sel_hi:[0,1,1]
	v_pk_fma_f32 v[22:23], v[58:59], v[36:37], v[22:23] op_sel_hi:[0,1,1]
	v_pk_fma_f32 v[28:29], v[58:59], v[64:65], v[28:29] op_sel_hi:[0,1,1]
	v_pk_fma_f32 v[26:27], v[58:59], v[38:39], v[26:27] op_sel_hi:[0,1,1]
	v_pk_fma_f32 v[32:33], v[58:59], v[108:109], v[32:33] op_sel_hi:[0,1,1]
	v_pk_fma_f32 v[30:31], v[58:59], v[40:41], v[30:31] op_sel_hi:[0,1,1]
	v_pk_mul_f32 v[16:17], v[16:17], v[18:19]
	v_pk_mul_f32 v[14:15], v[14:15], v[20:21]
	v_pk_mul_f32 v[12:13], v[12:13], v[22:23]
	v_pk_mul_f32 v[10:11], v[10:11], v[24:25]
	v_pk_mul_f32 v[8:9], v[8:9], v[26:27]
	v_pk_mul_f32 v[6:7], v[6:7], v[28:29]
	v_pk_mul_f32 v[4:5], v[4:5], v[30:31]
	v_pk_mul_f32 v[2:3], v[2:3], v[32:33]
	v_cvt_pk_bf16_f32 v14, v14, v15
	v_cvt_pk_bf16_f32 v15, v16, v17
	v_cvt_pk_bf16_f32 v10, v10, v11
	v_cvt_pk_bf16_f32 v11, v12, v13
	v_cvt_pk_bf16_f32 v6, v6, v7
	v_cvt_pk_bf16_f32 v7, v8, v9
	v_cvt_pk_bf16_f32 v2, v2, v3
	v_cvt_pk_bf16_f32 v3, v4, v5
	global_store_dwordx2 v[106:107], v[14:15], off
	global_store_dwordx2 v[106:107], v[10:11], off offset:32
	global_store_dwordx2 v[106:107], v[6:7], off offset:64
	global_store_dwordx2 v[106:107], v[2:3], off offset:96
	s_cbranch_scc1 .LBB0_623
	s_setprio 0
